# GEMM K loops: in each load segment the LDS-DMA loads (and their address/m0 arithmetic) are issued before the ds_reads instead of after them
# speedup vs baseline: 1.0017x; 1.0017x over previous
; #define PG8_STAGE(bufoff, gbase, voff) do { _Pragma("unroll") for (int _i = 0; _i < 2; ++_i) \
;         __builtin_amdgcn_global_load_lds((const unsigned*)((const char*)(gbase) + (voff)[_i]), (PG8_LAS unsigned*)(lds + (bufoff) + ldsw + _i * 8192), 16, 0, 0); } while (0)
; #define PG8_LDA(dst, b, h) do { _Pragma("unroll") for (int m = 0; m < 4; ++m) _Pragma("unroll") for (int k = 0; k < 2; ++k) dst[m][k] = *(const PG8_LAS bf16x8*)(lds + PG8_SA(b, h) + aoff + m * 2048 + k * 1024); } while (0)
; #define PG8_LDB(dst, b, h) do { _Pragma("unroll") for (int n = 0; n < 2; ++n) _Pragma("unroll") for (int k = 0; k < 2; ++k) dst[n][k] = *(const PG8_LAS bf16x8*)(lds + PG8_SB(b, h) + boff + n * 2048 + k * 1024); } while (0)
; #define PG8_MMA(ai, bj, At, Bt) do { __builtin_amdgcn_s_setprio(1); _Pragma("unroll") for (int m = 0; m < 4; ++m) _Pragma("unroll") for (int n = 0; n < 2; ++n) _Pragma("unroll") for (int k = 0; k < 2; ++k) \
;         acc[ai][bj][m][n] = __builtin_amdgcn_mfma_f32_16x16x32_bf16(Bt[n][k], At[m][k], acc[ai][bj][m][n], 0, 0, 0); __builtin_amdgcn_s_setprio(0); } while (0)
; #define PG8_WAIT_V(n) asm volatile("s_waitcnt vmcnt(" #n ")" ::: "memory")
; #define PG8_WAIT_L(n) asm volatile("s_waitcnt lgkmcnt(" #n ")" ::: "memory")
; #define PG8_BAR __builtin_amdgcn_s_barrier()
; #define PG8_SCHED __builtin_amdgcn_sched_barrier(0)
; template <class Epi, class Sched, bool ALIGN_EPI = false, bool SP2 = false>
; __device__ __forceinline__ void gemm_phase(PG8_LAS unsigned char* lds, const Gemm g, const Sched& S, const Epi& E) {
;     ...
;             PG8_LDB(B0, 0, 0); PG8_LDB(B1, 0, 1); PG8_SCHED; PG8_LDA(At, 0, 0); PG8_STAGE(PG8_SA(1, 1), a1 + hstep, voffA);
;             PG8_WAIT_V(8); PG8_WAIT_L(0); PG8_BAR; PG8_MMA(0, 0, At, B0); PG8_MMA(0, 1, At, B1); PG8_BAR; PG8_SCHED;
;             PG8_LDA(At, 0, 1); PG8_STAGE(PG8_SB(0, 0), b2, voffB); PG8_STAGE(PG8_SB(0, 1), b2 + hstep, voffB); PG8_STAGE(PG8_SA(0, 0), a2, voffA);
;             PG8_WAIT_V(8); PG8_WAIT_L(0); PG8_BAR; PG8_MMA(1, 0, At, B0); PG8_MMA(1, 1, At, B1); PG8_BAR; PG8_SCHED;
.LBB0_427:
	s_add_u32 s28, s8, 0xfffc0080
	s_addc_u32 s29, s9, -1
	s_cmp_eq_u32 s39, 12
	s_cselect_b32 s37, s5, s29
	s_cselect_b32 s36, s7, s28
	s_cselect_b32 s29, s12, s38
	s_cselect_b32 s28, s21, s23
	v_lshl_add_u64 v[160:161], s[8:9], 0, v[140:141]
	s_add_i32 m0, s63, 0xc000
	ds_read_b128 v[152:155], v162
	global_load_lds_dwordx4 v[160:161], off
	v_lshl_add_u64 v[160:161], s[8:9], 0, v[142:143]
	s_add_i32 m0, s63, 0xe000
	ds_read_b128 v[156:159], v162 offset:1024
	global_load_lds_dwordx4 v[160:161], off
	ds_read_b128 v[166:169], v162 offset:2048
	ds_read_b128 v[170:173], v162 offset:3072
	ds_read_b128 v[174:177], v163
	ds_read_b128 v[178:181], v163 offset:1024
	ds_read_b128 v[182:185], v163 offset:2048
	ds_read_b128 v[186:189], v163 offset:3072
	ds_read_b128 v[190:193], v164
	ds_read_b128 v[194:197], v164 offset:1024
	ds_read_b128 v[198:201], v164 offset:2048
	ds_read_b128 v[202:205], v164 offset:3072
	ds_read_b128 v[206:209], v164 offset:4096
	ds_read_b128 v[210:213], v164 offset:5120
	ds_read_b128 v[214:217], v164 offset:6144
	ds_read_b128 v[218:221], v164 offset:7168
	s_waitcnt vmcnt(8)
	s_waitcnt lgkmcnt(0)
	s_barrier
	s_setprio 1
	s_waitcnt lgkmcnt(0)
	v_mfma_f32_16x16x32_bf16 v[124:127], v[152:155], v[190:193], v[124:127]
	v_mfma_f32_16x16x32_bf16 v[120:123], v[166:169], v[190:193], v[120:123]
	v_mfma_f32_16x16x32_bf16 v[108:111], v[152:155], v[198:201], v[108:111]
	v_mfma_f32_16x16x32_bf16 v[104:107], v[166:169], v[198:201], v[104:107]
	v_mfma_f32_16x16x32_bf16 v[92:95], v[152:155], v[206:209], v[92:95]
	v_mfma_f32_16x16x32_bf16 v[88:91], v[166:169], v[206:209], v[88:91]
	v_mfma_f32_16x16x32_bf16 v[76:79], v[152:155], v[214:217], v[76:79]
	v_mfma_f32_16x16x32_bf16 v[72:75], v[166:169], v[214:217], v[72:75]
	v_mfma_f32_16x16x32_bf16 v[124:127], v[156:159], v[194:197], v[124:127]
	v_mfma_f32_16x16x32_bf16 v[120:123], v[170:173], v[194:197], v[120:123]
	v_mfma_f32_16x16x32_bf16 v[108:111], v[156:159], v[202:205], v[108:111]
	v_mfma_f32_16x16x32_bf16 v[104:107], v[170:173], v[202:205], v[104:107]
	v_mfma_f32_16x16x32_bf16 v[92:95], v[156:159], v[210:213], v[92:95]
	v_mfma_f32_16x16x32_bf16 v[88:91], v[170:173], v[210:213], v[88:91]
	v_mfma_f32_16x16x32_bf16 v[76:79], v[156:159], v[218:221], v[76:79]
	v_mfma_f32_16x16x32_bf16 v[72:75], v[170:173], v[218:221], v[72:75]
	s_setprio 0
	s_setprio 1
	v_mfma_f32_16x16x32_bf16 v[116:119], v[174:177], v[190:193], v[116:119]
	v_mfma_f32_16x16x32_bf16 v[112:115], v[182:185], v[190:193], v[112:115]
	v_mfma_f32_16x16x32_bf16 v[100:103], v[174:177], v[198:201], v[100:103]
	v_mfma_f32_16x16x32_bf16 v[96:99], v[182:185], v[198:201], v[96:99]
	v_mfma_f32_16x16x32_bf16 v[84:87], v[174:177], v[206:209], v[84:87]
	v_mfma_f32_16x16x32_bf16 v[80:83], v[182:185], v[206:209], v[80:83]
	v_mfma_f32_16x16x32_bf16 v[68:71], v[174:177], v[214:217], v[68:71]
	v_mfma_f32_16x16x32_bf16 v[64:67], v[182:185], v[214:217], v[64:67]
	v_mfma_f32_16x16x32_bf16 v[116:119], v[178:181], v[194:197], v[116:119]
	v_mfma_f32_16x16x32_bf16 v[112:115], v[186:189], v[194:197], v[112:115]
	v_mfma_f32_16x16x32_bf16 v[100:103], v[178:181], v[202:205], v[100:103]
	v_mfma_f32_16x16x32_bf16 v[96:99], v[186:189], v[202:205], v[96:99]
	v_mfma_f32_16x16x32_bf16 v[84:87], v[178:181], v[210:213], v[84:87]
	v_mfma_f32_16x16x32_bf16 v[80:83], v[186:189], v[210:213], v[80:83]
	v_mfma_f32_16x16x32_bf16 v[68:71], v[178:181], v[218:221], v[68:71]
	v_mfma_f32_16x16x32_bf16 v[64:67], v[186:189], v[218:221], v[64:67]
	s_setprio 0
	s_barrier
	s_add_i32 s42, s79, s62
	v_lshl_add_u64 v[160:161], s[28:29], 0, v[130:131]
	s_mov_b32 m0, s42
	v_lshl_add_u64 v[222:223], s[28:29], 0, v[134:135]
	global_load_lds_dwordx4 v[160:161], off
	s_add_i32 m0, s42, 0x2000
	s_add_u32 s42, s28, 0x40000
	s_addc_u32 s43, s29, 0
	s_add_i32 s44, s84, s62
	global_load_lds_dwordx4 v[222:223], off
	v_lshl_add_u64 v[224:225], s[42:43], 0, v[130:131]
	s_mov_b32 m0, s44
	v_lshl_add_u64 v[226:227], s[36:37], 0, v[132:133]
	global_load_lds_dwordx4 v[224:225], off
	v_lshl_add_u64 v[224:225], s[42:43], 0, v[134:135]
	s_add_i32 m0, s44, 0x2000
	ds_read_b128 v[190:193], v164 offset:16384
	global_load_lds_dwordx4 v[224:225], off
	v_lshl_add_u64 v[224:225], s[36:37], 0, v[128:129]
	s_mov_b32 m0, s63
	ds_read_b128 v[194:197], v164 offset:17408
	global_load_lds_dwordx4 v[224:225], off
	s_mov_b32 m0, s68
	ds_read_b128 v[198:201], v164 offset:18432
	global_load_lds_dwordx4 v[226:227], off
	ds_read_b128 v[202:205], v164 offset:19456
	ds_read_b128 v[206:209], v164 offset:20480
	ds_read_b128 v[210:213], v164 offset:21504
	ds_read_b128 v[214:217], v164 offset:22528
	ds_read_b128 v[218:221], v164 offset:23552
	s_waitcnt vmcnt(8)
	s_waitcnt lgkmcnt(0)
	s_barrier
; #define PG8_STAGE(bufoff, gbase, voff) do { _Pragma("unroll") for (int _i = 0; _i < 2; ++_i) \
;         __builtin_amdgcn_global_load_lds((const unsigned*)((const char*)(gbase) + (voff)[_i]), (PG8_LAS unsigned*)(lds + (bufoff) + ldsw + _i * 8192), 16, 0, 0); } while (0)
; #define PG8_LDA(dst, b, h) do { _Pragma("unroll") for (int m = 0; m < 4; ++m) _Pragma("unroll") for (int k = 0; k < 2; ++k) dst[m][k] = *(const PG8_LAS bf16x8*)(lds + PG8_SA(b, h) + aoff + m * 2048 + k * 1024); } while (0)
; #define PG8_LDB(dst, b, h) do { _Pragma("unroll") for (int n = 0; n < 2; ++n) _Pragma("unroll") for (int k = 0; k < 2; ++k) dst[n][k] = *(const PG8_LAS bf16x8*)(lds + PG8_SB(b, h) + boff + n * 2048 + k * 1024); } while (0)
; #define PG8_MMA(ai, bj, At, Bt) do { __builtin_amdgcn_s_setprio(1); _Pragma("unroll") for (int m = 0; m < 4; ++m) _Pragma("unroll") for (int n = 0; n < 2; ++n) _Pragma("unroll") for (int k = 0; k < 2; ++k) \
;         acc[ai][bj][m][n] = __builtin_amdgcn_mfma_f32_16x16x32_bf16(Bt[n][k], At[m][k], acc[ai][bj][m][n], 0, 0, 0); __builtin_amdgcn_s_setprio(0); } while (0)
; #define PG8_WAIT_V(n) asm volatile("s_waitcnt vmcnt(" #n ")" ::: "memory")
; #define PG8_WAIT_L(n) asm volatile("s_waitcnt lgkmcnt(" #n ")" ::: "memory")
; #define PG8_BAR __builtin_amdgcn_s_barrier()
; #define PG8_SCHED __builtin_amdgcn_sched_barrier(0)
; template <class Epi, class Sched, bool ALIGN_EPI = false, bool SP2 = false>
; __device__ __forceinline__ void gemm_phase(PG8_LAS unsigned char* lds, const Gemm g, const Sched& S, const Epi& E) {
;     ...
;             PG8_WAIT_V(8); PG8_WAIT_L(0); PG8_BAR; PG8_MMA(1, 0, At, B0); PG8_MMA(1, 1, At, B1); PG8_BAR; PG8_SCHED;
;             PG8_LDB(B0, 1, 0); PG8_LDB(B1, 1, 1); PG8_SCHED; PG8_LDA(At, 1, 0); PG8_STAGE(PG8_SA(0, 1), a2 + hstep, voffA);
;             PG8_WAIT_V(8); PG8_WAIT_L(0); PG8_BAR; PG8_MMA(0, 0, At, B0); PG8_MMA(0, 1, At, B1); PG8_BAR; PG8_SCHED;
	s_setprio 1
	s_waitcnt lgkmcnt(0)
	v_mfma_f32_16x16x32_bf16 v[60:63], v[152:155], v[190:193], v[60:63]
	v_mfma_f32_16x16x32_bf16 v[56:59], v[166:169], v[190:193], v[56:59]
	v_mfma_f32_16x16x32_bf16 v[44:47], v[152:155], v[198:201], v[44:47]
	v_mfma_f32_16x16x32_bf16 v[40:43], v[166:169], v[198:201], v[40:43]
	v_mfma_f32_16x16x32_bf16 v[28:31], v[152:155], v[206:209], v[28:31]
	v_mfma_f32_16x16x32_bf16 v[24:27], v[166:169], v[206:209], v[24:27]
	v_mfma_f32_16x16x32_bf16 v[12:15], v[152:155], v[214:217], v[12:15]
	v_mfma_f32_16x16x32_bf16 v[8:11], v[166:169], v[214:217], v[8:11]
	v_mfma_f32_16x16x32_bf16 v[60:63], v[156:159], v[194:197], v[60:63]
	v_mfma_f32_16x16x32_bf16 v[56:59], v[170:173], v[194:197], v[56:59]
	v_mfma_f32_16x16x32_bf16 v[44:47], v[156:159], v[202:205], v[44:47]
	v_mfma_f32_16x16x32_bf16 v[40:43], v[170:173], v[202:205], v[40:43]
	v_mfma_f32_16x16x32_bf16 v[28:31], v[156:159], v[210:213], v[28:31]
	v_mfma_f32_16x16x32_bf16 v[24:27], v[170:173], v[210:213], v[24:27]
	v_mfma_f32_16x16x32_bf16 v[12:15], v[156:159], v[218:221], v[12:15]
	v_mfma_f32_16x16x32_bf16 v[8:11], v[170:173], v[218:221], v[8:11]
	s_setprio 0
	s_setprio 1
	v_mfma_f32_16x16x32_bf16 v[52:55], v[174:177], v[190:193], v[52:55]
	v_mfma_f32_16x16x32_bf16 v[48:51], v[182:185], v[190:193], v[48:51]
	v_mfma_f32_16x16x32_bf16 v[36:39], v[174:177], v[198:201], v[36:39]
	v_mfma_f32_16x16x32_bf16 v[32:35], v[182:185], v[198:201], v[32:35]
	v_mfma_f32_16x16x32_bf16 v[20:23], v[174:177], v[206:209], v[20:23]
	v_mfma_f32_16x16x32_bf16 v[16:19], v[182:185], v[206:209], v[16:19]
	v_mfma_f32_16x16x32_bf16 v[4:7], v[174:177], v[214:217], v[4:7]
	v_mfma_f32_16x16x32_bf16 v[0:3], v[182:185], v[214:217], v[0:3]
	v_mfma_f32_16x16x32_bf16 v[52:55], v[178:181], v[194:197], v[52:55]
	v_mfma_f32_16x16x32_bf16 v[48:51], v[186:189], v[194:197], v[48:51]
	v_mfma_f32_16x16x32_bf16 v[36:39], v[178:181], v[202:205], v[36:39]
	v_mfma_f32_16x16x32_bf16 v[32:35], v[186:189], v[202:205], v[32:35]
	v_mfma_f32_16x16x32_bf16 v[20:23], v[178:181], v[210:213], v[20:23]
	v_mfma_f32_16x16x32_bf16 v[16:19], v[186:189], v[210:213], v[16:19]
	v_mfma_f32_16x16x32_bf16 v[4:7], v[178:181], v[218:221], v[4:7]
	v_mfma_f32_16x16x32_bf16 v[0:3], v[186:189], v[218:221], v[0:3]
	s_setprio 0
	s_barrier
	s_add_i32 s42, 0, 0x18000
	s_add_i32 s43, 0, 0x1c000
	s_add_u32 s36, s36, 0x40000
	s_addc_u32 s37, s37, 0
	s_mov_b32 m0, s50
	v_lshl_add_u64 v[228:229], s[36:37], 0, v[128:129]
	global_load_lds_dwordx4 v[228:229], off
	v_lshl_add_u64 v[228:229], s[36:37], 0, v[132:133]
	s_mov_b32 m0, s51
	v_add_u32_e32 v136, s42, v149
	global_load_lds_dwordx4 v[228:229], off
	ds_read_b128 v[152:155], v136
	ds_read_b128 v[156:159], v136 offset:1024
	ds_read_b128 v[166:169], v136 offset:2048
	ds_read_b128 v[170:173], v136 offset:3072
	v_add_u32_e32 v136, s43, v149
	ds_read_b128 v[174:177], v136
	ds_read_b128 v[178:181], v136 offset:1024
	ds_read_b128 v[182:185], v136 offset:2048
	ds_read_b128 v[186:189], v136 offset:3072
	ds_read_b128 v[190:193], v164 offset:32768
	ds_read_b128 v[194:197], v164 offset:33792
	ds_read_b128 v[198:201], v164 offset:34816
	ds_read_b128 v[202:205], v164 offset:35840
	ds_read_b128 v[206:209], v164 offset:36864
	ds_read_b128 v[210:213], v164 offset:37888
	ds_read_b128 v[214:217], v164 offset:38912
	ds_read_b128 v[218:221], v164 offset:39936
	s_waitcnt vmcnt(8)
	s_waitcnt lgkmcnt(0)
	s_barrier
	s_setprio 1
	s_waitcnt lgkmcnt(0)
	v_mfma_f32_16x16x32_bf16 v[124:127], v[152:155], v[190:193], v[124:127]
	v_mfma_f32_16x16x32_bf16 v[120:123], v[166:169], v[190:193], v[120:123]
	v_mfma_f32_16x16x32_bf16 v[108:111], v[152:155], v[198:201], v[108:111]
	v_mfma_f32_16x16x32_bf16 v[104:107], v[166:169], v[198:201], v[104:107]
	v_mfma_f32_16x16x32_bf16 v[92:95], v[152:155], v[206:209], v[92:95]
	v_mfma_f32_16x16x32_bf16 v[88:91], v[166:169], v[206:209], v[88:91]
	v_mfma_f32_16x16x32_bf16 v[76:79], v[152:155], v[214:217], v[76:79]
	v_mfma_f32_16x16x32_bf16 v[72:75], v[166:169], v[214:217], v[72:75]
	v_mfma_f32_16x16x32_bf16 v[124:127], v[156:159], v[194:197], v[124:127]
	v_mfma_f32_16x16x32_bf16 v[120:123], v[170:173], v[194:197], v[120:123]
	v_mfma_f32_16x16x32_bf16 v[108:111], v[156:159], v[202:205], v[108:111]
	v_mfma_f32_16x16x32_bf16 v[104:107], v[170:173], v[202:205], v[104:107]
	v_mfma_f32_16x16x32_bf16 v[92:95], v[156:159], v[210:213], v[92:95]
	v_mfma_f32_16x16x32_bf16 v[88:91], v[170:173], v[210:213], v[88:91]
	v_mfma_f32_16x16x32_bf16 v[76:79], v[156:159], v[218:221], v[76:79]
	v_mfma_f32_16x16x32_bf16 v[72:75], v[170:173], v[218:221], v[72:75]
	s_setprio 0
	s_setprio 1
	v_mfma_f32_16x16x32_bf16 v[116:119], v[174:177], v[190:193], v[116:119]
	v_mfma_f32_16x16x32_bf16 v[112:115], v[182:185], v[190:193], v[112:115]
	v_mfma_f32_16x16x32_bf16 v[100:103], v[174:177], v[198:201], v[100:103]
	v_mfma_f32_16x16x32_bf16 v[96:99], v[182:185], v[198:201], v[96:99]
	v_mfma_f32_16x16x32_bf16 v[84:87], v[174:177], v[206:209], v[84:87]
	v_mfma_f32_16x16x32_bf16 v[80:83], v[182:185], v[206:209], v[80:83]
	v_mfma_f32_16x16x32_bf16 v[68:71], v[174:177], v[214:217], v[68:71]
	v_mfma_f32_16x16x32_bf16 v[64:67], v[182:185], v[214:217], v[64:67]
	v_mfma_f32_16x16x32_bf16 v[116:119], v[178:181], v[194:197], v[116:119]
	v_mfma_f32_16x16x32_bf16 v[112:115], v[186:189], v[194:197], v[112:115]
	v_mfma_f32_16x16x32_bf16 v[100:103], v[178:181], v[202:205], v[100:103]
	v_mfma_f32_16x16x32_bf16 v[96:99], v[186:189], v[202:205], v[96:99]
	v_mfma_f32_16x16x32_bf16 v[84:87], v[178:181], v[210:213], v[84:87]
	v_mfma_f32_16x16x32_bf16 v[80:83], v[186:189], v[210:213], v[80:83]
	v_mfma_f32_16x16x32_bf16 v[68:71], v[178:181], v[218:221], v[68:71]
	v_mfma_f32_16x16x32_bf16 v[64:67], v[186:189], v[218:221], v[64:67]
	s_setprio 0
	s_barrier
; #define PG8_STAGE(bufoff, gbase, voff) do { _Pragma("unroll") for (int _i = 0; _i < 2; ++_i) \
;         __builtin_amdgcn_global_load_lds((const unsigned*)((const char*)(gbase) + (voff)[_i]), (PG8_LAS unsigned*)(lds + (bufoff) + ldsw + _i * 8192), 16, 0, 0); } while (0)
; #define PG8_LDA(dst, b, h) do { _Pragma("unroll") for (int m = 0; m < 4; ++m) _Pragma("unroll") for (int k = 0; k < 2; ++k) dst[m][k] = *(const PG8_LAS bf16x8*)(lds + PG8_SA(b, h) + aoff + m * 2048 + k * 1024); } while (0)
; #define PG8_MMA(ai, bj, At, Bt) do { __builtin_amdgcn_s_setprio(1); _Pragma("unroll") for (int m = 0; m < 4; ++m) _Pragma("unroll") for (int n = 0; n < 2; ++n) _Pragma("unroll") for (int k = 0; k < 2; ++k) \
;         acc[ai][bj][m][n] = __builtin_amdgcn_mfma_f32_16x16x32_bf16(Bt[n][k], At[m][k], acc[ai][bj][m][n], 0, 0, 0); __builtin_amdgcn_s_setprio(0); } while (0)
; #define PG8_WAIT_V(n) asm volatile("s_waitcnt vmcnt(" #n ")" ::: "memory")
; #define PG8_WAIT_L(n) asm volatile("s_waitcnt lgkmcnt(" #n ")" ::: "memory")
; #define PG8_BAR __builtin_amdgcn_s_barrier()
; #define PG8_SCHED __builtin_amdgcn_sched_barrier(0)
; template <class Epi, class Sched, bool ALIGN_EPI = false, bool SP2 = false>
; __device__ __forceinline__ void gemm_phase(PG8_LAS unsigned char* lds, const Gemm g, const Sched& S, const Epi& E) {
;     ...
;             PG8_WAIT_V(8); PG8_WAIT_L(0); PG8_BAR; PG8_MMA(0, 0, At, B0); PG8_MMA(0, 1, At, B1); PG8_BAR; PG8_SCHED;
;             PG8_LDA(At, 1, 1); PG8_STAGE(PG8_SB(1, 0), b3, voffB); PG8_STAGE(PG8_SB(1, 1), b3 + hstep, voffB); PG8_STAGE(PG8_SA(1, 0), a3, voffA);
;             PG8_WAIT_V(8); PG8_WAIT_L(0); PG8_BAR; PG8_MMA(1, 0, At, B0); PG8_MMA(1, 1, At, B1); PG8_BAR; PG8_SCHED;
	s_add_i32 s36, s42, s62
	v_lshl_add_u64 v[160:161], v[160:161], 0, s[16:17]
	s_mov_b32 m0, s36
	ds_read_b128 v[190:193], v164 offset:49152
	global_load_lds_dwordx4 v[160:161], off
	s_add_i32 m0, s36, 0x2000
	s_add_u32 s28, s28, 0x40080
	v_lshl_add_u64 v[160:161], v[222:223], 0, s[16:17]
	s_addc_u32 s29, s29, 0
	s_add_i32 s36, s43, s62
	global_load_lds_dwordx4 v[160:161], off
	v_lshl_add_u64 v[160:161], s[28:29], 0, v[130:131]
	s_mov_b32 m0, s36
	ds_read_b128 v[194:197], v164 offset:50176
	global_load_lds_dwordx4 v[160:161], off
	v_lshl_add_u64 v[160:161], s[28:29], 0, v[134:135]
	s_add_i32 m0, s36, 0x2000
	ds_read_b128 v[198:201], v164 offset:51200
	global_load_lds_dwordx4 v[160:161], off
	v_lshl_add_u64 v[160:161], v[224:225], 0, s[16:17]
	s_mov_b32 m0, s69
	ds_read_b128 v[202:205], v164 offset:52224
	global_load_lds_dwordx4 v[160:161], off
	v_lshl_add_u64 v[160:161], v[226:227], 0, s[16:17]
	s_mov_b32 m0, s70
	ds_read_b128 v[206:209], v164 offset:53248
	global_load_lds_dwordx4 v[160:161], off
	ds_read_b128 v[210:213], v164 offset:54272
	ds_read_b128 v[214:217], v164 offset:55296
	ds_read_b128 v[218:221], v164 offset:56320
	s_waitcnt vmcnt(8)
	s_waitcnt lgkmcnt(0)
	s_barrier
	s_setprio 1
	s_waitcnt lgkmcnt(0)
	v_mfma_f32_16x16x32_bf16 v[60:63], v[152:155], v[190:193], v[60:63]
	v_mfma_f32_16x16x32_bf16 v[56:59], v[166:169], v[190:193], v[56:59]
	v_mfma_f32_16x16x32_bf16 v[44:47], v[152:155], v[198:201], v[44:47]
	v_mfma_f32_16x16x32_bf16 v[40:43], v[166:169], v[198:201], v[40:43]
	v_mfma_f32_16x16x32_bf16 v[28:31], v[152:155], v[206:209], v[28:31]
	v_mfma_f32_16x16x32_bf16 v[24:27], v[166:169], v[206:209], v[24:27]
	v_mfma_f32_16x16x32_bf16 v[12:15], v[152:155], v[214:217], v[12:15]
	v_mfma_f32_16x16x32_bf16 v[8:11], v[166:169], v[214:217], v[8:11]
	v_mfma_f32_16x16x32_bf16 v[60:63], v[156:159], v[194:197], v[60:63]
	v_mfma_f32_16x16x32_bf16 v[56:59], v[170:173], v[194:197], v[56:59]
	v_mfma_f32_16x16x32_bf16 v[44:47], v[156:159], v[202:205], v[44:47]
	v_mfma_f32_16x16x32_bf16 v[40:43], v[170:173], v[202:205], v[40:43]
	v_mfma_f32_16x16x32_bf16 v[28:31], v[156:159], v[210:213], v[28:31]
	v_mfma_f32_16x16x32_bf16 v[24:27], v[170:173], v[210:213], v[24:27]
	v_mfma_f32_16x16x32_bf16 v[12:15], v[156:159], v[218:221], v[12:15]
	v_mfma_f32_16x16x32_bf16 v[8:11], v[170:173], v[218:221], v[8:11]
	s_setprio 0
	s_setprio 1
	v_mfma_f32_16x16x32_bf16 v[52:55], v[174:177], v[190:193], v[52:55]
	v_mfma_f32_16x16x32_bf16 v[48:51], v[182:185], v[190:193], v[48:51]
	v_mfma_f32_16x16x32_bf16 v[36:39], v[174:177], v[198:201], v[36:39]
	v_mfma_f32_16x16x32_bf16 v[32:35], v[182:185], v[198:201], v[32:35]
	v_mfma_f32_16x16x32_bf16 v[20:23], v[174:177], v[206:209], v[20:23]
	v_mfma_f32_16x16x32_bf16 v[16:19], v[182:185], v[206:209], v[16:19]
	v_mfma_f32_16x16x32_bf16 v[4:7], v[174:177], v[214:217], v[4:7]
	v_mfma_f32_16x16x32_bf16 v[0:3], v[182:185], v[214:217], v[0:3]
	v_mfma_f32_16x16x32_bf16 v[52:55], v[178:181], v[194:197], v[52:55]
	v_mfma_f32_16x16x32_bf16 v[48:51], v[186:189], v[194:197], v[48:51]
	v_mfma_f32_16x16x32_bf16 v[36:39], v[178:181], v[202:205], v[36:39]
	v_mfma_f32_16x16x32_bf16 v[32:35], v[186:189], v[202:205], v[32:35]
	v_mfma_f32_16x16x32_bf16 v[20:23], v[178:181], v[210:213], v[20:23]
	v_mfma_f32_16x16x32_bf16 v[16:19], v[186:189], v[210:213], v[16:19]
	v_mfma_f32_16x16x32_bf16 v[4:7], v[178:181], v[218:221], v[4:7]
	v_mfma_f32_16x16x32_bf16 v[0:3], v[186:189], v[218:221], v[0:3]
	s_setprio 0
	s_barrier
	s_add_i32 s39, s39, 2
	s_add_u32 s8, s8, 0x100
	s_addc_u32 s9, s9, 0
	s_add_u32 s23, s23, 0x100
	s_addc_u32 s38, s38, 0
	s_cmp_gt_u32 s39, 13
	s_cbranch_scc0 .LBB0_427
	s_nop 0
	s_nop 0
	s_nop 0
	s_nop 0
	s_nop 0
	s_nop 0
	s_nop 0
	s_nop 0
	s_nop 0
	s_and_b64 vcc, exec, s[18:19]
	s_cbranch_vccz .LBB0_430
	s_barrier

; #define PG8_STAGE(bufoff, gbase, voff) do { _Pragma("unroll") for (int _i = 0; _i < 2; ++_i) \
;         __builtin_amdgcn_global_load_lds((const unsigned*)((const char*)(gbase) + (voff)[_i]), (PG8_LAS unsigned*)(lds + (bufoff) + ldsw + _i * 8192), 16, 0, 0); } while (0)
; #define PG8_LDA(dst, b, h) do { _Pragma("unroll") for (int m = 0; m < 4; ++m) _Pragma("unroll") for (int k = 0; k < 2; ++k) dst[m][k] = *(const PG8_LAS bf16x8*)(lds + PG8_SA(b, h) + aoff + m * 2048 + k * 1024); } while (0)
; #define PG8_LDB(dst, b, h) do { _Pragma("unroll") for (int n = 0; n < 2; ++n) _Pragma("unroll") for (int k = 0; k < 2; ++k) dst[n][k] = *(const PG8_LAS bf16x8*)(lds + PG8_SB(b, h) + boff + n * 2048 + k * 1024); } while (0)
; #define PG8_MMA(ai, bj, At, Bt) do { __builtin_amdgcn_s_setprio(1); _Pragma("unroll") for (int m = 0; m < 4; ++m) _Pragma("unroll") for (int n = 0; n < 2; ++n) _Pragma("unroll") for (int k = 0; k < 2; ++k) \
;         acc[ai][bj][m][n] = __builtin_amdgcn_mfma_f32_16x16x32_bf16(Bt[n][k], At[m][k], acc[ai][bj][m][n], 0, 0, 0); __builtin_amdgcn_s_setprio(0); } while (0)
; #define PG8_WAIT_V(n) asm volatile("s_waitcnt vmcnt(" #n ")" ::: "memory")
; #define PG8_WAIT_L(n) asm volatile("s_waitcnt lgkmcnt(" #n ")" ::: "memory")
; #define PG8_BAR __builtin_amdgcn_s_barrier()
; #define PG8_SCHED __builtin_amdgcn_sched_barrier(0)
; template <class Epi, class Sched, bool ALIGN_EPI = false, bool SP2 = false>
; __device__ __forceinline__ void gemm_phase(PG8_LAS unsigned char* lds, const Gemm g, const Sched& S, const Epi& E) {
;     ...
;             PG8_LDB(B0, 0, 0); PG8_LDB(B1, 0, 1); PG8_SCHED; PG8_LDA(At, 0, 0); PG8_STAGE(PG8_SA(1, 1), a1 + hstep, voffA);
;             PG8_WAIT_V(8); PG8_WAIT_L(0); PG8_BAR; PG8_MMA(0, 0, At, B0); PG8_MMA(0, 1, At, B1); PG8_BAR; PG8_SCHED;
;             PG8_LDA(At, 0, 1); PG8_STAGE(PG8_SB(0, 0), b2, voffB); PG8_STAGE(PG8_SB(0, 1), b2 + hstep, voffB); PG8_STAGE(PG8_SA(0, 0), a2, voffA);
;             PG8_WAIT_V(8); PG8_WAIT_L(0); PG8_BAR; PG8_MMA(1, 0, At, B0); PG8_MMA(1, 1, At, B1); PG8_BAR; PG8_SCHED;
.LBB0_1247:
	s_add_u32 s6, s4, 0xfffc0080
	s_addc_u32 s7, s5, -1
	s_cmp_eq_u32 s56, 12
	s_cselect_b32 s9, s10, s7
	s_cselect_b32 s8, s11, s6
	s_cselect_b32 s7, s27, s53
	s_cselect_b32 s6, s29, s52
	v_lshl_add_u64 v[154:155], s[4:5], 0, v[136:137]
	s_add_i32 m0, s40, 0xc000
	ds_read_b128 v[144:147], v163
	global_load_lds_dwordx4 v[154:155], off
	v_lshl_add_u64 v[154:155], s[4:5], 0, v[138:139]
	s_add_i32 m0, s40, 0xe000
	ds_read_b128 v[174:177], v163 offset:1024
	global_load_lds_dwordx4 v[154:155], off
	ds_read_b128 v[178:181], v163 offset:2048
	ds_read_b128 v[182:185], v163 offset:3072
	ds_read_b128 v[186:189], v170
	ds_read_b128 v[190:193], v170 offset:1024
	ds_read_b128 v[194:197], v170 offset:2048
	ds_read_b128 v[198:201], v170 offset:3072
	ds_read_b128 v[202:205], v171
	ds_read_b128 v[206:209], v171 offset:1024
	ds_read_b128 v[210:213], v171 offset:2048
	ds_read_b128 v[214:217], v171 offset:3072
	ds_read_b128 v[218:221], v171 offset:4096
	ds_read_b128 v[222:225], v171 offset:5120
	ds_read_b128 v[226:229], v171 offset:6144
	ds_read_b128 v[230:233], v171 offset:7168
	s_waitcnt vmcnt(8)
	s_waitcnt lgkmcnt(0)
	s_barrier
	s_setprio 1
	s_waitcnt lgkmcnt(0)
	v_mfma_f32_16x16x32_bf16 v[124:127], v[144:147], v[202:205], v[124:127]
	v_mfma_f32_16x16x32_bf16 v[120:123], v[178:181], v[202:205], v[120:123]
	v_mfma_f32_16x16x32_bf16 v[108:111], v[144:147], v[210:213], v[108:111]
	v_mfma_f32_16x16x32_bf16 v[104:107], v[178:181], v[210:213], v[104:107]
	v_mfma_f32_16x16x32_bf16 v[92:95], v[144:147], v[218:221], v[92:95]
	v_mfma_f32_16x16x32_bf16 v[88:91], v[178:181], v[218:221], v[88:91]
	v_mfma_f32_16x16x32_bf16 v[76:79], v[144:147], v[226:229], v[76:79]
	v_mfma_f32_16x16x32_bf16 v[72:75], v[178:181], v[226:229], v[72:75]
	v_mfma_f32_16x16x32_bf16 v[124:127], v[174:177], v[206:209], v[124:127]
	v_mfma_f32_16x16x32_bf16 v[120:123], v[182:185], v[206:209], v[120:123]
	v_mfma_f32_16x16x32_bf16 v[108:111], v[174:177], v[214:217], v[108:111]
	v_mfma_f32_16x16x32_bf16 v[104:107], v[182:185], v[214:217], v[104:107]
	v_mfma_f32_16x16x32_bf16 v[92:95], v[174:177], v[222:225], v[92:95]
	v_mfma_f32_16x16x32_bf16 v[88:91], v[182:185], v[222:225], v[88:91]
	v_mfma_f32_16x16x32_bf16 v[76:79], v[174:177], v[230:233], v[76:79]
	v_mfma_f32_16x16x32_bf16 v[72:75], v[182:185], v[230:233], v[72:75]
	s_setprio 0
	s_setprio 1
	v_mfma_f32_16x16x32_bf16 v[116:119], v[186:189], v[202:205], v[116:119]
	v_mfma_f32_16x16x32_bf16 v[112:115], v[194:197], v[202:205], v[112:115]
	v_mfma_f32_16x16x32_bf16 v[100:103], v[186:189], v[210:213], v[100:103]
	v_mfma_f32_16x16x32_bf16 v[96:99], v[194:197], v[210:213], v[96:99]
	v_mfma_f32_16x16x32_bf16 v[84:87], v[186:189], v[218:221], v[84:87]
	v_mfma_f32_16x16x32_bf16 v[80:83], v[194:197], v[218:221], v[80:83]
	v_mfma_f32_16x16x32_bf16 v[68:71], v[186:189], v[226:229], v[68:71]
	v_mfma_f32_16x16x32_bf16 v[64:67], v[194:197], v[226:229], v[64:67]
	v_mfma_f32_16x16x32_bf16 v[116:119], v[190:193], v[206:209], v[116:119]
	v_mfma_f32_16x16x32_bf16 v[112:115], v[198:201], v[206:209], v[112:115]
	v_mfma_f32_16x16x32_bf16 v[100:103], v[190:193], v[214:217], v[100:103]
	v_mfma_f32_16x16x32_bf16 v[96:99], v[198:201], v[214:217], v[96:99]
	v_mfma_f32_16x16x32_bf16 v[84:87], v[190:193], v[222:225], v[84:87]
	v_mfma_f32_16x16x32_bf16 v[80:83], v[198:201], v[222:225], v[80:83]
	v_mfma_f32_16x16x32_bf16 v[68:71], v[190:193], v[230:233], v[68:71]
	v_mfma_f32_16x16x32_bf16 v[64:67], v[198:201], v[230:233], v[64:67]
	s_setprio 0
	s_barrier
	s_add_i32 s57, s60, s39
	v_lshl_add_u64 v[154:155], s[6:7], 0, v[130:131]
	s_mov_b32 m0, s57
	v_lshl_add_u64 v[234:235], s[6:7], 0, v[134:135]
	global_load_lds_dwordx4 v[154:155], off
	s_add_i32 m0, s57, 0x2000
	s_add_u32 s70, s6, 0x40000
	s_addc_u32 s71, s7, 0
	s_add_i32 s57, s61, s39
	global_load_lds_dwordx4 v[234:235], off
	v_lshl_add_u64 v[236:237], s[70:71], 0, v[130:131]
	s_mov_b32 m0, s57
	v_lshl_add_u64 v[238:239], s[8:9], 0, v[132:133]
	global_load_lds_dwordx4 v[236:237], off
	v_lshl_add_u64 v[236:237], s[70:71], 0, v[134:135]
	s_add_i32 m0, s57, 0x2000
	ds_read_b128 v[202:205], v171 offset:16384
	global_load_lds_dwordx4 v[236:237], off
	v_lshl_add_u64 v[236:237], s[8:9], 0, v[128:129]
	s_mov_b32 m0, s40
	ds_read_b128 v[206:209], v171 offset:17408
	global_load_lds_dwordx4 v[236:237], off
	s_mov_b32 m0, s41
	ds_read_b128 v[210:213], v171 offset:18432
	global_load_lds_dwordx4 v[238:239], off
	ds_read_b128 v[214:217], v171 offset:19456
	ds_read_b128 v[218:221], v171 offset:20480
	ds_read_b128 v[222:225], v171 offset:21504
	ds_read_b128 v[226:229], v171 offset:22528
	ds_read_b128 v[230:233], v171 offset:23552
	s_waitcnt vmcnt(8)
	s_waitcnt lgkmcnt(0)
	s_barrier
; #define PG8_STAGE(bufoff, gbase, voff) do { _Pragma("unroll") for (int _i = 0; _i < 2; ++_i) \
;         __builtin_amdgcn_global_load_lds((const unsigned*)((const char*)(gbase) + (voff)[_i]), (PG8_LAS unsigned*)(lds + (bufoff) + ldsw + _i * 8192), 16, 0, 0); } while (0)
; #define PG8_LDA(dst, b, h) do { _Pragma("unroll") for (int m = 0; m < 4; ++m) _Pragma("unroll") for (int k = 0; k < 2; ++k) dst[m][k] = *(const PG8_LAS bf16x8*)(lds + PG8_SA(b, h) + aoff + m * 2048 + k * 1024); } while (0)
; #define PG8_LDB(dst, b, h) do { _Pragma("unroll") for (int n = 0; n < 2; ++n) _Pragma("unroll") for (int k = 0; k < 2; ++k) dst[n][k] = *(const PG8_LAS bf16x8*)(lds + PG8_SB(b, h) + boff + n * 2048 + k * 1024); } while (0)
; #define PG8_MMA(ai, bj, At, Bt) do { __builtin_amdgcn_s_setprio(1); _Pragma("unroll") for (int m = 0; m < 4; ++m) _Pragma("unroll") for (int n = 0; n < 2; ++n) _Pragma("unroll") for (int k = 0; k < 2; ++k) \
;         acc[ai][bj][m][n] = __builtin_amdgcn_mfma_f32_16x16x32_bf16(Bt[n][k], At[m][k], acc[ai][bj][m][n], 0, 0, 0); __builtin_amdgcn_s_setprio(0); } while (0)
; #define PG8_WAIT_V(n) asm volatile("s_waitcnt vmcnt(" #n ")" ::: "memory")
; #define PG8_WAIT_L(n) asm volatile("s_waitcnt lgkmcnt(" #n ")" ::: "memory")
; #define PG8_BAR __builtin_amdgcn_s_barrier()
; #define PG8_SCHED __builtin_amdgcn_sched_barrier(0)
; template <class Epi, class Sched, bool ALIGN_EPI = false, bool SP2 = false>
; __device__ __forceinline__ void gemm_phase(PG8_LAS unsigned char* lds, const Gemm g, const Sched& S, const Epi& E) {
;     ...
;             PG8_WAIT_V(8); PG8_WAIT_L(0); PG8_BAR; PG8_MMA(1, 0, At, B0); PG8_MMA(1, 1, At, B1); PG8_BAR; PG8_SCHED;
;             PG8_LDB(B0, 1, 0); PG8_LDB(B1, 1, 1); PG8_SCHED; PG8_LDA(At, 1, 0); PG8_STAGE(PG8_SA(0, 1), a2 + hstep, voffA);
;             PG8_WAIT_V(8); PG8_WAIT_L(0); PG8_BAR; PG8_MMA(0, 0, At, B0); PG8_MMA(0, 1, At, B1); PG8_BAR; PG8_SCHED;
	s_setprio 1
	s_waitcnt lgkmcnt(0)
	v_mfma_f32_16x16x32_bf16 v[60:63], v[144:147], v[202:205], v[60:63]
	v_mfma_f32_16x16x32_bf16 v[56:59], v[178:181], v[202:205], v[56:59]
	v_mfma_f32_16x16x32_bf16 v[44:47], v[144:147], v[210:213], v[44:47]
	v_mfma_f32_16x16x32_bf16 v[40:43], v[178:181], v[210:213], v[40:43]
	v_mfma_f32_16x16x32_bf16 v[28:31], v[144:147], v[218:221], v[28:31]
	v_mfma_f32_16x16x32_bf16 v[24:27], v[178:181], v[218:221], v[24:27]
	v_mfma_f32_16x16x32_bf16 v[12:15], v[144:147], v[226:229], v[12:15]
	v_mfma_f32_16x16x32_bf16 v[8:11], v[178:181], v[226:229], v[8:11]
	v_mfma_f32_16x16x32_bf16 v[60:63], v[174:177], v[206:209], v[60:63]
	v_mfma_f32_16x16x32_bf16 v[56:59], v[182:185], v[206:209], v[56:59]
	v_mfma_f32_16x16x32_bf16 v[44:47], v[174:177], v[214:217], v[44:47]
	v_mfma_f32_16x16x32_bf16 v[40:43], v[182:185], v[214:217], v[40:43]
	v_mfma_f32_16x16x32_bf16 v[28:31], v[174:177], v[222:225], v[28:31]
	v_mfma_f32_16x16x32_bf16 v[24:27], v[182:185], v[222:225], v[24:27]
	v_mfma_f32_16x16x32_bf16 v[12:15], v[174:177], v[230:233], v[12:15]
	v_mfma_f32_16x16x32_bf16 v[8:11], v[182:185], v[230:233], v[8:11]
	s_setprio 0
	s_setprio 1
	v_mfma_f32_16x16x32_bf16 v[52:55], v[186:189], v[202:205], v[52:55]
	v_mfma_f32_16x16x32_bf16 v[48:51], v[194:197], v[202:205], v[48:51]
	v_mfma_f32_16x16x32_bf16 v[36:39], v[186:189], v[210:213], v[36:39]
	v_mfma_f32_16x16x32_bf16 v[32:35], v[194:197], v[210:213], v[32:35]
	v_mfma_f32_16x16x32_bf16 v[20:23], v[186:189], v[218:221], v[20:23]
	v_mfma_f32_16x16x32_bf16 v[16:19], v[194:197], v[218:221], v[16:19]
	v_mfma_f32_16x16x32_bf16 v[4:7], v[186:189], v[226:229], v[4:7]
	v_mfma_f32_16x16x32_bf16 v[0:3], v[194:197], v[226:229], v[0:3]
	v_mfma_f32_16x16x32_bf16 v[52:55], v[190:193], v[206:209], v[52:55]
	v_mfma_f32_16x16x32_bf16 v[48:51], v[198:201], v[206:209], v[48:51]
	v_mfma_f32_16x16x32_bf16 v[36:39], v[190:193], v[214:217], v[36:39]
	v_mfma_f32_16x16x32_bf16 v[32:35], v[198:201], v[214:217], v[32:35]
	v_mfma_f32_16x16x32_bf16 v[20:23], v[190:193], v[222:225], v[20:23]
	v_mfma_f32_16x16x32_bf16 v[16:19], v[198:201], v[222:225], v[16:19]
	v_mfma_f32_16x16x32_bf16 v[4:7], v[190:193], v[230:233], v[4:7]
	v_mfma_f32_16x16x32_bf16 v[0:3], v[198:201], v[230:233], v[0:3]
	s_setprio 0
	s_barrier
	s_add_i32 s57, 0, 0x18000
	s_add_i32 s69, 0, 0x1c000
	s_add_u32 s8, s8, 0x40000
	s_addc_u32 s9, s9, 0
	s_mov_b32 m0, s42
	v_lshl_add_u64 v[240:241], s[8:9], 0, v[128:129]
	global_load_lds_dwordx4 v[240:241], off
	v_lshl_add_u64 v[240:241], s[8:9], 0, v[132:133]
	s_mov_b32 m0, s43
	v_add_u32_e32 v152, s57, v161
	global_load_lds_dwordx4 v[240:241], off
	ds_read_b128 v[144:147], v152
	ds_read_b128 v[174:177], v152 offset:1024
	ds_read_b128 v[178:181], v152 offset:2048
	ds_read_b128 v[182:185], v152 offset:3072
	v_add_u32_e32 v152, s69, v161
	ds_read_b128 v[186:189], v152
	ds_read_b128 v[190:193], v152 offset:1024
	ds_read_b128 v[194:197], v152 offset:2048
	ds_read_b128 v[198:201], v152 offset:3072
	ds_read_b128 v[202:205], v171 offset:32768
	ds_read_b128 v[206:209], v171 offset:33792
	ds_read_b128 v[210:213], v171 offset:34816
	ds_read_b128 v[214:217], v171 offset:35840
	ds_read_b128 v[218:221], v171 offset:36864
	ds_read_b128 v[222:225], v171 offset:37888
	ds_read_b128 v[226:229], v171 offset:38912
	ds_read_b128 v[230:233], v171 offset:39936
	s_waitcnt vmcnt(8)
	s_waitcnt lgkmcnt(0)
	s_barrier
	s_setprio 1
	s_waitcnt lgkmcnt(0)
	v_mfma_f32_16x16x32_bf16 v[124:127], v[144:147], v[202:205], v[124:127]
	v_mfma_f32_16x16x32_bf16 v[120:123], v[178:181], v[202:205], v[120:123]
	v_mfma_f32_16x16x32_bf16 v[108:111], v[144:147], v[210:213], v[108:111]
	v_mfma_f32_16x16x32_bf16 v[104:107], v[178:181], v[210:213], v[104:107]
	v_mfma_f32_16x16x32_bf16 v[92:95], v[144:147], v[218:221], v[92:95]
	v_mfma_f32_16x16x32_bf16 v[88:91], v[178:181], v[218:221], v[88:91]
	v_mfma_f32_16x16x32_bf16 v[76:79], v[144:147], v[226:229], v[76:79]
	v_mfma_f32_16x16x32_bf16 v[72:75], v[178:181], v[226:229], v[72:75]
	v_mfma_f32_16x16x32_bf16 v[124:127], v[174:177], v[206:209], v[124:127]
	v_mfma_f32_16x16x32_bf16 v[120:123], v[182:185], v[206:209], v[120:123]
	v_mfma_f32_16x16x32_bf16 v[108:111], v[174:177], v[214:217], v[108:111]
	v_mfma_f32_16x16x32_bf16 v[104:107], v[182:185], v[214:217], v[104:107]
	v_mfma_f32_16x16x32_bf16 v[92:95], v[174:177], v[222:225], v[92:95]
	v_mfma_f32_16x16x32_bf16 v[88:91], v[182:185], v[222:225], v[88:91]
	v_mfma_f32_16x16x32_bf16 v[76:79], v[174:177], v[230:233], v[76:79]
	v_mfma_f32_16x16x32_bf16 v[72:75], v[182:185], v[230:233], v[72:75]
	s_setprio 0
	s_setprio 1
	v_mfma_f32_16x16x32_bf16 v[116:119], v[186:189], v[202:205], v[116:119]
	v_mfma_f32_16x16x32_bf16 v[112:115], v[194:197], v[202:205], v[112:115]
	v_mfma_f32_16x16x32_bf16 v[100:103], v[186:189], v[210:213], v[100:103]
	v_mfma_f32_16x16x32_bf16 v[96:99], v[194:197], v[210:213], v[96:99]
	v_mfma_f32_16x16x32_bf16 v[84:87], v[186:189], v[218:221], v[84:87]
	v_mfma_f32_16x16x32_bf16 v[80:83], v[194:197], v[218:221], v[80:83]
	v_mfma_f32_16x16x32_bf16 v[68:71], v[186:189], v[226:229], v[68:71]
	v_mfma_f32_16x16x32_bf16 v[64:67], v[194:197], v[226:229], v[64:67]
	v_mfma_f32_16x16x32_bf16 v[116:119], v[190:193], v[206:209], v[116:119]
	v_mfma_f32_16x16x32_bf16 v[112:115], v[198:201], v[206:209], v[112:115]
	v_mfma_f32_16x16x32_bf16 v[100:103], v[190:193], v[214:217], v[100:103]
	v_mfma_f32_16x16x32_bf16 v[96:99], v[198:201], v[214:217], v[96:99]
	v_mfma_f32_16x16x32_bf16 v[84:87], v[190:193], v[222:225], v[84:87]
	v_mfma_f32_16x16x32_bf16 v[80:83], v[198:201], v[222:225], v[80:83]
	v_mfma_f32_16x16x32_bf16 v[68:71], v[190:193], v[230:233], v[68:71]
	v_mfma_f32_16x16x32_bf16 v[64:67], v[198:201], v[230:233], v[64:67]
	s_setprio 0
	s_barrier
; #define PG8_STAGE(bufoff, gbase, voff) do { _Pragma("unroll") for (int _i = 0; _i < 2; ++_i) \
;         __builtin_amdgcn_global_load_lds((const unsigned*)((const char*)(gbase) + (voff)[_i]), (PG8_LAS unsigned*)(lds + (bufoff) + ldsw + _i * 8192), 16, 0, 0); } while (0)
; #define PG8_LDA(dst, b, h) do { _Pragma("unroll") for (int m = 0; m < 4; ++m) _Pragma("unroll") for (int k = 0; k < 2; ++k) dst[m][k] = *(const PG8_LAS bf16x8*)(lds + PG8_SA(b, h) + aoff + m * 2048 + k * 1024); } while (0)
; #define PG8_MMA(ai, bj, At, Bt) do { __builtin_amdgcn_s_setprio(1); _Pragma("unroll") for (int m = 0; m < 4; ++m) _Pragma("unroll") for (int n = 0; n < 2; ++n) _Pragma("unroll") for (int k = 0; k < 2; ++k) \
;         acc[ai][bj][m][n] = __builtin_amdgcn_mfma_f32_16x16x32_bf16(Bt[n][k], At[m][k], acc[ai][bj][m][n], 0, 0, 0); __builtin_amdgcn_s_setprio(0); } while (0)
; #define PG8_WAIT_V(n) asm volatile("s_waitcnt vmcnt(" #n ")" ::: "memory")
; #define PG8_WAIT_L(n) asm volatile("s_waitcnt lgkmcnt(" #n ")" ::: "memory")
; #define PG8_BAR __builtin_amdgcn_s_barrier()
; #define PG8_SCHED __builtin_amdgcn_sched_barrier(0)
; template <class Epi, class Sched, bool ALIGN_EPI = false, bool SP2 = false>
; __device__ __forceinline__ void gemm_phase(PG8_LAS unsigned char* lds, const Gemm g, const Sched& S, const Epi& E) {
;     ...
;             PG8_WAIT_V(8); PG8_WAIT_L(0); PG8_BAR; PG8_MMA(0, 0, At, B0); PG8_MMA(0, 1, At, B1); PG8_BAR; PG8_SCHED;
;             PG8_LDA(At, 1, 1); PG8_STAGE(PG8_SB(1, 0), b3, voffB); PG8_STAGE(PG8_SB(1, 1), b3 + hstep, voffB); PG8_STAGE(PG8_SA(1, 0), a3, voffA);
;             PG8_WAIT_V(8); PG8_WAIT_L(0); PG8_BAR; PG8_MMA(1, 0, At, B0); PG8_MMA(1, 1, At, B1); PG8_BAR; PG8_SCHED;
	s_add_i32 s8, s57, s39
	v_lshl_add_u64 v[154:155], v[154:155], 0, s[18:19]
	s_mov_b32 m0, s8
	ds_read_b128 v[202:205], v171 offset:49152
	global_load_lds_dwordx4 v[154:155], off
	s_add_i32 m0, s8, 0x2000
	s_add_u32 s6, s6, 0x40080
	v_lshl_add_u64 v[154:155], v[234:235], 0, s[18:19]
	s_addc_u32 s7, s7, 0
	s_add_i32 s8, s69, s39
	global_load_lds_dwordx4 v[154:155], off
	v_lshl_add_u64 v[154:155], s[6:7], 0, v[130:131]
	s_mov_b32 m0, s8
	ds_read_b128 v[206:209], v171 offset:50176
	global_load_lds_dwordx4 v[154:155], off
	v_lshl_add_u64 v[154:155], s[6:7], 0, v[134:135]
	s_add_i32 m0, s8, 0x2000
	ds_read_b128 v[210:213], v171 offset:51200
	global_load_lds_dwordx4 v[154:155], off
	v_lshl_add_u64 v[154:155], v[236:237], 0, s[18:19]
	s_mov_b32 m0, s45
	ds_read_b128 v[214:217], v171 offset:52224
	global_load_lds_dwordx4 v[154:155], off
	v_lshl_add_u64 v[154:155], v[238:239], 0, s[18:19]
	s_mov_b32 m0, s50
	ds_read_b128 v[218:221], v171 offset:53248
	global_load_lds_dwordx4 v[154:155], off
	ds_read_b128 v[222:225], v171 offset:54272
	ds_read_b128 v[226:229], v171 offset:55296
	ds_read_b128 v[230:233], v171 offset:56320
	s_waitcnt vmcnt(8)
	s_waitcnt lgkmcnt(0)
	s_barrier
	s_setprio 1
	s_waitcnt lgkmcnt(0)
	v_mfma_f32_16x16x32_bf16 v[60:63], v[144:147], v[202:205], v[60:63]
	v_mfma_f32_16x16x32_bf16 v[56:59], v[178:181], v[202:205], v[56:59]
	v_mfma_f32_16x16x32_bf16 v[44:47], v[144:147], v[210:213], v[44:47]
	v_mfma_f32_16x16x32_bf16 v[40:43], v[178:181], v[210:213], v[40:43]
	v_mfma_f32_16x16x32_bf16 v[28:31], v[144:147], v[218:221], v[28:31]
	v_mfma_f32_16x16x32_bf16 v[24:27], v[178:181], v[218:221], v[24:27]
	v_mfma_f32_16x16x32_bf16 v[12:15], v[144:147], v[226:229], v[12:15]
	v_mfma_f32_16x16x32_bf16 v[8:11], v[178:181], v[226:229], v[8:11]
	v_mfma_f32_16x16x32_bf16 v[60:63], v[174:177], v[206:209], v[60:63]
	v_mfma_f32_16x16x32_bf16 v[56:59], v[182:185], v[206:209], v[56:59]
	v_mfma_f32_16x16x32_bf16 v[44:47], v[174:177], v[214:217], v[44:47]
	v_mfma_f32_16x16x32_bf16 v[40:43], v[182:185], v[214:217], v[40:43]
	v_mfma_f32_16x16x32_bf16 v[28:31], v[174:177], v[222:225], v[28:31]
	v_mfma_f32_16x16x32_bf16 v[24:27], v[182:185], v[222:225], v[24:27]
	v_mfma_f32_16x16x32_bf16 v[12:15], v[174:177], v[230:233], v[12:15]
	v_mfma_f32_16x16x32_bf16 v[8:11], v[182:185], v[230:233], v[8:11]
	s_setprio 0
	s_setprio 1
	v_mfma_f32_16x16x32_bf16 v[52:55], v[186:189], v[202:205], v[52:55]
	v_mfma_f32_16x16x32_bf16 v[48:51], v[194:197], v[202:205], v[48:51]
	v_mfma_f32_16x16x32_bf16 v[36:39], v[186:189], v[210:213], v[36:39]
	v_mfma_f32_16x16x32_bf16 v[32:35], v[194:197], v[210:213], v[32:35]
	v_mfma_f32_16x16x32_bf16 v[20:23], v[186:189], v[218:221], v[20:23]
	v_mfma_f32_16x16x32_bf16 v[16:19], v[194:197], v[218:221], v[16:19]
	v_mfma_f32_16x16x32_bf16 v[4:7], v[186:189], v[226:229], v[4:7]
	v_mfma_f32_16x16x32_bf16 v[0:3], v[194:197], v[226:229], v[0:3]
	v_mfma_f32_16x16x32_bf16 v[52:55], v[190:193], v[206:209], v[52:55]
	v_mfma_f32_16x16x32_bf16 v[48:51], v[198:201], v[206:209], v[48:51]
	v_mfma_f32_16x16x32_bf16 v[36:39], v[190:193], v[214:217], v[36:39]
	v_mfma_f32_16x16x32_bf16 v[32:35], v[198:201], v[214:217], v[32:35]
	v_mfma_f32_16x16x32_bf16 v[20:23], v[190:193], v[222:225], v[20:23]
	v_mfma_f32_16x16x32_bf16 v[16:19], v[198:201], v[222:225], v[16:19]
	v_mfma_f32_16x16x32_bf16 v[4:7], v[190:193], v[230:233], v[4:7]
	v_mfma_f32_16x16x32_bf16 v[0:3], v[198:201], v[230:233], v[0:3]
	s_setprio 0
	s_barrier
	s_add_i32 s56, s56, 2
	s_add_u32 s4, s4, 0x100
	s_addc_u32 s5, s5, 0
	s_add_u32 s52, s52, 0x100
	s_addc_u32 s53, s53, 0
	s_cmp_gt_u32 s56, 13
	s_cbranch_scc0 .LBB0_1247
	s_nop 0
	s_nop 0
	s_nop 0
	s_nop 0
	s_nop 0
	s_nop 0
	s_nop 0
	s_nop 0
	s_nop 0
	s_and_b64 vcc, exec, s[20:21]
	s_cbranch_vccz .LBB0_1250
	s_barrier

; #define PG8_STAGE(bufoff, gbase, voff) do { _Pragma("unroll") for (int _i = 0; _i < 2; ++_i) \
;         __builtin_amdgcn_global_load_lds((const unsigned*)((const char*)(gbase) + (voff)[_i]), (PG8_LAS unsigned*)(lds + (bufoff) + ldsw + _i * 8192), 16, 0, 0); } while (0)
; #define PG8_LDA(dst, b, h) do { _Pragma("unroll") for (int m = 0; m < 4; ++m) _Pragma("unroll") for (int k = 0; k < 2; ++k) dst[m][k] = *(const PG8_LAS bf16x8*)(lds + PG8_SA(b, h) + aoff + m * 2048 + k * 1024); } while (0)
; #define PG8_LDB(dst, b, h) do { _Pragma("unroll") for (int n = 0; n < 2; ++n) _Pragma("unroll") for (int k = 0; k < 2; ++k) dst[n][k] = *(const PG8_LAS bf16x8*)(lds + PG8_SB(b, h) + boff + n * 2048 + k * 1024); } while (0)
; #define PG8_MMA(ai, bj, At, Bt) do { __builtin_amdgcn_s_setprio(1); _Pragma("unroll") for (int m = 0; m < 4; ++m) _Pragma("unroll") for (int n = 0; n < 2; ++n) _Pragma("unroll") for (int k = 0; k < 2; ++k) \
;         acc[ai][bj][m][n] = __builtin_amdgcn_mfma_f32_16x16x32_bf16(Bt[n][k], At[m][k], acc[ai][bj][m][n], 0, 0, 0); __builtin_amdgcn_s_setprio(0); } while (0)
; #define PG8_WAIT_V(n) asm volatile("s_waitcnt vmcnt(" #n ")" ::: "memory")
; #define PG8_WAIT_L(n) asm volatile("s_waitcnt lgkmcnt(" #n ")" ::: "memory")
; #define PG8_BAR __builtin_amdgcn_s_barrier()
; #define PG8_SCHED __builtin_amdgcn_sched_barrier(0)
; template <class Epi, class Sched, bool ALIGN_EPI = false, bool SP2 = false>
; __device__ __forceinline__ void gemm_phase(PG8_LAS unsigned char* lds, const Gemm g, const Sched& S, const Epi& E) {
;     ...
;             PG8_LDB(B0, 0, 0); PG8_LDB(B1, 0, 1); PG8_SCHED; PG8_LDA(At, 0, 0); PG8_STAGE(PG8_SA(1, 1), a1 + hstep, voffA);
;             PG8_WAIT_V(8); PG8_WAIT_L(0); PG8_BAR; PG8_MMA(0, 0, At, B0); PG8_MMA(0, 1, At, B1); PG8_BAR; PG8_SCHED;
;             PG8_LDA(At, 0, 1); PG8_STAGE(PG8_SB(0, 0), b2, voffB); PG8_STAGE(PG8_SB(0, 1), b2 + hstep, voffB); PG8_STAGE(PG8_SA(0, 0), a2, voffA);
;             PG8_WAIT_V(8); PG8_WAIT_L(0); PG8_BAR; PG8_MMA(1, 0, At, B0); PG8_MMA(1, 1, At, B1); PG8_BAR; PG8_SCHED;
.LBB0_1271:
	s_add_u32 s30, s28, 0xfffe0080
	s_addc_u32 s31, s29, -1
	s_cmp_eq_u32 s63, 4
	s_cselect_b32 s35, s21, s31
	s_cselect_b32 s34, s56, s30
	s_cselect_b32 s31, s19, s62
	s_cselect_b32 s30, s57, s61
	v_lshl_add_u64 v[160:161], s[28:29], 0, v[144:145]
	s_add_i32 m0, s27, 0xc000
	ds_read_b128 v[156:159], v135
	global_load_lds_dwordx4 v[160:161], off
	v_lshl_add_u64 v[160:161], s[28:29], 0, v[146:147]
	s_add_i32 m0, s27, 0xe000
	ds_read_b128 v[170:173], v135 offset:1024
	global_load_lds_dwordx4 v[160:161], off
	ds_read_b128 v[174:177], v135 offset:2048
	ds_read_b128 v[178:181], v135 offset:3072
	ds_read_b128 v[182:185], v162
	ds_read_b128 v[186:189], v162 offset:1024
	ds_read_b128 v[190:193], v162 offset:2048
	ds_read_b128 v[194:197], v162 offset:3072
	ds_read_b128 v[198:201], v163
	ds_read_b128 v[202:205], v163 offset:1024
	ds_read_b128 v[206:209], v163 offset:2048
	ds_read_b128 v[210:213], v163 offset:3072
	ds_read_b128 v[214:217], v163 offset:4096
	ds_read_b128 v[218:221], v163 offset:5120
	ds_read_b128 v[222:225], v163 offset:6144
	ds_read_b128 v[226:229], v163 offset:7168
	s_waitcnt vmcnt(8)
	s_waitcnt lgkmcnt(0)
	s_barrier
	s_setprio 1
	s_waitcnt lgkmcnt(0)
	v_mfma_f32_16x16x32_bf16 v[124:127], v[156:159], v[198:201], v[124:127]
	v_mfma_f32_16x16x32_bf16 v[120:123], v[174:177], v[198:201], v[120:123]
	v_mfma_f32_16x16x32_bf16 v[108:111], v[156:159], v[206:209], v[108:111]
	v_mfma_f32_16x16x32_bf16 v[104:107], v[174:177], v[206:209], v[104:107]
	v_mfma_f32_16x16x32_bf16 v[92:95], v[156:159], v[214:217], v[92:95]
	v_mfma_f32_16x16x32_bf16 v[88:91], v[174:177], v[214:217], v[88:91]
	v_mfma_f32_16x16x32_bf16 v[76:79], v[156:159], v[222:225], v[76:79]
	v_mfma_f32_16x16x32_bf16 v[72:75], v[174:177], v[222:225], v[72:75]
	v_mfma_f32_16x16x32_bf16 v[124:127], v[170:173], v[202:205], v[124:127]
	v_mfma_f32_16x16x32_bf16 v[120:123], v[178:181], v[202:205], v[120:123]
	v_mfma_f32_16x16x32_bf16 v[108:111], v[170:173], v[210:213], v[108:111]
	v_mfma_f32_16x16x32_bf16 v[104:107], v[178:181], v[210:213], v[104:107]
	v_mfma_f32_16x16x32_bf16 v[92:95], v[170:173], v[218:221], v[92:95]
	v_mfma_f32_16x16x32_bf16 v[88:91], v[178:181], v[218:221], v[88:91]
	v_mfma_f32_16x16x32_bf16 v[76:79], v[170:173], v[226:229], v[76:79]
	v_mfma_f32_16x16x32_bf16 v[72:75], v[178:181], v[226:229], v[72:75]
	s_setprio 0
	s_setprio 1
	v_mfma_f32_16x16x32_bf16 v[116:119], v[182:185], v[198:201], v[116:119]
	v_mfma_f32_16x16x32_bf16 v[112:115], v[190:193], v[198:201], v[112:115]
	v_mfma_f32_16x16x32_bf16 v[100:103], v[182:185], v[206:209], v[100:103]
	v_mfma_f32_16x16x32_bf16 v[96:99], v[190:193], v[206:209], v[96:99]
	v_mfma_f32_16x16x32_bf16 v[84:87], v[182:185], v[214:217], v[84:87]
	v_mfma_f32_16x16x32_bf16 v[80:83], v[190:193], v[214:217], v[80:83]
	v_mfma_f32_16x16x32_bf16 v[68:71], v[182:185], v[222:225], v[68:71]
	v_mfma_f32_16x16x32_bf16 v[64:67], v[190:193], v[222:225], v[64:67]
	v_mfma_f32_16x16x32_bf16 v[116:119], v[186:189], v[202:205], v[116:119]
	v_mfma_f32_16x16x32_bf16 v[112:115], v[194:197], v[202:205], v[112:115]
	v_mfma_f32_16x16x32_bf16 v[100:103], v[186:189], v[210:213], v[100:103]
	v_mfma_f32_16x16x32_bf16 v[96:99], v[194:197], v[210:213], v[96:99]
	v_mfma_f32_16x16x32_bf16 v[84:87], v[186:189], v[218:221], v[84:87]
	v_mfma_f32_16x16x32_bf16 v[80:83], v[194:197], v[218:221], v[80:83]
	v_mfma_f32_16x16x32_bf16 v[68:71], v[186:189], v[226:229], v[68:71]
	v_mfma_f32_16x16x32_bf16 v[64:67], v[194:197], v[226:229], v[64:67]
	s_setprio 0
	s_barrier
	s_add_i32 s68, s45, s37
	v_lshl_add_u64 v[160:161], s[30:31], 0, v[138:139]
	s_mov_b32 m0, s68
	v_lshl_add_u64 v[230:231], s[30:31], 0, v[142:143]
	global_load_lds_dwordx4 v[160:161], off
	s_add_i32 m0, s68, 0x2000
	s_add_u32 s68, s30, 0x20000
	s_addc_u32 s69, s31, 0
	s_add_i32 s70, s50, s37
	global_load_lds_dwordx4 v[230:231], off
	v_lshl_add_u64 v[232:233], s[68:69], 0, v[138:139]
	s_mov_b32 m0, s70
	v_lshl_add_u64 v[234:235], s[34:35], 0, v[140:141]
	global_load_lds_dwordx4 v[232:233], off
	v_lshl_add_u64 v[232:233], s[68:69], 0, v[142:143]
	s_add_i32 m0, s70, 0x2000
	ds_read_b128 v[198:201], v163 offset:16384
	global_load_lds_dwordx4 v[232:233], off
	v_lshl_add_u64 v[232:233], s[34:35], 0, v[136:137]
	s_mov_b32 m0, s27
	ds_read_b128 v[202:205], v163 offset:17408
	global_load_lds_dwordx4 v[232:233], off
	s_mov_b32 m0, s38
	ds_read_b128 v[206:209], v163 offset:18432
	global_load_lds_dwordx4 v[234:235], off
	ds_read_b128 v[210:213], v163 offset:19456
	ds_read_b128 v[214:217], v163 offset:20480
	ds_read_b128 v[218:221], v163 offset:21504
	ds_read_b128 v[222:225], v163 offset:22528
	ds_read_b128 v[226:229], v163 offset:23552
	s_waitcnt vmcnt(8)
	s_waitcnt lgkmcnt(0)
	s_barrier
; #define PG8_STAGE(bufoff, gbase, voff) do { _Pragma("unroll") for (int _i = 0; _i < 2; ++_i) \
;         __builtin_amdgcn_global_load_lds((const unsigned*)((const char*)(gbase) + (voff)[_i]), (PG8_LAS unsigned*)(lds + (bufoff) + ldsw + _i * 8192), 16, 0, 0); } while (0)
; #define PG8_LDA(dst, b, h) do { _Pragma("unroll") for (int m = 0; m < 4; ++m) _Pragma("unroll") for (int k = 0; k < 2; ++k) dst[m][k] = *(const PG8_LAS bf16x8*)(lds + PG8_SA(b, h) + aoff + m * 2048 + k * 1024); } while (0)
; #define PG8_LDB(dst, b, h) do { _Pragma("unroll") for (int n = 0; n < 2; ++n) _Pragma("unroll") for (int k = 0; k < 2; ++k) dst[n][k] = *(const PG8_LAS bf16x8*)(lds + PG8_SB(b, h) + boff + n * 2048 + k * 1024); } while (0)
; #define PG8_MMA(ai, bj, At, Bt) do { __builtin_amdgcn_s_setprio(1); _Pragma("unroll") for (int m = 0; m < 4; ++m) _Pragma("unroll") for (int n = 0; n < 2; ++n) _Pragma("unroll") for (int k = 0; k < 2; ++k) \
;         acc[ai][bj][m][n] = __builtin_amdgcn_mfma_f32_16x16x32_bf16(Bt[n][k], At[m][k], acc[ai][bj][m][n], 0, 0, 0); __builtin_amdgcn_s_setprio(0); } while (0)
; #define PG8_WAIT_V(n) asm volatile("s_waitcnt vmcnt(" #n ")" ::: "memory")
; #define PG8_WAIT_L(n) asm volatile("s_waitcnt lgkmcnt(" #n ")" ::: "memory")
; #define PG8_BAR __builtin_amdgcn_s_barrier()
; #define PG8_SCHED __builtin_amdgcn_sched_barrier(0)
; template <class Epi, class Sched, bool ALIGN_EPI = false, bool SP2 = false>
; __device__ __forceinline__ void gemm_phase(PG8_LAS unsigned char* lds, const Gemm g, const Sched& S, const Epi& E) {
;     ...
;             PG8_WAIT_V(8); PG8_WAIT_L(0); PG8_BAR; PG8_MMA(1, 0, At, B0); PG8_MMA(1, 1, At, B1); PG8_BAR; PG8_SCHED;
;             PG8_LDB(B0, 1, 0); PG8_LDB(B1, 1, 1); PG8_SCHED; PG8_LDA(At, 1, 0); PG8_STAGE(PG8_SA(0, 1), a2 + hstep, voffA);
;             PG8_WAIT_V(8); PG8_WAIT_L(0); PG8_BAR; PG8_MMA(0, 0, At, B0); PG8_MMA(0, 1, At, B1); PG8_BAR; PG8_SCHED;
	s_setprio 1
	s_waitcnt lgkmcnt(0)
	v_mfma_f32_16x16x32_bf16 v[60:63], v[156:159], v[198:201], v[60:63]
	v_mfma_f32_16x16x32_bf16 v[56:59], v[174:177], v[198:201], v[56:59]
	v_mfma_f32_16x16x32_bf16 v[44:47], v[156:159], v[206:209], v[44:47]
	v_mfma_f32_16x16x32_bf16 v[40:43], v[174:177], v[206:209], v[40:43]
	v_mfma_f32_16x16x32_bf16 v[28:31], v[156:159], v[214:217], v[28:31]
	v_mfma_f32_16x16x32_bf16 v[24:27], v[174:177], v[214:217], v[24:27]
	v_mfma_f32_16x16x32_bf16 v[12:15], v[156:159], v[222:225], v[12:15]
	v_mfma_f32_16x16x32_bf16 v[8:11], v[174:177], v[222:225], v[8:11]
	v_mfma_f32_16x16x32_bf16 v[60:63], v[170:173], v[202:205], v[60:63]
	v_mfma_f32_16x16x32_bf16 v[56:59], v[178:181], v[202:205], v[56:59]
	v_mfma_f32_16x16x32_bf16 v[44:47], v[170:173], v[210:213], v[44:47]
	v_mfma_f32_16x16x32_bf16 v[40:43], v[178:181], v[210:213], v[40:43]
	v_mfma_f32_16x16x32_bf16 v[28:31], v[170:173], v[218:221], v[28:31]
	v_mfma_f32_16x16x32_bf16 v[24:27], v[178:181], v[218:221], v[24:27]
	v_mfma_f32_16x16x32_bf16 v[12:15], v[170:173], v[226:229], v[12:15]
	v_mfma_f32_16x16x32_bf16 v[8:11], v[178:181], v[226:229], v[8:11]
	s_setprio 0
	s_setprio 1
	v_mfma_f32_16x16x32_bf16 v[52:55], v[182:185], v[198:201], v[52:55]
	v_mfma_f32_16x16x32_bf16 v[48:51], v[190:193], v[198:201], v[48:51]
	v_mfma_f32_16x16x32_bf16 v[36:39], v[182:185], v[206:209], v[36:39]
	v_mfma_f32_16x16x32_bf16 v[32:35], v[190:193], v[206:209], v[32:35]
	v_mfma_f32_16x16x32_bf16 v[20:23], v[182:185], v[214:217], v[20:23]
	v_mfma_f32_16x16x32_bf16 v[16:19], v[190:193], v[214:217], v[16:19]
	v_mfma_f32_16x16x32_bf16 v[4:7], v[182:185], v[222:225], v[4:7]
	v_mfma_f32_16x16x32_bf16 v[0:3], v[190:193], v[222:225], v[0:3]
	v_mfma_f32_16x16x32_bf16 v[52:55], v[186:189], v[202:205], v[52:55]
	v_mfma_f32_16x16x32_bf16 v[48:51], v[194:197], v[202:205], v[48:51]
	v_mfma_f32_16x16x32_bf16 v[36:39], v[186:189], v[210:213], v[36:39]
	v_mfma_f32_16x16x32_bf16 v[32:35], v[194:197], v[210:213], v[32:35]
	v_mfma_f32_16x16x32_bf16 v[20:23], v[186:189], v[218:221], v[20:23]
	v_mfma_f32_16x16x32_bf16 v[16:19], v[194:197], v[218:221], v[16:19]
	v_mfma_f32_16x16x32_bf16 v[4:7], v[186:189], v[226:229], v[4:7]
	v_mfma_f32_16x16x32_bf16 v[0:3], v[194:197], v[226:229], v[0:3]
	s_setprio 0
	s_barrier
	s_add_i32 s68, 0, 0x18000
	s_add_i32 s69, 0, 0x1c000
	s_add_u32 s34, s34, 0x20000
	s_addc_u32 s35, s35, 0
	s_mov_b32 m0, s39
	v_lshl_add_u64 v[236:237], s[34:35], 0, v[136:137]
	global_load_lds_dwordx4 v[236:237], off
	v_lshl_add_u64 v[236:237], s[34:35], 0, v[140:141]
	s_mov_b32 m0, s40
	v_add_u32_e32 v178, s68, v131
	global_load_lds_dwordx4 v[236:237], off
	v_add_u32_e32 v194, s69, v131
	ds_read_b128 v[156:159], v178
	ds_read_b128 v[170:173], v178 offset:1024
	ds_read_b128 v[174:177], v178 offset:2048
	ds_read_b128 v[178:181], v178 offset:3072
	ds_read_b128 v[182:185], v194
	ds_read_b128 v[186:189], v194 offset:1024
	ds_read_b128 v[190:193], v194 offset:2048
	ds_read_b128 v[194:197], v194 offset:3072
	ds_read_b128 v[198:201], v163 offset:32768
	ds_read_b128 v[202:205], v163 offset:33792
	ds_read_b128 v[206:209], v163 offset:34816
	ds_read_b128 v[210:213], v163 offset:35840
	ds_read_b128 v[214:217], v163 offset:36864
	ds_read_b128 v[218:221], v163 offset:37888
	ds_read_b128 v[222:225], v163 offset:38912
	ds_read_b128 v[226:229], v163 offset:39936
	s_waitcnt vmcnt(8)
	s_waitcnt lgkmcnt(0)
	s_barrier
	s_setprio 1
	s_waitcnt lgkmcnt(0)
	v_mfma_f32_16x16x32_bf16 v[124:127], v[156:159], v[198:201], v[124:127]
	v_mfma_f32_16x16x32_bf16 v[120:123], v[174:177], v[198:201], v[120:123]
	v_mfma_f32_16x16x32_bf16 v[108:111], v[156:159], v[206:209], v[108:111]
	v_mfma_f32_16x16x32_bf16 v[104:107], v[174:177], v[206:209], v[104:107]
	v_mfma_f32_16x16x32_bf16 v[92:95], v[156:159], v[214:217], v[92:95]
	v_mfma_f32_16x16x32_bf16 v[88:91], v[174:177], v[214:217], v[88:91]
	v_mfma_f32_16x16x32_bf16 v[76:79], v[156:159], v[222:225], v[76:79]
	v_mfma_f32_16x16x32_bf16 v[72:75], v[174:177], v[222:225], v[72:75]
	v_mfma_f32_16x16x32_bf16 v[124:127], v[170:173], v[202:205], v[124:127]
	v_mfma_f32_16x16x32_bf16 v[120:123], v[178:181], v[202:205], v[120:123]
	v_mfma_f32_16x16x32_bf16 v[108:111], v[170:173], v[210:213], v[108:111]
	v_mfma_f32_16x16x32_bf16 v[104:107], v[178:181], v[210:213], v[104:107]
	v_mfma_f32_16x16x32_bf16 v[92:95], v[170:173], v[218:221], v[92:95]
	v_mfma_f32_16x16x32_bf16 v[88:91], v[178:181], v[218:221], v[88:91]
	v_mfma_f32_16x16x32_bf16 v[76:79], v[170:173], v[226:229], v[76:79]
	v_mfma_f32_16x16x32_bf16 v[72:75], v[178:181], v[226:229], v[72:75]
	s_setprio 0
	s_setprio 1
	v_mfma_f32_16x16x32_bf16 v[116:119], v[182:185], v[198:201], v[116:119]
	v_mfma_f32_16x16x32_bf16 v[112:115], v[190:193], v[198:201], v[112:115]
	v_mfma_f32_16x16x32_bf16 v[100:103], v[182:185], v[206:209], v[100:103]
	v_mfma_f32_16x16x32_bf16 v[96:99], v[190:193], v[206:209], v[96:99]
	v_mfma_f32_16x16x32_bf16 v[84:87], v[182:185], v[214:217], v[84:87]
	v_mfma_f32_16x16x32_bf16 v[80:83], v[190:193], v[214:217], v[80:83]
	v_mfma_f32_16x16x32_bf16 v[68:71], v[182:185], v[222:225], v[68:71]
	v_mfma_f32_16x16x32_bf16 v[64:67], v[190:193], v[222:225], v[64:67]
	v_mfma_f32_16x16x32_bf16 v[116:119], v[186:189], v[202:205], v[116:119]
	v_mfma_f32_16x16x32_bf16 v[112:115], v[194:197], v[202:205], v[112:115]
	v_mfma_f32_16x16x32_bf16 v[100:103], v[186:189], v[210:213], v[100:103]
	v_mfma_f32_16x16x32_bf16 v[96:99], v[194:197], v[210:213], v[96:99]
	v_mfma_f32_16x16x32_bf16 v[84:87], v[186:189], v[218:221], v[84:87]
	v_mfma_f32_16x16x32_bf16 v[80:83], v[194:197], v[218:221], v[80:83]
	v_mfma_f32_16x16x32_bf16 v[68:71], v[186:189], v[226:229], v[68:71]
	v_mfma_f32_16x16x32_bf16 v[64:67], v[194:197], v[226:229], v[64:67]
	s_setprio 0
	s_barrier
; #define PG8_STAGE(bufoff, gbase, voff) do { _Pragma("unroll") for (int _i = 0; _i < 2; ++_i) \
;         __builtin_amdgcn_global_load_lds((const unsigned*)((const char*)(gbase) + (voff)[_i]), (PG8_LAS unsigned*)(lds + (bufoff) + ldsw + _i * 8192), 16, 0, 0); } while (0)
; #define PG8_LDA(dst, b, h) do { _Pragma("unroll") for (int m = 0; m < 4; ++m) _Pragma("unroll") for (int k = 0; k < 2; ++k) dst[m][k] = *(const PG8_LAS bf16x8*)(lds + PG8_SA(b, h) + aoff + m * 2048 + k * 1024); } while (0)
; #define PG8_MMA(ai, bj, At, Bt) do { __builtin_amdgcn_s_setprio(1); _Pragma("unroll") for (int m = 0; m < 4; ++m) _Pragma("unroll") for (int n = 0; n < 2; ++n) _Pragma("unroll") for (int k = 0; k < 2; ++k) \
;         acc[ai][bj][m][n] = __builtin_amdgcn_mfma_f32_16x16x32_bf16(Bt[n][k], At[m][k], acc[ai][bj][m][n], 0, 0, 0); __builtin_amdgcn_s_setprio(0); } while (0)
; #define PG8_WAIT_V(n) asm volatile("s_waitcnt vmcnt(" #n ")" ::: "memory")
; #define PG8_WAIT_L(n) asm volatile("s_waitcnt lgkmcnt(" #n ")" ::: "memory")
; #define PG8_BAR __builtin_amdgcn_s_barrier()
; #define PG8_SCHED __builtin_amdgcn_sched_barrier(0)
; template <class Epi, class Sched, bool ALIGN_EPI = false, bool SP2 = false>
; __device__ __forceinline__ void gemm_phase(PG8_LAS unsigned char* lds, const Gemm g, const Sched& S, const Epi& E) {
;     ...
;             PG8_WAIT_V(8); PG8_WAIT_L(0); PG8_BAR; PG8_MMA(0, 0, At, B0); PG8_MMA(0, 1, At, B1); PG8_BAR; PG8_SCHED;
;             PG8_LDA(At, 1, 1); PG8_STAGE(PG8_SB(1, 0), b3, voffB); PG8_STAGE(PG8_SB(1, 1), b3 + hstep, voffB); PG8_STAGE(PG8_SA(1, 0), a3, voffA);
;             PG8_WAIT_V(8); PG8_WAIT_L(0); PG8_BAR; PG8_MMA(1, 0, At, B0); PG8_MMA(1, 1, At, B1); PG8_BAR; PG8_SCHED;
	s_add_i32 s34, s68, s37
	v_lshl_add_u64 v[160:161], v[160:161], 0, s[6:7]
	s_mov_b32 m0, s34
	ds_read_b128 v[198:201], v163 offset:49152
	global_load_lds_dwordx4 v[160:161], off
	s_add_i32 m0, s34, 0x2000
	s_add_u32 s30, s30, 0x20080
	v_lshl_add_u64 v[160:161], v[230:231], 0, s[6:7]
	s_addc_u32 s31, s31, 0
	s_add_i32 s34, s69, s37
	global_load_lds_dwordx4 v[160:161], off
	v_lshl_add_u64 v[160:161], s[30:31], 0, v[138:139]
	s_mov_b32 m0, s34
	ds_read_b128 v[202:205], v163 offset:50176
	global_load_lds_dwordx4 v[160:161], off
	v_lshl_add_u64 v[160:161], s[30:31], 0, v[142:143]
	s_add_i32 m0, s34, 0x2000
	ds_read_b128 v[206:209], v163 offset:51200
	global_load_lds_dwordx4 v[160:161], off
	v_lshl_add_u64 v[160:161], v[232:233], 0, s[6:7]
	s_mov_b32 m0, s42
	ds_read_b128 v[210:213], v163 offset:52224
	global_load_lds_dwordx4 v[160:161], off
	v_lshl_add_u64 v[160:161], v[234:235], 0, s[6:7]
	s_mov_b32 m0, s43
	ds_read_b128 v[214:217], v163 offset:53248
	global_load_lds_dwordx4 v[160:161], off
	ds_read_b128 v[218:221], v163 offset:54272
	ds_read_b128 v[222:225], v163 offset:55296
	ds_read_b128 v[226:229], v163 offset:56320
	s_waitcnt vmcnt(8)
	s_waitcnt lgkmcnt(0)
	s_barrier
	s_setprio 1
	s_waitcnt lgkmcnt(0)
	v_mfma_f32_16x16x32_bf16 v[60:63], v[156:159], v[198:201], v[60:63]
	v_mfma_f32_16x16x32_bf16 v[56:59], v[174:177], v[198:201], v[56:59]
	v_mfma_f32_16x16x32_bf16 v[44:47], v[156:159], v[206:209], v[44:47]
	v_mfma_f32_16x16x32_bf16 v[40:43], v[174:177], v[206:209], v[40:43]
	v_mfma_f32_16x16x32_bf16 v[28:31], v[156:159], v[214:217], v[28:31]
	v_mfma_f32_16x16x32_bf16 v[24:27], v[174:177], v[214:217], v[24:27]
	v_mfma_f32_16x16x32_bf16 v[12:15], v[156:159], v[222:225], v[12:15]
	v_mfma_f32_16x16x32_bf16 v[8:11], v[174:177], v[222:225], v[8:11]
	v_mfma_f32_16x16x32_bf16 v[60:63], v[170:173], v[202:205], v[60:63]
	v_mfma_f32_16x16x32_bf16 v[56:59], v[178:181], v[202:205], v[56:59]
	v_mfma_f32_16x16x32_bf16 v[44:47], v[170:173], v[210:213], v[44:47]
	v_mfma_f32_16x16x32_bf16 v[40:43], v[178:181], v[210:213], v[40:43]
	v_mfma_f32_16x16x32_bf16 v[28:31], v[170:173], v[218:221], v[28:31]
	v_mfma_f32_16x16x32_bf16 v[24:27], v[178:181], v[218:221], v[24:27]
	v_mfma_f32_16x16x32_bf16 v[12:15], v[170:173], v[226:229], v[12:15]
	v_mfma_f32_16x16x32_bf16 v[8:11], v[178:181], v[226:229], v[8:11]
	s_setprio 0
	s_setprio 1
	v_mfma_f32_16x16x32_bf16 v[52:55], v[182:185], v[198:201], v[52:55]
	v_mfma_f32_16x16x32_bf16 v[48:51], v[190:193], v[198:201], v[48:51]
	v_mfma_f32_16x16x32_bf16 v[36:39], v[182:185], v[206:209], v[36:39]
	v_mfma_f32_16x16x32_bf16 v[32:35], v[190:193], v[206:209], v[32:35]
	v_mfma_f32_16x16x32_bf16 v[20:23], v[182:185], v[214:217], v[20:23]
	v_mfma_f32_16x16x32_bf16 v[16:19], v[190:193], v[214:217], v[16:19]
	v_mfma_f32_16x16x32_bf16 v[4:7], v[182:185], v[222:225], v[4:7]
	v_mfma_f32_16x16x32_bf16 v[0:3], v[190:193], v[222:225], v[0:3]
	v_mfma_f32_16x16x32_bf16 v[52:55], v[186:189], v[202:205], v[52:55]
	v_mfma_f32_16x16x32_bf16 v[48:51], v[194:197], v[202:205], v[48:51]
	v_mfma_f32_16x16x32_bf16 v[36:39], v[186:189], v[210:213], v[36:39]
	v_mfma_f32_16x16x32_bf16 v[32:35], v[194:197], v[210:213], v[32:35]
	v_mfma_f32_16x16x32_bf16 v[20:23], v[186:189], v[218:221], v[20:23]
	v_mfma_f32_16x16x32_bf16 v[16:19], v[194:197], v[218:221], v[16:19]
	v_mfma_f32_16x16x32_bf16 v[4:7], v[186:189], v[226:229], v[4:7]
	v_mfma_f32_16x16x32_bf16 v[0:3], v[194:197], v[226:229], v[0:3]
	s_setprio 0
	s_barrier
	s_add_i32 s63, s63, 2
	s_add_u32 s28, s28, 0x100
	s_addc_u32 s29, s29, 0
	s_add_u32 s61, s61, 0x100
	s_addc_u32 s62, s62, 0
	s_cmp_gt_u32 s63, 5
	s_cbranch_scc0 .LBB0_1271
	s_nop 0
	s_nop 0
	s_nop 0
	s_nop 0
	s_nop 0
	s_nop 0
	s_nop 0
	s_nop 0
	s_nop 0
	s_and_b64 vcc, exec, s[8:9]
	s_cbranch_vccz .LBB0_1274
	s_barrier

; #define PG8_STAGE(bufoff, gbase, voff) do { _Pragma("unroll") for (int _i = 0; _i < 2; ++_i) \
;         __builtin_amdgcn_global_load_lds((const unsigned*)((const char*)(gbase) + (voff)[_i]), (PG8_LAS unsigned*)(lds + (bufoff) + ldsw + _i * 8192), 16, 0, 0); } while (0)
; #define PG8_LDA(dst, b, h) do { _Pragma("unroll") for (int m = 0; m < 4; ++m) _Pragma("unroll") for (int k = 0; k < 2; ++k) dst[m][k] = *(const PG8_LAS bf16x8*)(lds + PG8_SA(b, h) + aoff + m * 2048 + k * 1024); } while (0)
; #define PG8_LDB(dst, b, h) do { _Pragma("unroll") for (int n = 0; n < 2; ++n) _Pragma("unroll") for (int k = 0; k < 2; ++k) dst[n][k] = *(const PG8_LAS bf16x8*)(lds + PG8_SB(b, h) + boff + n * 2048 + k * 1024); } while (0)
; #define PG8_MMA(ai, bj, At, Bt) do { __builtin_amdgcn_s_setprio(1); _Pragma("unroll") for (int m = 0; m < 4; ++m) _Pragma("unroll") for (int n = 0; n < 2; ++n) _Pragma("unroll") for (int k = 0; k < 2; ++k) \
;         acc[ai][bj][m][n] = __builtin_amdgcn_mfma_f32_16x16x32_bf16(Bt[n][k], At[m][k], acc[ai][bj][m][n], 0, 0, 0); __builtin_amdgcn_s_setprio(0); } while (0)
; #define PG8_WAIT_V(n) asm volatile("s_waitcnt vmcnt(" #n ")" ::: "memory")
; #define PG8_WAIT_L(n) asm volatile("s_waitcnt lgkmcnt(" #n ")" ::: "memory")
; #define PG8_BAR __builtin_amdgcn_s_barrier()
; #define PG8_SCHED __builtin_amdgcn_sched_barrier(0)
; template <class Epi, class Sched, bool ALIGN_EPI = false, bool SP2 = false>
; __device__ __forceinline__ void gemm_phase(PG8_LAS unsigned char* lds, const Gemm g, const Sched& S, const Epi& E) {
;     ...
;             PG8_LDB(B0, 0, 0); PG8_LDB(B1, 0, 1); PG8_SCHED; PG8_LDA(At, 0, 0); PG8_STAGE(PG8_SA(1, 1), a1 + hstep, voffA);
;             PG8_WAIT_V(8); PG8_WAIT_L(0); PG8_BAR; PG8_MMA(0, 0, At, B0); PG8_MMA(0, 1, At, B1); PG8_BAR; PG8_SCHED;
;             PG8_LDA(At, 0, 1); PG8_STAGE(PG8_SB(0, 0), b2, voffB); PG8_STAGE(PG8_SB(0, 1), b2 + hstep, voffB); PG8_STAGE(PG8_SA(0, 0), a2, voffA);
;             PG8_WAIT_V(8); PG8_WAIT_L(0); PG8_BAR; PG8_MMA(1, 0, At, B0); PG8_MMA(1, 1, At, B1); PG8_BAR; PG8_SCHED;
.LBB0_1295:
	s_add_u32 s8, s6, 0xfffc0080
	s_addc_u32 s9, s7, -1
	s_cmp_eq_u32 s68, 12
	s_cselect_b32 s11, s12, s9
	s_cselect_b32 s10, s13, s8
	s_cselect_b32 s9, s27, s53
	s_cselect_b32 s8, s29, s52
	v_lshl_add_u64 v[162:163], s[6:7], 0, v[144:145]
	s_add_i32 m0, s40, 0xc000
	ds_read_b128 v[156:159], v143
	global_load_lds_dwordx4 v[162:163], off
	v_lshl_add_u64 v[162:163], s[6:7], 0, v[146:147]
	s_add_i32 m0, s40, 0xe000
	ds_read_b128 v[172:175], v143 offset:1024
	global_load_lds_dwordx4 v[162:163], off
	ds_read_b128 v[176:179], v143 offset:2048
	ds_read_b128 v[180:183], v143 offset:3072
	ds_read_b128 v[184:187], v161
	ds_read_b128 v[188:191], v161 offset:1024
	ds_read_b128 v[192:195], v161 offset:2048
	ds_read_b128 v[196:199], v161 offset:3072
	ds_read_b128 v[200:203], v170
	ds_read_b128 v[204:207], v170 offset:1024
	ds_read_b128 v[208:211], v170 offset:2048
	ds_read_b128 v[212:215], v170 offset:3072
	ds_read_b128 v[216:219], v170 offset:4096
	ds_read_b128 v[220:223], v170 offset:5120
	ds_read_b128 v[224:227], v170 offset:6144
	ds_read_b128 v[228:231], v170 offset:7168
	s_waitcnt vmcnt(8)
	s_waitcnt lgkmcnt(0)
	s_barrier
	s_setprio 1
	s_waitcnt lgkmcnt(0)
	v_mfma_f32_16x16x32_bf16 v[124:127], v[156:159], v[200:203], v[124:127]
	v_mfma_f32_16x16x32_bf16 v[120:123], v[176:179], v[200:203], v[120:123]
	v_mfma_f32_16x16x32_bf16 v[108:111], v[156:159], v[208:211], v[108:111]
	v_mfma_f32_16x16x32_bf16 v[104:107], v[176:179], v[208:211], v[104:107]
	v_mfma_f32_16x16x32_bf16 v[92:95], v[156:159], v[216:219], v[92:95]
	v_mfma_f32_16x16x32_bf16 v[88:91], v[176:179], v[216:219], v[88:91]
	v_mfma_f32_16x16x32_bf16 v[76:79], v[156:159], v[224:227], v[76:79]
	v_mfma_f32_16x16x32_bf16 v[72:75], v[176:179], v[224:227], v[72:75]
	v_mfma_f32_16x16x32_bf16 v[124:127], v[172:175], v[204:207], v[124:127]
	v_mfma_f32_16x16x32_bf16 v[120:123], v[180:183], v[204:207], v[120:123]
	v_mfma_f32_16x16x32_bf16 v[108:111], v[172:175], v[212:215], v[108:111]
	v_mfma_f32_16x16x32_bf16 v[104:107], v[180:183], v[212:215], v[104:107]
	v_mfma_f32_16x16x32_bf16 v[92:95], v[172:175], v[220:223], v[92:95]
	v_mfma_f32_16x16x32_bf16 v[88:91], v[180:183], v[220:223], v[88:91]
	v_mfma_f32_16x16x32_bf16 v[76:79], v[172:175], v[228:231], v[76:79]
	v_mfma_f32_16x16x32_bf16 v[72:75], v[180:183], v[228:231], v[72:75]
	s_setprio 0
	s_setprio 1
	v_mfma_f32_16x16x32_bf16 v[116:119], v[184:187], v[200:203], v[116:119]
	v_mfma_f32_16x16x32_bf16 v[112:115], v[192:195], v[200:203], v[112:115]
	v_mfma_f32_16x16x32_bf16 v[100:103], v[184:187], v[208:211], v[100:103]
	v_mfma_f32_16x16x32_bf16 v[96:99], v[192:195], v[208:211], v[96:99]
	v_mfma_f32_16x16x32_bf16 v[84:87], v[184:187], v[216:219], v[84:87]
	v_mfma_f32_16x16x32_bf16 v[80:83], v[192:195], v[216:219], v[80:83]
	v_mfma_f32_16x16x32_bf16 v[68:71], v[184:187], v[224:227], v[68:71]
	v_mfma_f32_16x16x32_bf16 v[64:67], v[192:195], v[224:227], v[64:67]
	v_mfma_f32_16x16x32_bf16 v[116:119], v[188:191], v[204:207], v[116:119]
	v_mfma_f32_16x16x32_bf16 v[112:115], v[196:199], v[204:207], v[112:115]
	v_mfma_f32_16x16x32_bf16 v[100:103], v[188:191], v[212:215], v[100:103]
	v_mfma_f32_16x16x32_bf16 v[96:99], v[196:199], v[212:215], v[96:99]
	v_mfma_f32_16x16x32_bf16 v[84:87], v[188:191], v[220:223], v[84:87]
	v_mfma_f32_16x16x32_bf16 v[80:83], v[196:199], v[220:223], v[80:83]
	v_mfma_f32_16x16x32_bf16 v[68:71], v[188:191], v[228:231], v[68:71]
	v_mfma_f32_16x16x32_bf16 v[64:67], v[196:199], v[228:231], v[64:67]
	s_setprio 0
	s_barrier
	s_add_i32 s69, s56, s39
	v_lshl_add_u64 v[162:163], s[8:9], 0, v[130:131]
	s_mov_b32 m0, s69
	v_lshl_add_u64 v[232:233], s[8:9], 0, v[134:135]
	global_load_lds_dwordx4 v[162:163], off
	s_add_i32 m0, s69, 0x2000
	s_add_u32 s70, s8, 0x40000
	s_addc_u32 s71, s9, 0
	s_add_i32 s69, s57, s39
	global_load_lds_dwordx4 v[232:233], off
	v_lshl_add_u64 v[234:235], s[70:71], 0, v[130:131]
	s_mov_b32 m0, s69
	v_lshl_add_u64 v[236:237], s[10:11], 0, v[132:133]
	global_load_lds_dwordx4 v[234:235], off
	v_lshl_add_u64 v[234:235], s[70:71], 0, v[134:135]
	s_add_i32 m0, s69, 0x2000
	ds_read_b128 v[200:203], v170 offset:16384
	global_load_lds_dwordx4 v[234:235], off
	v_lshl_add_u64 v[234:235], s[10:11], 0, v[128:129]
	s_mov_b32 m0, s40
	ds_read_b128 v[204:207], v170 offset:17408
	global_load_lds_dwordx4 v[234:235], off
	s_mov_b32 m0, s41
	ds_read_b128 v[208:211], v170 offset:18432
	global_load_lds_dwordx4 v[236:237], off
	ds_read_b128 v[212:215], v170 offset:19456
	ds_read_b128 v[216:219], v170 offset:20480
	ds_read_b128 v[220:223], v170 offset:21504
	ds_read_b128 v[224:227], v170 offset:22528
	ds_read_b128 v[228:231], v170 offset:23552
	s_waitcnt vmcnt(8)
	s_waitcnt lgkmcnt(0)
	s_barrier
; #define PG8_STAGE(bufoff, gbase, voff) do { _Pragma("unroll") for (int _i = 0; _i < 2; ++_i) \
;         __builtin_amdgcn_global_load_lds((const unsigned*)((const char*)(gbase) + (voff)[_i]), (PG8_LAS unsigned*)(lds + (bufoff) + ldsw + _i * 8192), 16, 0, 0); } while (0)
; #define PG8_LDA(dst, b, h) do { _Pragma("unroll") for (int m = 0; m < 4; ++m) _Pragma("unroll") for (int k = 0; k < 2; ++k) dst[m][k] = *(const PG8_LAS bf16x8*)(lds + PG8_SA(b, h) + aoff + m * 2048 + k * 1024); } while (0)
; #define PG8_LDB(dst, b, h) do { _Pragma("unroll") for (int n = 0; n < 2; ++n) _Pragma("unroll") for (int k = 0; k < 2; ++k) dst[n][k] = *(const PG8_LAS bf16x8*)(lds + PG8_SB(b, h) + boff + n * 2048 + k * 1024); } while (0)
; #define PG8_MMA(ai, bj, At, Bt) do { __builtin_amdgcn_s_setprio(1); _Pragma("unroll") for (int m = 0; m < 4; ++m) _Pragma("unroll") for (int n = 0; n < 2; ++n) _Pragma("unroll") for (int k = 0; k < 2; ++k) \
;         acc[ai][bj][m][n] = __builtin_amdgcn_mfma_f32_16x16x32_bf16(Bt[n][k], At[m][k], acc[ai][bj][m][n], 0, 0, 0); __builtin_amdgcn_s_setprio(0); } while (0)
; #define PG8_WAIT_V(n) asm volatile("s_waitcnt vmcnt(" #n ")" ::: "memory")
; #define PG8_WAIT_L(n) asm volatile("s_waitcnt lgkmcnt(" #n ")" ::: "memory")
; #define PG8_BAR __builtin_amdgcn_s_barrier()
; #define PG8_SCHED __builtin_amdgcn_sched_barrier(0)
; template <class Epi, class Sched, bool ALIGN_EPI = false, bool SP2 = false>
; __device__ __forceinline__ void gemm_phase(PG8_LAS unsigned char* lds, const Gemm g, const Sched& S, const Epi& E) {
;     ...
;             PG8_WAIT_V(8); PG8_WAIT_L(0); PG8_BAR; PG8_MMA(1, 0, At, B0); PG8_MMA(1, 1, At, B1); PG8_BAR; PG8_SCHED;
;             PG8_LDB(B0, 1, 0); PG8_LDB(B1, 1, 1); PG8_SCHED; PG8_LDA(At, 1, 0); PG8_STAGE(PG8_SA(0, 1), a2 + hstep, voffA);
;             PG8_WAIT_V(8); PG8_WAIT_L(0); PG8_BAR; PG8_MMA(0, 0, At, B0); PG8_MMA(0, 1, At, B1); PG8_BAR; PG8_SCHED;
	s_setprio 1
	s_waitcnt lgkmcnt(0)
	v_mfma_f32_16x16x32_bf16 v[60:63], v[156:159], v[200:203], v[60:63]
	v_mfma_f32_16x16x32_bf16 v[56:59], v[176:179], v[200:203], v[56:59]
	v_mfma_f32_16x16x32_bf16 v[44:47], v[156:159], v[208:211], v[44:47]
	v_mfma_f32_16x16x32_bf16 v[40:43], v[176:179], v[208:211], v[40:43]
	v_mfma_f32_16x16x32_bf16 v[28:31], v[156:159], v[216:219], v[28:31]
	v_mfma_f32_16x16x32_bf16 v[24:27], v[176:179], v[216:219], v[24:27]
	v_mfma_f32_16x16x32_bf16 v[12:15], v[156:159], v[224:227], v[12:15]
	v_mfma_f32_16x16x32_bf16 v[8:11], v[176:179], v[224:227], v[8:11]
	v_mfma_f32_16x16x32_bf16 v[60:63], v[172:175], v[204:207], v[60:63]
	v_mfma_f32_16x16x32_bf16 v[56:59], v[180:183], v[204:207], v[56:59]
	v_mfma_f32_16x16x32_bf16 v[44:47], v[172:175], v[212:215], v[44:47]
	v_mfma_f32_16x16x32_bf16 v[40:43], v[180:183], v[212:215], v[40:43]
	v_mfma_f32_16x16x32_bf16 v[28:31], v[172:175], v[220:223], v[28:31]
	v_mfma_f32_16x16x32_bf16 v[24:27], v[180:183], v[220:223], v[24:27]
	v_mfma_f32_16x16x32_bf16 v[12:15], v[172:175], v[228:231], v[12:15]
	v_mfma_f32_16x16x32_bf16 v[8:11], v[180:183], v[228:231], v[8:11]
	s_setprio 0
	s_setprio 1
	v_mfma_f32_16x16x32_bf16 v[52:55], v[184:187], v[200:203], v[52:55]
	v_mfma_f32_16x16x32_bf16 v[48:51], v[192:195], v[200:203], v[48:51]
	v_mfma_f32_16x16x32_bf16 v[36:39], v[184:187], v[208:211], v[36:39]
	v_mfma_f32_16x16x32_bf16 v[32:35], v[192:195], v[208:211], v[32:35]
	v_mfma_f32_16x16x32_bf16 v[20:23], v[184:187], v[216:219], v[20:23]
	v_mfma_f32_16x16x32_bf16 v[16:19], v[192:195], v[216:219], v[16:19]
	v_mfma_f32_16x16x32_bf16 v[4:7], v[184:187], v[224:227], v[4:7]
	v_mfma_f32_16x16x32_bf16 v[0:3], v[192:195], v[224:227], v[0:3]
	v_mfma_f32_16x16x32_bf16 v[52:55], v[188:191], v[204:207], v[52:55]
	v_mfma_f32_16x16x32_bf16 v[48:51], v[196:199], v[204:207], v[48:51]
	v_mfma_f32_16x16x32_bf16 v[36:39], v[188:191], v[212:215], v[36:39]
	v_mfma_f32_16x16x32_bf16 v[32:35], v[196:199], v[212:215], v[32:35]
	v_mfma_f32_16x16x32_bf16 v[20:23], v[188:191], v[220:223], v[20:23]
	v_mfma_f32_16x16x32_bf16 v[16:19], v[196:199], v[220:223], v[16:19]
	v_mfma_f32_16x16x32_bf16 v[4:7], v[188:191], v[228:231], v[4:7]
	v_mfma_f32_16x16x32_bf16 v[0:3], v[196:199], v[228:231], v[0:3]
	s_setprio 0
	s_barrier
	s_add_i32 s69, 0, 0x18000
	s_add_i32 s70, 0, 0x1c000
	s_add_u32 s10, s10, 0x40000
	s_addc_u32 s11, s11, 0
	s_mov_b32 m0, s42
	v_lshl_add_u64 v[238:239], s[10:11], 0, v[128:129]
	global_load_lds_dwordx4 v[238:239], off
	v_lshl_add_u64 v[238:239], s[10:11], 0, v[132:133]
	s_mov_b32 m0, s43
	v_add_u32_e32 v160, s69, v139
	global_load_lds_dwordx4 v[238:239], off
	ds_read_b128 v[156:159], v160
	ds_read_b128 v[172:175], v160 offset:1024
	ds_read_b128 v[176:179], v160 offset:2048
	ds_read_b128 v[180:183], v160 offset:3072
	v_add_u32_e32 v160, s70, v139
	ds_read_b128 v[184:187], v160
	ds_read_b128 v[188:191], v160 offset:1024
	ds_read_b128 v[192:195], v160 offset:2048
	ds_read_b128 v[196:199], v160 offset:3072
	ds_read_b128 v[200:203], v170 offset:32768
	ds_read_b128 v[204:207], v170 offset:33792
	ds_read_b128 v[208:211], v170 offset:34816
	ds_read_b128 v[212:215], v170 offset:35840
	ds_read_b128 v[216:219], v170 offset:36864
	ds_read_b128 v[220:223], v170 offset:37888
	ds_read_b128 v[224:227], v170 offset:38912
	ds_read_b128 v[228:231], v170 offset:39936
	s_waitcnt vmcnt(8)
	s_waitcnt lgkmcnt(0)
	s_barrier
	s_setprio 1
	s_waitcnt lgkmcnt(0)
	v_mfma_f32_16x16x32_bf16 v[124:127], v[156:159], v[200:203], v[124:127]
	v_mfma_f32_16x16x32_bf16 v[120:123], v[176:179], v[200:203], v[120:123]
	v_mfma_f32_16x16x32_bf16 v[108:111], v[156:159], v[208:211], v[108:111]
	v_mfma_f32_16x16x32_bf16 v[104:107], v[176:179], v[208:211], v[104:107]
	v_mfma_f32_16x16x32_bf16 v[92:95], v[156:159], v[216:219], v[92:95]
	v_mfma_f32_16x16x32_bf16 v[88:91], v[176:179], v[216:219], v[88:91]
	v_mfma_f32_16x16x32_bf16 v[76:79], v[156:159], v[224:227], v[76:79]
	v_mfma_f32_16x16x32_bf16 v[72:75], v[176:179], v[224:227], v[72:75]
	v_mfma_f32_16x16x32_bf16 v[124:127], v[172:175], v[204:207], v[124:127]
	v_mfma_f32_16x16x32_bf16 v[120:123], v[180:183], v[204:207], v[120:123]
	v_mfma_f32_16x16x32_bf16 v[108:111], v[172:175], v[212:215], v[108:111]
	v_mfma_f32_16x16x32_bf16 v[104:107], v[180:183], v[212:215], v[104:107]
	v_mfma_f32_16x16x32_bf16 v[92:95], v[172:175], v[220:223], v[92:95]
	v_mfma_f32_16x16x32_bf16 v[88:91], v[180:183], v[220:223], v[88:91]
	v_mfma_f32_16x16x32_bf16 v[76:79], v[172:175], v[228:231], v[76:79]
	v_mfma_f32_16x16x32_bf16 v[72:75], v[180:183], v[228:231], v[72:75]
	s_setprio 0
	s_setprio 1
	v_mfma_f32_16x16x32_bf16 v[116:119], v[184:187], v[200:203], v[116:119]
	v_mfma_f32_16x16x32_bf16 v[112:115], v[192:195], v[200:203], v[112:115]
	v_mfma_f32_16x16x32_bf16 v[100:103], v[184:187], v[208:211], v[100:103]
	v_mfma_f32_16x16x32_bf16 v[96:99], v[192:195], v[208:211], v[96:99]
	v_mfma_f32_16x16x32_bf16 v[84:87], v[184:187], v[216:219], v[84:87]
	v_mfma_f32_16x16x32_bf16 v[80:83], v[192:195], v[216:219], v[80:83]
	v_mfma_f32_16x16x32_bf16 v[68:71], v[184:187], v[224:227], v[68:71]
	v_mfma_f32_16x16x32_bf16 v[64:67], v[192:195], v[224:227], v[64:67]
	v_mfma_f32_16x16x32_bf16 v[116:119], v[188:191], v[204:207], v[116:119]
	v_mfma_f32_16x16x32_bf16 v[112:115], v[196:199], v[204:207], v[112:115]
	v_mfma_f32_16x16x32_bf16 v[100:103], v[188:191], v[212:215], v[100:103]
	v_mfma_f32_16x16x32_bf16 v[96:99], v[196:199], v[212:215], v[96:99]
	v_mfma_f32_16x16x32_bf16 v[84:87], v[188:191], v[220:223], v[84:87]
	v_mfma_f32_16x16x32_bf16 v[80:83], v[196:199], v[220:223], v[80:83]
	v_mfma_f32_16x16x32_bf16 v[68:71], v[188:191], v[228:231], v[68:71]
	v_mfma_f32_16x16x32_bf16 v[64:67], v[196:199], v[228:231], v[64:67]
	s_setprio 0
	s_barrier
; #define PG8_STAGE(bufoff, gbase, voff) do { _Pragma("unroll") for (int _i = 0; _i < 2; ++_i) \
;         __builtin_amdgcn_global_load_lds((const unsigned*)((const char*)(gbase) + (voff)[_i]), (PG8_LAS unsigned*)(lds + (bufoff) + ldsw + _i * 8192), 16, 0, 0); } while (0)
; #define PG8_LDA(dst, b, h) do { _Pragma("unroll") for (int m = 0; m < 4; ++m) _Pragma("unroll") for (int k = 0; k < 2; ++k) dst[m][k] = *(const PG8_LAS bf16x8*)(lds + PG8_SA(b, h) + aoff + m * 2048 + k * 1024); } while (0)
; #define PG8_MMA(ai, bj, At, Bt) do { __builtin_amdgcn_s_setprio(1); _Pragma("unroll") for (int m = 0; m < 4; ++m) _Pragma("unroll") for (int n = 0; n < 2; ++n) _Pragma("unroll") for (int k = 0; k < 2; ++k) \
;         acc[ai][bj][m][n] = __builtin_amdgcn_mfma_f32_16x16x32_bf16(Bt[n][k], At[m][k], acc[ai][bj][m][n], 0, 0, 0); __builtin_amdgcn_s_setprio(0); } while (0)
; #define PG8_WAIT_V(n) asm volatile("s_waitcnt vmcnt(" #n ")" ::: "memory")
; #define PG8_WAIT_L(n) asm volatile("s_waitcnt lgkmcnt(" #n ")" ::: "memory")
; #define PG8_BAR __builtin_amdgcn_s_barrier()
; #define PG8_SCHED __builtin_amdgcn_sched_barrier(0)
; template <class Epi, class Sched, bool ALIGN_EPI = false, bool SP2 = false>
; __device__ __forceinline__ void gemm_phase(PG8_LAS unsigned char* lds, const Gemm g, const Sched& S, const Epi& E) {
;     ...
;             PG8_LDA(At, 1, 1); PG8_STAGE(PG8_SB(1, 0), b3, voffB); PG8_STAGE(PG8_SB(1, 1), b3 + hstep, voffB); PG8_STAGE(PG8_SA(1, 0), a3, voffA);
;             PG8_WAIT_V(8); PG8_WAIT_L(0); PG8_BAR; PG8_MMA(1, 0, At, B0); PG8_MMA(1, 1, At, B1); PG8_BAR; PG8_SCHED;
	s_add_i32 s10, s69, s39
	v_lshl_add_u64 v[162:163], v[162:163], 0, s[18:19]
	s_mov_b32 m0, s10
	ds_read_b128 v[200:203], v170 offset:49152
	global_load_lds_dwordx4 v[162:163], off
	s_add_i32 m0, s10, 0x2000
	s_add_u32 s8, s8, 0x40080
	v_lshl_add_u64 v[162:163], v[232:233], 0, s[18:19]
	s_addc_u32 s9, s9, 0
	s_add_i32 s10, s70, s39
	global_load_lds_dwordx4 v[162:163], off
	v_lshl_add_u64 v[162:163], s[8:9], 0, v[130:131]
	s_mov_b32 m0, s10
	ds_read_b128 v[204:207], v170 offset:50176
	global_load_lds_dwordx4 v[162:163], off
	v_lshl_add_u64 v[162:163], s[8:9], 0, v[134:135]
	s_add_i32 m0, s10, 0x2000
	ds_read_b128 v[208:211], v170 offset:51200
	global_load_lds_dwordx4 v[162:163], off
	v_lshl_add_u64 v[162:163], v[234:235], 0, s[18:19]
	s_mov_b32 m0, s45
	ds_read_b128 v[212:215], v170 offset:52224
	global_load_lds_dwordx4 v[162:163], off
	v_lshl_add_u64 v[162:163], v[236:237], 0, s[18:19]
	s_mov_b32 m0, s50
	ds_read_b128 v[216:219], v170 offset:53248
	global_load_lds_dwordx4 v[162:163], off
	ds_read_b128 v[220:223], v170 offset:54272
	ds_read_b128 v[224:227], v170 offset:55296
	ds_read_b128 v[228:231], v170 offset:56320
	s_waitcnt vmcnt(8)
	s_waitcnt lgkmcnt(0)
	s_barrier
	s_setprio 1
	s_waitcnt lgkmcnt(0)
	v_mfma_f32_16x16x32_bf16 v[60:63], v[156:159], v[200:203], v[60:63]
	v_mfma_f32_16x16x32_bf16 v[56:59], v[176:179], v[200:203], v[56:59]
	v_mfma_f32_16x16x32_bf16 v[44:47], v[156:159], v[208:211], v[44:47]
	v_mfma_f32_16x16x32_bf16 v[40:43], v[176:179], v[208:211], v[40:43]
	v_mfma_f32_16x16x32_bf16 v[28:31], v[156:159], v[216:219], v[28:31]
	v_mfma_f32_16x16x32_bf16 v[24:27], v[176:179], v[216:219], v[24:27]
	v_mfma_f32_16x16x32_bf16 v[12:15], v[156:159], v[224:227], v[12:15]
	v_mfma_f32_16x16x32_bf16 v[8:11], v[176:179], v[224:227], v[8:11]
	v_mfma_f32_16x16x32_bf16 v[60:63], v[172:175], v[204:207], v[60:63]
	v_mfma_f32_16x16x32_bf16 v[56:59], v[180:183], v[204:207], v[56:59]
	v_mfma_f32_16x16x32_bf16 v[44:47], v[172:175], v[212:215], v[44:47]
	v_mfma_f32_16x16x32_bf16 v[40:43], v[180:183], v[212:215], v[40:43]
	v_mfma_f32_16x16x32_bf16 v[28:31], v[172:175], v[220:223], v[28:31]
	v_mfma_f32_16x16x32_bf16 v[24:27], v[180:183], v[220:223], v[24:27]
	v_mfma_f32_16x16x32_bf16 v[12:15], v[172:175], v[228:231], v[12:15]
	v_mfma_f32_16x16x32_bf16 v[8:11], v[180:183], v[228:231], v[8:11]
	s_setprio 0
	s_setprio 1
	v_mfma_f32_16x16x32_bf16 v[52:55], v[184:187], v[200:203], v[52:55]
	v_mfma_f32_16x16x32_bf16 v[48:51], v[192:195], v[200:203], v[48:51]
	v_mfma_f32_16x16x32_bf16 v[36:39], v[184:187], v[208:211], v[36:39]
	v_mfma_f32_16x16x32_bf16 v[32:35], v[192:195], v[208:211], v[32:35]
	v_mfma_f32_16x16x32_bf16 v[20:23], v[184:187], v[216:219], v[20:23]
	v_mfma_f32_16x16x32_bf16 v[16:19], v[192:195], v[216:219], v[16:19]
	v_mfma_f32_16x16x32_bf16 v[4:7], v[184:187], v[224:227], v[4:7]
	v_mfma_f32_16x16x32_bf16 v[0:3], v[192:195], v[224:227], v[0:3]
	v_mfma_f32_16x16x32_bf16 v[52:55], v[188:191], v[204:207], v[52:55]
	v_mfma_f32_16x16x32_bf16 v[48:51], v[196:199], v[204:207], v[48:51]
	v_mfma_f32_16x16x32_bf16 v[36:39], v[188:191], v[212:215], v[36:39]
	v_mfma_f32_16x16x32_bf16 v[32:35], v[196:199], v[212:215], v[32:35]
	v_mfma_f32_16x16x32_bf16 v[20:23], v[188:191], v[220:223], v[20:23]
	v_mfma_f32_16x16x32_bf16 v[16:19], v[196:199], v[220:223], v[16:19]
	v_mfma_f32_16x16x32_bf16 v[4:7], v[188:191], v[228:231], v[4:7]
	v_mfma_f32_16x16x32_bf16 v[0:3], v[196:199], v[228:231], v[0:3]
	s_setprio 0
	s_barrier
	s_add_i32 s68, s68, 2
	s_add_u32 s6, s6, 0x100
	s_addc_u32 s7, s7, 0
	s_add_u32 s52, s52, 0x100
	s_addc_u32 s53, s53, 0
	s_cmp_gt_u32 s68, 13
	s_cbranch_scc0 .LBB0_1295
	s_nop 0
	s_nop 0
	s_nop 0
	s_nop 0
	s_nop 0
	s_nop 0
	s_nop 0
	s_nop 0
	s_nop 0
	s_and_b64 vcc, exec, s[20:21]
	s_cbranch_vccz .LBB0_1298
	s_barrier

; #define PG8_STAGE(bufoff, gbase, voff) do { _Pragma("unroll") for (int _i = 0; _i < 2; ++_i) \
;         __builtin_amdgcn_global_load_lds((const unsigned*)((const char*)(gbase) + (voff)[_i]), (PG8_LAS unsigned*)(lds + (bufoff) + ldsw + _i * 8192), 16, 0, 0); } while (0)
; #define PG8_LDA(dst, b, h) do { _Pragma("unroll") for (int m = 0; m < 4; ++m) _Pragma("unroll") for (int k = 0; k < 2; ++k) dst[m][k] = *(const PG8_LAS bf16x8*)(lds + PG8_SA(b, h) + aoff + m * 2048 + k * 1024); } while (0)
; #define PG8_LDB(dst, b, h) do { _Pragma("unroll") for (int n = 0; n < 2; ++n) _Pragma("unroll") for (int k = 0; k < 2; ++k) dst[n][k] = *(const PG8_LAS bf16x8*)(lds + PG8_SB(b, h) + boff + n * 2048 + k * 1024); } while (0)
; #define PG8_MMA(ai, bj, At, Bt) do { __builtin_amdgcn_s_setprio(1); _Pragma("unroll") for (int m = 0; m < 4; ++m) _Pragma("unroll") for (int n = 0; n < 2; ++n) _Pragma("unroll") for (int k = 0; k < 2; ++k) \
;         acc[ai][bj][m][n] = __builtin_amdgcn_mfma_f32_16x16x32_bf16(Bt[n][k], At[m][k], acc[ai][bj][m][n], 0, 0, 0); __builtin_amdgcn_s_setprio(0); } while (0)
; #define PG8_WAIT_V(n) asm volatile("s_waitcnt vmcnt(" #n ")" ::: "memory")
; #define PG8_WAIT_L(n) asm volatile("s_waitcnt lgkmcnt(" #n ")" ::: "memory")
; #define PG8_BAR __builtin_amdgcn_s_barrier()
; #define PG8_SCHED __builtin_amdgcn_sched_barrier(0)
; template <class Epi, class Sched, bool ALIGN_EPI = false, bool SP2 = false>
; __device__ __forceinline__ void gemm_phase(PG8_LAS unsigned char* lds, const Gemm g, const Sched& S, const Epi& E) {
;     ...
;             PG8_LDB(B0, 0, 0); PG8_LDB(B1, 0, 1); PG8_SCHED; PG8_LDA(At, 0, 0); PG8_STAGE(PG8_SA(1, 1), a1 + hstep, voffA);
;             PG8_WAIT_V(8); PG8_WAIT_L(0); PG8_BAR; PG8_MMA(0, 0, At, B0); PG8_MMA(0, 1, At, B1); PG8_BAR; PG8_SCHED;
;             PG8_LDA(At, 0, 1); PG8_STAGE(PG8_SB(0, 0), b2, voffB); PG8_STAGE(PG8_SB(0, 1), b2 + hstep, voffB); PG8_STAGE(PG8_SA(0, 0), a2, voffA);
;             PG8_WAIT_V(8); PG8_WAIT_L(0); PG8_BAR; PG8_MMA(1, 0, At, B0); PG8_MMA(1, 1, At, B1); PG8_BAR; PG8_SCHED;
.LBB0_1319:
	s_add_u32 s34, s30, 0xfffe0080
	s_addc_u32 s35, s31, -1
	s_cmp_eq_u32 s69, 4
	s_cselect_b32 s37, s23, s35
	s_cselect_b32 s36, s53, s34
	s_cselect_b32 s35, s21, s68
	s_cselect_b32 s34, s62, s63
	v_lshl_add_u64 v[216:217], s[30:31], 0, v[128:129]
	s_add_i32 m0, s29, 0xc000
	ds_read_b128 v[144:147], v149
	global_load_lds_dwordx4 v[216:217], off
	v_lshl_add_u64 v[216:217], s[30:31], 0, v[130:131]
	s_add_i32 m0, s29, 0xe000
	ds_read_b128 v[152:155], v149 offset:1024
	global_load_lds_dwordx4 v[216:217], off
	ds_read_b128 v[160:163], v149 offset:2048
	ds_read_b128 v[164:167], v149 offset:3072
	ds_read_b128 v[168:171], v151
	ds_read_b128 v[172:175], v151 offset:1024
	ds_read_b128 v[176:179], v151 offset:2048
	ds_read_b128 v[180:183], v151 offset:3072
	ds_read_b128 v[184:187], v159
	ds_read_b128 v[188:191], v159 offset:1024
	ds_read_b128 v[192:195], v159 offset:2048
	ds_read_b128 v[196:199], v159 offset:3072
	ds_read_b128 v[200:203], v159 offset:4096
	ds_read_b128 v[204:207], v159 offset:5120
	ds_read_b128 v[208:211], v159 offset:6144
	ds_read_b128 v[212:215], v159 offset:7168
	s_waitcnt vmcnt(8)
	s_waitcnt lgkmcnt(0)
	s_barrier
	s_setprio 1
	s_waitcnt lgkmcnt(0)
	v_mfma_f32_16x16x32_bf16 v[124:127], v[144:147], v[184:187], v[124:127]
	v_mfma_f32_16x16x32_bf16 v[120:123], v[160:163], v[184:187], v[120:123]
	v_mfma_f32_16x16x32_bf16 v[108:111], v[144:147], v[192:195], v[108:111]
	v_mfma_f32_16x16x32_bf16 v[104:107], v[160:163], v[192:195], v[104:107]
	v_mfma_f32_16x16x32_bf16 v[92:95], v[144:147], v[200:203], v[92:95]
	v_mfma_f32_16x16x32_bf16 v[88:91], v[160:163], v[200:203], v[88:91]
	v_mfma_f32_16x16x32_bf16 v[76:79], v[144:147], v[208:211], v[76:79]
	v_mfma_f32_16x16x32_bf16 v[72:75], v[160:163], v[208:211], v[72:75]
	v_mfma_f32_16x16x32_bf16 v[124:127], v[152:155], v[188:191], v[124:127]
	v_mfma_f32_16x16x32_bf16 v[120:123], v[164:167], v[188:191], v[120:123]
	v_mfma_f32_16x16x32_bf16 v[108:111], v[152:155], v[196:199], v[108:111]
	v_mfma_f32_16x16x32_bf16 v[104:107], v[164:167], v[196:199], v[104:107]
	v_mfma_f32_16x16x32_bf16 v[92:95], v[152:155], v[204:207], v[92:95]
	v_mfma_f32_16x16x32_bf16 v[88:91], v[164:167], v[204:207], v[88:91]
	v_mfma_f32_16x16x32_bf16 v[76:79], v[152:155], v[212:215], v[76:79]
	v_mfma_f32_16x16x32_bf16 v[72:75], v[164:167], v[212:215], v[72:75]
	s_setprio 0
	s_setprio 1
	v_mfma_f32_16x16x32_bf16 v[116:119], v[168:171], v[184:187], v[116:119]
	v_mfma_f32_16x16x32_bf16 v[112:115], v[176:179], v[184:187], v[112:115]
	v_mfma_f32_16x16x32_bf16 v[100:103], v[168:171], v[192:195], v[100:103]
	v_mfma_f32_16x16x32_bf16 v[96:99], v[176:179], v[192:195], v[96:99]
	v_mfma_f32_16x16x32_bf16 v[84:87], v[168:171], v[200:203], v[84:87]
	v_mfma_f32_16x16x32_bf16 v[80:83], v[176:179], v[200:203], v[80:83]
	v_mfma_f32_16x16x32_bf16 v[68:71], v[168:171], v[208:211], v[68:71]
	v_mfma_f32_16x16x32_bf16 v[64:67], v[176:179], v[208:211], v[64:67]
	v_mfma_f32_16x16x32_bf16 v[116:119], v[172:175], v[188:191], v[116:119]
	v_mfma_f32_16x16x32_bf16 v[112:115], v[180:183], v[188:191], v[112:115]
	v_mfma_f32_16x16x32_bf16 v[100:103], v[172:175], v[196:199], v[100:103]
	v_mfma_f32_16x16x32_bf16 v[96:99], v[180:183], v[196:199], v[96:99]
	v_mfma_f32_16x16x32_bf16 v[84:87], v[172:175], v[204:207], v[84:87]
	v_mfma_f32_16x16x32_bf16 v[80:83], v[180:183], v[204:207], v[80:83]
	v_mfma_f32_16x16x32_bf16 v[68:71], v[172:175], v[212:215], v[68:71]
	v_mfma_f32_16x16x32_bf16 v[64:67], v[180:183], v[212:215], v[64:67]
	s_setprio 0
	s_barrier
	s_add_i32 s70, s51, s39
	v_lshl_add_u64 v[216:217], s[34:35], 0, v[138:139]
	s_mov_b32 m0, s70
	v_lshl_add_u64 v[218:219], s[34:35], 0, v[142:143]
	global_load_lds_dwordx4 v[216:217], off
	s_add_i32 m0, s70, 0x2000
	s_add_u32 s70, s34, 0x20000
	s_addc_u32 s71, s35, 0
	s_add_i32 s72, s56, s39
	global_load_lds_dwordx4 v[218:219], off
	v_lshl_add_u64 v[220:221], s[70:71], 0, v[138:139]
	s_mov_b32 m0, s72
	v_lshl_add_u64 v[222:223], s[36:37], 0, v[140:141]
	global_load_lds_dwordx4 v[220:221], off
	v_lshl_add_u64 v[220:221], s[70:71], 0, v[142:143]
	s_add_i32 m0, s72, 0x2000
	ds_read_b128 v[184:187], v159 offset:16384
	global_load_lds_dwordx4 v[220:221], off
	v_lshl_add_u64 v[220:221], s[36:37], 0, v[136:137]
	s_mov_b32 m0, s29
	ds_read_b128 v[188:191], v159 offset:17408
	global_load_lds_dwordx4 v[220:221], off
	s_mov_b32 m0, s40
	ds_read_b128 v[192:195], v159 offset:18432
	global_load_lds_dwordx4 v[222:223], off
	ds_read_b128 v[196:199], v159 offset:19456
	ds_read_b128 v[200:203], v159 offset:20480
	ds_read_b128 v[204:207], v159 offset:21504
	ds_read_b128 v[208:211], v159 offset:22528
	ds_read_b128 v[212:215], v159 offset:23552
	s_waitcnt vmcnt(8)
	s_waitcnt lgkmcnt(0)
	s_barrier
; #define PG8_STAGE(bufoff, gbase, voff) do { _Pragma("unroll") for (int _i = 0; _i < 2; ++_i) \
;         __builtin_amdgcn_global_load_lds((const unsigned*)((const char*)(gbase) + (voff)[_i]), (PG8_LAS unsigned*)(lds + (bufoff) + ldsw + _i * 8192), 16, 0, 0); } while (0)
; #define PG8_LDA(dst, b, h) do { _Pragma("unroll") for (int m = 0; m < 4; ++m) _Pragma("unroll") for (int k = 0; k < 2; ++k) dst[m][k] = *(const PG8_LAS bf16x8*)(lds + PG8_SA(b, h) + aoff + m * 2048 + k * 1024); } while (0)
; #define PG8_LDB(dst, b, h) do { _Pragma("unroll") for (int n = 0; n < 2; ++n) _Pragma("unroll") for (int k = 0; k < 2; ++k) dst[n][k] = *(const PG8_LAS bf16x8*)(lds + PG8_SB(b, h) + boff + n * 2048 + k * 1024); } while (0)
; #define PG8_MMA(ai, bj, At, Bt) do { __builtin_amdgcn_s_setprio(1); _Pragma("unroll") for (int m = 0; m < 4; ++m) _Pragma("unroll") for (int n = 0; n < 2; ++n) _Pragma("unroll") for (int k = 0; k < 2; ++k) \
;         acc[ai][bj][m][n] = __builtin_amdgcn_mfma_f32_16x16x32_bf16(Bt[n][k], At[m][k], acc[ai][bj][m][n], 0, 0, 0); __builtin_amdgcn_s_setprio(0); } while (0)
; #define PG8_WAIT_V(n) asm volatile("s_waitcnt vmcnt(" #n ")" ::: "memory")
; #define PG8_WAIT_L(n) asm volatile("s_waitcnt lgkmcnt(" #n ")" ::: "memory")
; #define PG8_BAR __builtin_amdgcn_s_barrier()
; #define PG8_SCHED __builtin_amdgcn_sched_barrier(0)
; template <class Epi, class Sched, bool ALIGN_EPI = false, bool SP2 = false>
; __device__ __forceinline__ void gemm_phase(PG8_LAS unsigned char* lds, const Gemm g, const Sched& S, const Epi& E) {
;     ...
;             PG8_WAIT_V(8); PG8_WAIT_L(0); PG8_BAR; PG8_MMA(1, 0, At, B0); PG8_MMA(1, 1, At, B1); PG8_BAR; PG8_SCHED;
;             PG8_LDB(B0, 1, 0); PG8_LDB(B1, 1, 1); PG8_SCHED; PG8_LDA(At, 1, 0); PG8_STAGE(PG8_SA(0, 1), a2 + hstep, voffA);
;             PG8_WAIT_V(8); PG8_WAIT_L(0); PG8_BAR; PG8_MMA(0, 0, At, B0); PG8_MMA(0, 1, At, B1); PG8_BAR; PG8_SCHED;
	s_setprio 1
	s_waitcnt lgkmcnt(0)
	v_mfma_f32_16x16x32_bf16 v[60:63], v[144:147], v[184:187], v[60:63]
	v_mfma_f32_16x16x32_bf16 v[56:59], v[160:163], v[184:187], v[56:59]
	v_mfma_f32_16x16x32_bf16 v[44:47], v[144:147], v[192:195], v[44:47]
	v_mfma_f32_16x16x32_bf16 v[40:43], v[160:163], v[192:195], v[40:43]
	v_mfma_f32_16x16x32_bf16 v[28:31], v[144:147], v[200:203], v[28:31]
	v_mfma_f32_16x16x32_bf16 v[24:27], v[160:163], v[200:203], v[24:27]
	v_mfma_f32_16x16x32_bf16 v[12:15], v[144:147], v[208:211], v[12:15]
	v_mfma_f32_16x16x32_bf16 v[8:11], v[160:163], v[208:211], v[8:11]
	v_mfma_f32_16x16x32_bf16 v[60:63], v[152:155], v[188:191], v[60:63]
	v_mfma_f32_16x16x32_bf16 v[56:59], v[164:167], v[188:191], v[56:59]
	v_mfma_f32_16x16x32_bf16 v[44:47], v[152:155], v[196:199], v[44:47]
	v_mfma_f32_16x16x32_bf16 v[40:43], v[164:167], v[196:199], v[40:43]
	v_mfma_f32_16x16x32_bf16 v[28:31], v[152:155], v[204:207], v[28:31]
	v_mfma_f32_16x16x32_bf16 v[24:27], v[164:167], v[204:207], v[24:27]
	v_mfma_f32_16x16x32_bf16 v[12:15], v[152:155], v[212:215], v[12:15]
	v_mfma_f32_16x16x32_bf16 v[8:11], v[164:167], v[212:215], v[8:11]
	s_setprio 0
	s_setprio 1
	v_mfma_f32_16x16x32_bf16 v[52:55], v[168:171], v[184:187], v[52:55]
	v_mfma_f32_16x16x32_bf16 v[48:51], v[176:179], v[184:187], v[48:51]
	v_mfma_f32_16x16x32_bf16 v[36:39], v[168:171], v[192:195], v[36:39]
	v_mfma_f32_16x16x32_bf16 v[32:35], v[176:179], v[192:195], v[32:35]
	v_mfma_f32_16x16x32_bf16 v[20:23], v[168:171], v[200:203], v[20:23]
	v_mfma_f32_16x16x32_bf16 v[16:19], v[176:179], v[200:203], v[16:19]
	v_mfma_f32_16x16x32_bf16 v[4:7], v[168:171], v[208:211], v[4:7]
	v_mfma_f32_16x16x32_bf16 v[0:3], v[176:179], v[208:211], v[0:3]
	v_mfma_f32_16x16x32_bf16 v[52:55], v[172:175], v[188:191], v[52:55]
	v_mfma_f32_16x16x32_bf16 v[48:51], v[180:183], v[188:191], v[48:51]
	v_mfma_f32_16x16x32_bf16 v[36:39], v[172:175], v[196:199], v[36:39]
	v_mfma_f32_16x16x32_bf16 v[32:35], v[180:183], v[196:199], v[32:35]
	v_mfma_f32_16x16x32_bf16 v[20:23], v[172:175], v[204:207], v[20:23]
	v_mfma_f32_16x16x32_bf16 v[16:19], v[180:183], v[204:207], v[16:19]
	v_mfma_f32_16x16x32_bf16 v[4:7], v[172:175], v[212:215], v[4:7]
	v_mfma_f32_16x16x32_bf16 v[0:3], v[180:183], v[212:215], v[0:3]
	s_setprio 0
	s_barrier
	s_add_i32 s70, 0, 0x18000
	s_add_i32 s71, 0, 0x1c000
	s_add_u32 s36, s36, 0x20000
	s_addc_u32 s37, s37, 0
	s_mov_b32 m0, s41
	v_lshl_add_u64 v[224:225], s[36:37], 0, v[136:137]
	global_load_lds_dwordx4 v[224:225], off
	v_lshl_add_u64 v[224:225], s[36:37], 0, v[140:141]
	s_mov_b32 m0, s42
	v_add_u32_e32 v164, s70, v157
	global_load_lds_dwordx4 v[224:225], off
	v_add_u32_e32 v180, s71, v157
	ds_read_b128 v[144:147], v164
	ds_read_b128 v[152:155], v164 offset:1024
	ds_read_b128 v[160:163], v164 offset:2048
	ds_read_b128 v[164:167], v164 offset:3072
	ds_read_b128 v[168:171], v180
	ds_read_b128 v[172:175], v180 offset:1024
	ds_read_b128 v[176:179], v180 offset:2048
	ds_read_b128 v[180:183], v180 offset:3072
	ds_read_b128 v[184:187], v159 offset:32768
	ds_read_b128 v[188:191], v159 offset:33792
	ds_read_b128 v[192:195], v159 offset:34816
	ds_read_b128 v[196:199], v159 offset:35840
	ds_read_b128 v[200:203], v159 offset:36864
	ds_read_b128 v[204:207], v159 offset:37888
	ds_read_b128 v[208:211], v159 offset:38912
	ds_read_b128 v[212:215], v159 offset:39936
	s_waitcnt vmcnt(8)
	s_waitcnt lgkmcnt(0)
	s_barrier
	s_setprio 1
	s_waitcnt lgkmcnt(0)
	v_mfma_f32_16x16x32_bf16 v[124:127], v[144:147], v[184:187], v[124:127]
	v_mfma_f32_16x16x32_bf16 v[120:123], v[160:163], v[184:187], v[120:123]
	v_mfma_f32_16x16x32_bf16 v[108:111], v[144:147], v[192:195], v[108:111]
	v_mfma_f32_16x16x32_bf16 v[104:107], v[160:163], v[192:195], v[104:107]
	v_mfma_f32_16x16x32_bf16 v[92:95], v[144:147], v[200:203], v[92:95]
	v_mfma_f32_16x16x32_bf16 v[88:91], v[160:163], v[200:203], v[88:91]
	v_mfma_f32_16x16x32_bf16 v[76:79], v[144:147], v[208:211], v[76:79]
	v_mfma_f32_16x16x32_bf16 v[72:75], v[160:163], v[208:211], v[72:75]
	v_mfma_f32_16x16x32_bf16 v[124:127], v[152:155], v[188:191], v[124:127]
	v_mfma_f32_16x16x32_bf16 v[120:123], v[164:167], v[188:191], v[120:123]
	v_mfma_f32_16x16x32_bf16 v[108:111], v[152:155], v[196:199], v[108:111]
	v_mfma_f32_16x16x32_bf16 v[104:107], v[164:167], v[196:199], v[104:107]
	v_mfma_f32_16x16x32_bf16 v[92:95], v[152:155], v[204:207], v[92:95]
	v_mfma_f32_16x16x32_bf16 v[88:91], v[164:167], v[204:207], v[88:91]
	v_mfma_f32_16x16x32_bf16 v[76:79], v[152:155], v[212:215], v[76:79]
	v_mfma_f32_16x16x32_bf16 v[72:75], v[164:167], v[212:215], v[72:75]
	s_setprio 0
	s_setprio 1
	v_mfma_f32_16x16x32_bf16 v[116:119], v[168:171], v[184:187], v[116:119]
	v_mfma_f32_16x16x32_bf16 v[112:115], v[176:179], v[184:187], v[112:115]
	v_mfma_f32_16x16x32_bf16 v[100:103], v[168:171], v[192:195], v[100:103]
	v_mfma_f32_16x16x32_bf16 v[96:99], v[176:179], v[192:195], v[96:99]
	v_mfma_f32_16x16x32_bf16 v[84:87], v[168:171], v[200:203], v[84:87]
	v_mfma_f32_16x16x32_bf16 v[80:83], v[176:179], v[200:203], v[80:83]
	v_mfma_f32_16x16x32_bf16 v[68:71], v[168:171], v[208:211], v[68:71]
	v_mfma_f32_16x16x32_bf16 v[64:67], v[176:179], v[208:211], v[64:67]
	v_mfma_f32_16x16x32_bf16 v[116:119], v[172:175], v[188:191], v[116:119]
	v_mfma_f32_16x16x32_bf16 v[112:115], v[180:183], v[188:191], v[112:115]
	v_mfma_f32_16x16x32_bf16 v[100:103], v[172:175], v[196:199], v[100:103]
	v_mfma_f32_16x16x32_bf16 v[96:99], v[180:183], v[196:199], v[96:99]
	v_mfma_f32_16x16x32_bf16 v[84:87], v[172:175], v[204:207], v[84:87]
	v_mfma_f32_16x16x32_bf16 v[80:83], v[180:183], v[204:207], v[80:83]
	v_mfma_f32_16x16x32_bf16 v[68:71], v[172:175], v[212:215], v[68:71]
	v_mfma_f32_16x16x32_bf16 v[64:67], v[180:183], v[212:215], v[64:67]
	s_setprio 0
	s_barrier
; #define PG8_STAGE(bufoff, gbase, voff) do { _Pragma("unroll") for (int _i = 0; _i < 2; ++_i) \
;         __builtin_amdgcn_global_load_lds((const unsigned*)((const char*)(gbase) + (voff)[_i]), (PG8_LAS unsigned*)(lds + (bufoff) + ldsw + _i * 8192), 16, 0, 0); } while (0)
; #define PG8_LDA(dst, b, h) do { _Pragma("unroll") for (int m = 0; m < 4; ++m) _Pragma("unroll") for (int k = 0; k < 2; ++k) dst[m][k] = *(const PG8_LAS bf16x8*)(lds + PG8_SA(b, h) + aoff + m * 2048 + k * 1024); } while (0)
; #define PG8_MMA(ai, bj, At, Bt) do { __builtin_amdgcn_s_setprio(1); _Pragma("unroll") for (int m = 0; m < 4; ++m) _Pragma("unroll") for (int n = 0; n < 2; ++n) _Pragma("unroll") for (int k = 0; k < 2; ++k) \
;         acc[ai][bj][m][n] = __builtin_amdgcn_mfma_f32_16x16x32_bf16(Bt[n][k], At[m][k], acc[ai][bj][m][n], 0, 0, 0); __builtin_amdgcn_s_setprio(0); } while (0)
; #define PG8_WAIT_V(n) asm volatile("s_waitcnt vmcnt(" #n ")" ::: "memory")
; #define PG8_WAIT_L(n) asm volatile("s_waitcnt lgkmcnt(" #n ")" ::: "memory")
; #define PG8_BAR __builtin_amdgcn_s_barrier()
; #define PG8_SCHED __builtin_amdgcn_sched_barrier(0)
; template <class Epi, class Sched, bool ALIGN_EPI = false, bool SP2 = false>
; __device__ __forceinline__ void gemm_phase(PG8_LAS unsigned char* lds, const Gemm g, const Sched& S, const Epi& E) {
;     ...
;             PG8_LDA(At, 1, 1); PG8_STAGE(PG8_SB(1, 0), b3, voffB); PG8_STAGE(PG8_SB(1, 1), b3 + hstep, voffB); PG8_STAGE(PG8_SA(1, 0), a3, voffA);
;             PG8_WAIT_V(8); PG8_WAIT_L(0); PG8_BAR; PG8_MMA(1, 0, At, B0); PG8_MMA(1, 1, At, B1); PG8_BAR; PG8_SCHED;
	s_add_i32 s36, s70, s39
	v_lshl_add_u64 v[216:217], v[216:217], 0, s[4:5]
	s_mov_b32 m0, s36
	ds_read_b128 v[184:187], v159 offset:49152
	global_load_lds_dwordx4 v[216:217], off
	s_add_i32 m0, s36, 0x2000
	s_add_u32 s34, s34, 0x20080
	v_lshl_add_u64 v[216:217], v[218:219], 0, s[4:5]
	s_addc_u32 s35, s35, 0
	s_add_i32 s36, s71, s39
	global_load_lds_dwordx4 v[216:217], off
	v_lshl_add_u64 v[216:217], s[34:35], 0, v[138:139]
	s_mov_b32 m0, s36
	ds_read_b128 v[188:191], v159 offset:50176
	global_load_lds_dwordx4 v[216:217], off
	v_lshl_add_u64 v[216:217], s[34:35], 0, v[142:143]
	s_add_i32 m0, s36, 0x2000
	ds_read_b128 v[192:195], v159 offset:51200
	global_load_lds_dwordx4 v[216:217], off
	v_lshl_add_u64 v[216:217], v[220:221], 0, s[4:5]
	s_mov_b32 m0, s44
	ds_read_b128 v[196:199], v159 offset:52224
	global_load_lds_dwordx4 v[216:217], off
	v_lshl_add_u64 v[216:217], v[222:223], 0, s[4:5]
	s_mov_b32 m0, s45
	ds_read_b128 v[200:203], v159 offset:53248
	global_load_lds_dwordx4 v[216:217], off
	ds_read_b128 v[204:207], v159 offset:54272
	ds_read_b128 v[208:211], v159 offset:55296
	ds_read_b128 v[212:215], v159 offset:56320
	s_waitcnt vmcnt(8)
	s_waitcnt lgkmcnt(0)
	s_barrier
	s_setprio 1
	s_waitcnt lgkmcnt(0)
	v_mfma_f32_16x16x32_bf16 v[60:63], v[144:147], v[184:187], v[60:63]
	v_mfma_f32_16x16x32_bf16 v[56:59], v[160:163], v[184:187], v[56:59]
	v_mfma_f32_16x16x32_bf16 v[44:47], v[144:147], v[192:195], v[44:47]
	v_mfma_f32_16x16x32_bf16 v[40:43], v[160:163], v[192:195], v[40:43]
	v_mfma_f32_16x16x32_bf16 v[28:31], v[144:147], v[200:203], v[28:31]
	v_mfma_f32_16x16x32_bf16 v[24:27], v[160:163], v[200:203], v[24:27]
	v_mfma_f32_16x16x32_bf16 v[12:15], v[144:147], v[208:211], v[12:15]
	v_mfma_f32_16x16x32_bf16 v[8:11], v[160:163], v[208:211], v[8:11]
	v_mfma_f32_16x16x32_bf16 v[60:63], v[152:155], v[188:191], v[60:63]
	v_mfma_f32_16x16x32_bf16 v[56:59], v[164:167], v[188:191], v[56:59]
	v_mfma_f32_16x16x32_bf16 v[44:47], v[152:155], v[196:199], v[44:47]
	v_mfma_f32_16x16x32_bf16 v[40:43], v[164:167], v[196:199], v[40:43]
	v_mfma_f32_16x16x32_bf16 v[28:31], v[152:155], v[204:207], v[28:31]
	v_mfma_f32_16x16x32_bf16 v[24:27], v[164:167], v[204:207], v[24:27]
	v_mfma_f32_16x16x32_bf16 v[12:15], v[152:155], v[212:215], v[12:15]
	v_mfma_f32_16x16x32_bf16 v[8:11], v[164:167], v[212:215], v[8:11]
	s_setprio 0
	s_setprio 1
	v_mfma_f32_16x16x32_bf16 v[52:55], v[168:171], v[184:187], v[52:55]
	v_mfma_f32_16x16x32_bf16 v[48:51], v[176:179], v[184:187], v[48:51]
	v_mfma_f32_16x16x32_bf16 v[36:39], v[168:171], v[192:195], v[36:39]
	v_mfma_f32_16x16x32_bf16 v[32:35], v[176:179], v[192:195], v[32:35]
	v_mfma_f32_16x16x32_bf16 v[20:23], v[168:171], v[200:203], v[20:23]
	v_mfma_f32_16x16x32_bf16 v[16:19], v[176:179], v[200:203], v[16:19]
	v_mfma_f32_16x16x32_bf16 v[4:7], v[168:171], v[208:211], v[4:7]
	v_mfma_f32_16x16x32_bf16 v[0:3], v[176:179], v[208:211], v[0:3]
	v_mfma_f32_16x16x32_bf16 v[52:55], v[172:175], v[188:191], v[52:55]
	v_mfma_f32_16x16x32_bf16 v[48:51], v[180:183], v[188:191], v[48:51]
	v_mfma_f32_16x16x32_bf16 v[36:39], v[172:175], v[196:199], v[36:39]
	v_mfma_f32_16x16x32_bf16 v[32:35], v[180:183], v[196:199], v[32:35]
	v_mfma_f32_16x16x32_bf16 v[20:23], v[172:175], v[204:207], v[20:23]
	v_mfma_f32_16x16x32_bf16 v[16:19], v[180:183], v[204:207], v[16:19]
	v_mfma_f32_16x16x32_bf16 v[4:7], v[172:175], v[212:215], v[4:7]
	v_mfma_f32_16x16x32_bf16 v[0:3], v[180:183], v[212:215], v[0:3]
	s_setprio 0
	s_barrier
	s_add_i32 s69, s69, 2
	s_add_u32 s30, s30, 0x100
	s_addc_u32 s31, s31, 0
	s_add_u32 s63, s63, 0x100
	s_addc_u32 s68, s68, 0
	s_cmp_gt_u32 s69, 5
	s_cbranch_scc0 .LBB0_1319
	s_nop 0
	s_nop 0
	s_nop 0
	s_nop 0
	s_nop 0
	s_nop 0
	s_nop 0
	s_nop 0
	s_nop 0
	s_and_b64 vcc, exec, s[6:7]
	s_cbranch_vccz .LBB0_1322
	s_barrier

; #define PG8_STAGE(bufoff, gbase, voff) do { _Pragma("unroll") for (int _i = 0; _i < 2; ++_i) \
;         __builtin_amdgcn_global_load_lds((const unsigned*)((const char*)(gbase) + (voff)[_i]), (PG8_LAS unsigned*)(lds + (bufoff) + ldsw + _i * 8192), 16, 0, 0); } while (0)
; #define PG8_LDA(dst, b, h) do { _Pragma("unroll") for (int m = 0; m < 4; ++m) _Pragma("unroll") for (int k = 0; k < 2; ++k) dst[m][k] = *(const PG8_LAS bf16x8*)(lds + PG8_SA(b, h) + aoff + m * 2048 + k * 1024); } while (0)
; #define PG8_LDB(dst, b, h) do { _Pragma("unroll") for (int n = 0; n < 2; ++n) _Pragma("unroll") for (int k = 0; k < 2; ++k) dst[n][k] = *(const PG8_LAS bf16x8*)(lds + PG8_SB(b, h) + boff + n * 2048 + k * 1024); } while (0)
; #define PG8_MMA(ai, bj, At, Bt) do { __builtin_amdgcn_s_setprio(1); _Pragma("unroll") for (int m = 0; m < 4; ++m) _Pragma("unroll") for (int n = 0; n < 2; ++n) _Pragma("unroll") for (int k = 0; k < 2; ++k) \
;         acc[ai][bj][m][n] = __builtin_amdgcn_mfma_f32_16x16x32_bf16(Bt[n][k], At[m][k], acc[ai][bj][m][n], 0, 0, 0); __builtin_amdgcn_s_setprio(0); } while (0)
; #define PG8_WAIT_V(n) asm volatile("s_waitcnt vmcnt(" #n ")" ::: "memory")
; #define PG8_WAIT_L(n) asm volatile("s_waitcnt lgkmcnt(" #n ")" ::: "memory")
; #define PG8_BAR __builtin_amdgcn_s_barrier()
; #define PG8_SCHED __builtin_amdgcn_sched_barrier(0)
; template <class Epi, class Sched, bool ALIGN_EPI = false, bool SP2 = false>
; __device__ __forceinline__ void gemm_phase(PG8_LAS unsigned char* lds, const Gemm g, const Sched& S, const Epi& E) {
;     ...
;             PG8_LDB(B0, 0, 0); PG8_LDB(B1, 0, 1); PG8_SCHED; PG8_LDA(At, 0, 0); PG8_STAGE(PG8_SA(1, 1), a1 + hstep, voffA);
;             PG8_WAIT_V(8); PG8_WAIT_L(0); PG8_BAR; PG8_MMA(0, 0, At, B0); PG8_MMA(0, 1, At, B1); PG8_BAR; PG8_SCHED;
;             PG8_LDA(At, 0, 1); PG8_STAGE(PG8_SB(0, 0), b2, voffB); PG8_STAGE(PG8_SB(0, 1), b2 + hstep, voffB); PG8_STAGE(PG8_SA(0, 0), a2, voffA);
;             PG8_WAIT_V(8); PG8_WAIT_L(0); PG8_BAR; PG8_MMA(1, 0, At, B0); PG8_MMA(1, 1, At, B1); PG8_BAR; PG8_SCHED;
.LBB0_1400:
	s_add_u32 s26, s24, 0xfffc0080
	s_addc_u32 s27, s25, -1
	s_cmp_eq_u32 s60, 12
	s_cselect_b32 s29, s15, s27
	s_cselect_b32 s28, s21, s26
	s_cselect_b32 s27, s13, s59
	s_cselect_b32 s26, s57, s58
	v_lshl_add_u64 v[214:215], s[24:25], 0, v[132:133]
	s_add_i32 m0, s23, 0xc000
	ds_read_b128 v[140:143], v147
	global_load_lds_dwordx4 v[214:215], off
	v_lshl_add_u64 v[214:215], s[24:25], 0, v[134:135]
	s_add_i32 m0, s23, 0xe000
	ds_read_b128 v[154:157], v147 offset:1024
	global_load_lds_dwordx4 v[214:215], off
	ds_read_b128 v[158:161], v147 offset:2048
	ds_read_b128 v[162:165], v147 offset:3072
	ds_read_b128 v[166:169], v149
	ds_read_b128 v[170:173], v149 offset:1024
	ds_read_b128 v[174:177], v149 offset:2048
	ds_read_b128 v[178:181], v149 offset:3072
	ds_read_b128 v[182:185], v151
	ds_read_b128 v[186:189], v151 offset:1024
	ds_read_b128 v[190:193], v151 offset:2048
	ds_read_b128 v[194:197], v151 offset:3072
	ds_read_b128 v[198:201], v151 offset:4096
	ds_read_b128 v[202:205], v151 offset:5120
	ds_read_b128 v[206:209], v151 offset:6144
	ds_read_b128 v[210:213], v151 offset:7168
	s_waitcnt vmcnt(8)
	s_waitcnt lgkmcnt(0)
	s_barrier
	s_setprio 1
	s_waitcnt lgkmcnt(0)
	v_mfma_f32_16x16x32_bf16 v[124:127], v[140:143], v[182:185], v[124:127]
	v_mfma_f32_16x16x32_bf16 v[120:123], v[158:161], v[182:185], v[120:123]
	v_mfma_f32_16x16x32_bf16 v[108:111], v[140:143], v[190:193], v[108:111]
	v_mfma_f32_16x16x32_bf16 v[104:107], v[158:161], v[190:193], v[104:107]
	v_mfma_f32_16x16x32_bf16 v[92:95], v[140:143], v[198:201], v[92:95]
	v_mfma_f32_16x16x32_bf16 v[88:91], v[158:161], v[198:201], v[88:91]
	v_mfma_f32_16x16x32_bf16 v[76:79], v[140:143], v[206:209], v[76:79]
	v_mfma_f32_16x16x32_bf16 v[72:75], v[158:161], v[206:209], v[72:75]
	v_mfma_f32_16x16x32_bf16 v[124:127], v[154:157], v[186:189], v[124:127]
	v_mfma_f32_16x16x32_bf16 v[120:123], v[162:165], v[186:189], v[120:123]
	v_mfma_f32_16x16x32_bf16 v[108:111], v[154:157], v[194:197], v[108:111]
	v_mfma_f32_16x16x32_bf16 v[104:107], v[162:165], v[194:197], v[104:107]
	v_mfma_f32_16x16x32_bf16 v[92:95], v[154:157], v[202:205], v[92:95]
	v_mfma_f32_16x16x32_bf16 v[88:91], v[162:165], v[202:205], v[88:91]
	v_mfma_f32_16x16x32_bf16 v[76:79], v[154:157], v[210:213], v[76:79]
	v_mfma_f32_16x16x32_bf16 v[72:75], v[162:165], v[210:213], v[72:75]
	s_setprio 0
	s_setprio 1
	v_mfma_f32_16x16x32_bf16 v[116:119], v[166:169], v[182:185], v[116:119]
	v_mfma_f32_16x16x32_bf16 v[112:115], v[174:177], v[182:185], v[112:115]
	v_mfma_f32_16x16x32_bf16 v[100:103], v[166:169], v[190:193], v[100:103]
	v_mfma_f32_16x16x32_bf16 v[96:99], v[174:177], v[190:193], v[96:99]
	v_mfma_f32_16x16x32_bf16 v[84:87], v[166:169], v[198:201], v[84:87]
	v_mfma_f32_16x16x32_bf16 v[80:83], v[174:177], v[198:201], v[80:83]
	v_mfma_f32_16x16x32_bf16 v[68:71], v[166:169], v[206:209], v[68:71]
	v_mfma_f32_16x16x32_bf16 v[64:67], v[174:177], v[206:209], v[64:67]
	v_mfma_f32_16x16x32_bf16 v[116:119], v[170:173], v[186:189], v[116:119]
	v_mfma_f32_16x16x32_bf16 v[112:115], v[178:181], v[186:189], v[112:115]
	v_mfma_f32_16x16x32_bf16 v[100:103], v[170:173], v[194:197], v[100:103]
	v_mfma_f32_16x16x32_bf16 v[96:99], v[178:181], v[194:197], v[96:99]
	v_mfma_f32_16x16x32_bf16 v[84:87], v[170:173], v[202:205], v[84:87]
	v_mfma_f32_16x16x32_bf16 v[80:83], v[178:181], v[202:205], v[80:83]
	v_mfma_f32_16x16x32_bf16 v[68:71], v[170:173], v[210:213], v[68:71]
	v_mfma_f32_16x16x32_bf16 v[64:67], v[178:181], v[210:213], v[64:67]
	s_setprio 0
	s_barrier
	s_add_i32 s61, s42, s30
	v_lshl_add_u64 v[214:215], s[26:27], 0, v[128:129]
	s_mov_b32 m0, s61
	v_lshl_add_u64 v[216:217], s[26:27], 0, v[130:131]
	global_load_lds_dwordx4 v[214:215], off
	s_add_i32 m0, s61, 0x2000
	s_add_u32 s62, s26, 0x40000
	s_addc_u32 s63, s27, 0
	s_add_i32 s61, s43, s30
	global_load_lds_dwordx4 v[216:217], off
	v_lshl_add_u64 v[218:219], s[62:63], 0, v[128:129]
	s_mov_b32 m0, s61
	v_lshl_add_u64 v[220:221], s[28:29], 0, v[130:131]
	global_load_lds_dwordx4 v[218:219], off
	v_lshl_add_u64 v[218:219], s[62:63], 0, v[130:131]
	s_add_i32 m0, s61, 0x2000
	ds_read_b128 v[182:185], v151 offset:16384
	global_load_lds_dwordx4 v[218:219], off
	v_lshl_add_u64 v[218:219], s[28:29], 0, v[128:129]
	s_mov_b32 m0, s23
	ds_read_b128 v[186:189], v151 offset:17408
	global_load_lds_dwordx4 v[218:219], off
	s_mov_b32 m0, s31
	ds_read_b128 v[190:193], v151 offset:18432
	global_load_lds_dwordx4 v[220:221], off
	ds_read_b128 v[194:197], v151 offset:19456
	ds_read_b128 v[198:201], v151 offset:20480
	ds_read_b128 v[202:205], v151 offset:21504
	ds_read_b128 v[206:209], v151 offset:22528
	ds_read_b128 v[210:213], v151 offset:23552
	s_waitcnt vmcnt(8)
	s_waitcnt lgkmcnt(0)
	s_barrier
; #define PG8_STAGE(bufoff, gbase, voff) do { _Pragma("unroll") for (int _i = 0; _i < 2; ++_i) \
;         __builtin_amdgcn_global_load_lds((const unsigned*)((const char*)(gbase) + (voff)[_i]), (PG8_LAS unsigned*)(lds + (bufoff) + ldsw + _i * 8192), 16, 0, 0); } while (0)
; #define PG8_LDA(dst, b, h) do { _Pragma("unroll") for (int m = 0; m < 4; ++m) _Pragma("unroll") for (int k = 0; k < 2; ++k) dst[m][k] = *(const PG8_LAS bf16x8*)(lds + PG8_SA(b, h) + aoff + m * 2048 + k * 1024); } while (0)
; #define PG8_LDB(dst, b, h) do { _Pragma("unroll") for (int n = 0; n < 2; ++n) _Pragma("unroll") for (int k = 0; k < 2; ++k) dst[n][k] = *(const PG8_LAS bf16x8*)(lds + PG8_SB(b, h) + boff + n * 2048 + k * 1024); } while (0)
; #define PG8_MMA(ai, bj, At, Bt) do { __builtin_amdgcn_s_setprio(1); _Pragma("unroll") for (int m = 0; m < 4; ++m) _Pragma("unroll") for (int n = 0; n < 2; ++n) _Pragma("unroll") for (int k = 0; k < 2; ++k) \
;         acc[ai][bj][m][n] = __builtin_amdgcn_mfma_f32_16x16x32_bf16(Bt[n][k], At[m][k], acc[ai][bj][m][n], 0, 0, 0); __builtin_amdgcn_s_setprio(0); } while (0)
; #define PG8_WAIT_V(n) asm volatile("s_waitcnt vmcnt(" #n ")" ::: "memory")
; #define PG8_WAIT_L(n) asm volatile("s_waitcnt lgkmcnt(" #n ")" ::: "memory")
; #define PG8_BAR __builtin_amdgcn_s_barrier()
; #define PG8_SCHED __builtin_amdgcn_sched_barrier(0)
; template <class Epi, class Sched, bool ALIGN_EPI = false, bool SP2 = false>
; __device__ __forceinline__ void gemm_phase(PG8_LAS unsigned char* lds, const Gemm g, const Sched& S, const Epi& E) {
;     ...
;             PG8_WAIT_V(8); PG8_WAIT_L(0); PG8_BAR; PG8_MMA(1, 0, At, B0); PG8_MMA(1, 1, At, B1); PG8_BAR; PG8_SCHED;
;             PG8_LDB(B0, 1, 0); PG8_LDB(B1, 1, 1); PG8_SCHED; PG8_LDA(At, 1, 0); PG8_STAGE(PG8_SA(0, 1), a2 + hstep, voffA);
;             PG8_WAIT_V(8); PG8_WAIT_L(0); PG8_BAR; PG8_MMA(0, 0, At, B0); PG8_MMA(0, 1, At, B1); PG8_BAR; PG8_SCHED;
	s_setprio 1
	s_waitcnt lgkmcnt(0)
	v_mfma_f32_16x16x32_bf16 v[60:63], v[140:143], v[182:185], v[60:63]
	v_mfma_f32_16x16x32_bf16 v[56:59], v[158:161], v[182:185], v[56:59]
	v_mfma_f32_16x16x32_bf16 v[44:47], v[140:143], v[190:193], v[44:47]
	v_mfma_f32_16x16x32_bf16 v[40:43], v[158:161], v[190:193], v[40:43]
	v_mfma_f32_16x16x32_bf16 v[28:31], v[140:143], v[198:201], v[28:31]
	v_mfma_f32_16x16x32_bf16 v[24:27], v[158:161], v[198:201], v[24:27]
	v_mfma_f32_16x16x32_bf16 v[12:15], v[140:143], v[206:209], v[12:15]
	v_mfma_f32_16x16x32_bf16 v[8:11], v[158:161], v[206:209], v[8:11]
	v_mfma_f32_16x16x32_bf16 v[60:63], v[154:157], v[186:189], v[60:63]
	v_mfma_f32_16x16x32_bf16 v[56:59], v[162:165], v[186:189], v[56:59]
	v_mfma_f32_16x16x32_bf16 v[44:47], v[154:157], v[194:197], v[44:47]
	v_mfma_f32_16x16x32_bf16 v[40:43], v[162:165], v[194:197], v[40:43]
	v_mfma_f32_16x16x32_bf16 v[28:31], v[154:157], v[202:205], v[28:31]
	v_mfma_f32_16x16x32_bf16 v[24:27], v[162:165], v[202:205], v[24:27]
	v_mfma_f32_16x16x32_bf16 v[12:15], v[154:157], v[210:213], v[12:15]
	v_mfma_f32_16x16x32_bf16 v[8:11], v[162:165], v[210:213], v[8:11]
	s_setprio 0
	s_setprio 1
	v_mfma_f32_16x16x32_bf16 v[52:55], v[166:169], v[182:185], v[52:55]
	v_mfma_f32_16x16x32_bf16 v[48:51], v[174:177], v[182:185], v[48:51]
	v_mfma_f32_16x16x32_bf16 v[36:39], v[166:169], v[190:193], v[36:39]
	v_mfma_f32_16x16x32_bf16 v[32:35], v[174:177], v[190:193], v[32:35]
	v_mfma_f32_16x16x32_bf16 v[20:23], v[166:169], v[198:201], v[20:23]
	v_mfma_f32_16x16x32_bf16 v[16:19], v[174:177], v[198:201], v[16:19]
	v_mfma_f32_16x16x32_bf16 v[4:7], v[166:169], v[206:209], v[4:7]
	v_mfma_f32_16x16x32_bf16 v[0:3], v[174:177], v[206:209], v[0:3]
	v_mfma_f32_16x16x32_bf16 v[52:55], v[170:173], v[186:189], v[52:55]
	v_mfma_f32_16x16x32_bf16 v[48:51], v[178:181], v[186:189], v[48:51]
	v_mfma_f32_16x16x32_bf16 v[36:39], v[170:173], v[194:197], v[36:39]
	v_mfma_f32_16x16x32_bf16 v[32:35], v[178:181], v[194:197], v[32:35]
	v_mfma_f32_16x16x32_bf16 v[20:23], v[170:173], v[202:205], v[20:23]
	v_mfma_f32_16x16x32_bf16 v[16:19], v[178:181], v[202:205], v[16:19]
	v_mfma_f32_16x16x32_bf16 v[4:7], v[170:173], v[210:213], v[4:7]
	v_mfma_f32_16x16x32_bf16 v[0:3], v[178:181], v[210:213], v[0:3]
	s_setprio 0
	s_barrier
	s_add_i32 s61, 0, 0x18000
	s_add_i32 s62, 0, 0x1c000
	s_add_u32 s28, s28, 0x40000
	s_addc_u32 s29, s29, 0
	s_mov_b32 m0, s34
	v_lshl_add_u64 v[222:223], s[28:29], 0, v[128:129]
	global_load_lds_dwordx4 v[222:223], off
	v_lshl_add_u64 v[222:223], s[28:29], 0, v[130:131]
	s_mov_b32 m0, s35
	v_add_u32_e32 v153, s61, v145
	global_load_lds_dwordx4 v[222:223], off
	ds_read_b128 v[140:143], v153
	ds_read_b128 v[154:157], v153 offset:1024
	ds_read_b128 v[158:161], v153 offset:2048
	ds_read_b128 v[162:165], v153 offset:3072
	v_add_u32_e32 v153, s62, v145
	ds_read_b128 v[166:169], v153
	ds_read_b128 v[170:173], v153 offset:1024
	ds_read_b128 v[174:177], v153 offset:2048
	ds_read_b128 v[178:181], v153 offset:3072
	ds_read_b128 v[182:185], v151 offset:32768
	ds_read_b128 v[186:189], v151 offset:33792
	ds_read_b128 v[190:193], v151 offset:34816
	ds_read_b128 v[194:197], v151 offset:35840
	ds_read_b128 v[198:201], v151 offset:36864
	ds_read_b128 v[202:205], v151 offset:37888
	ds_read_b128 v[206:209], v151 offset:38912
	ds_read_b128 v[210:213], v151 offset:39936
	s_waitcnt vmcnt(8)
	s_waitcnt lgkmcnt(0)
	s_barrier
	s_setprio 1
	s_waitcnt lgkmcnt(0)
	v_mfma_f32_16x16x32_bf16 v[124:127], v[140:143], v[182:185], v[124:127]
	v_mfma_f32_16x16x32_bf16 v[120:123], v[158:161], v[182:185], v[120:123]
	v_mfma_f32_16x16x32_bf16 v[108:111], v[140:143], v[190:193], v[108:111]
	v_mfma_f32_16x16x32_bf16 v[104:107], v[158:161], v[190:193], v[104:107]
	v_mfma_f32_16x16x32_bf16 v[92:95], v[140:143], v[198:201], v[92:95]
	v_mfma_f32_16x16x32_bf16 v[88:91], v[158:161], v[198:201], v[88:91]
	v_mfma_f32_16x16x32_bf16 v[76:79], v[140:143], v[206:209], v[76:79]
	v_mfma_f32_16x16x32_bf16 v[72:75], v[158:161], v[206:209], v[72:75]
	v_mfma_f32_16x16x32_bf16 v[124:127], v[154:157], v[186:189], v[124:127]
	v_mfma_f32_16x16x32_bf16 v[120:123], v[162:165], v[186:189], v[120:123]
	v_mfma_f32_16x16x32_bf16 v[108:111], v[154:157], v[194:197], v[108:111]
	v_mfma_f32_16x16x32_bf16 v[104:107], v[162:165], v[194:197], v[104:107]
	v_mfma_f32_16x16x32_bf16 v[92:95], v[154:157], v[202:205], v[92:95]
	v_mfma_f32_16x16x32_bf16 v[88:91], v[162:165], v[202:205], v[88:91]
	v_mfma_f32_16x16x32_bf16 v[76:79], v[154:157], v[210:213], v[76:79]
	v_mfma_f32_16x16x32_bf16 v[72:75], v[162:165], v[210:213], v[72:75]
	s_setprio 0
	s_setprio 1
	v_mfma_f32_16x16x32_bf16 v[116:119], v[166:169], v[182:185], v[116:119]
	v_mfma_f32_16x16x32_bf16 v[112:115], v[174:177], v[182:185], v[112:115]
	v_mfma_f32_16x16x32_bf16 v[100:103], v[166:169], v[190:193], v[100:103]
	v_mfma_f32_16x16x32_bf16 v[96:99], v[174:177], v[190:193], v[96:99]
	v_mfma_f32_16x16x32_bf16 v[84:87], v[166:169], v[198:201], v[84:87]
	v_mfma_f32_16x16x32_bf16 v[80:83], v[174:177], v[198:201], v[80:83]
	v_mfma_f32_16x16x32_bf16 v[68:71], v[166:169], v[206:209], v[68:71]
	v_mfma_f32_16x16x32_bf16 v[64:67], v[174:177], v[206:209], v[64:67]
	v_mfma_f32_16x16x32_bf16 v[116:119], v[170:173], v[186:189], v[116:119]
	v_mfma_f32_16x16x32_bf16 v[112:115], v[178:181], v[186:189], v[112:115]
	v_mfma_f32_16x16x32_bf16 v[100:103], v[170:173], v[194:197], v[100:103]
	v_mfma_f32_16x16x32_bf16 v[96:99], v[178:181], v[194:197], v[96:99]
	v_mfma_f32_16x16x32_bf16 v[84:87], v[170:173], v[202:205], v[84:87]
	v_mfma_f32_16x16x32_bf16 v[80:83], v[178:181], v[202:205], v[80:83]
	v_mfma_f32_16x16x32_bf16 v[68:71], v[170:173], v[210:213], v[68:71]
	v_mfma_f32_16x16x32_bf16 v[64:67], v[178:181], v[210:213], v[64:67]
	s_setprio 0
	s_barrier
; #define PG8_STAGE(bufoff, gbase, voff) do { _Pragma("unroll") for (int _i = 0; _i < 2; ++_i) \
;         __builtin_amdgcn_global_load_lds((const unsigned*)((const char*)(gbase) + (voff)[_i]), (PG8_LAS unsigned*)(lds + (bufoff) + ldsw + _i * 8192), 16, 0, 0); } while (0)
; #define PG8_LDA(dst, b, h) do { _Pragma("unroll") for (int m = 0; m < 4; ++m) _Pragma("unroll") for (int k = 0; k < 2; ++k) dst[m][k] = *(const PG8_LAS bf16x8*)(lds + PG8_SA(b, h) + aoff + m * 2048 + k * 1024); } while (0)
; #define PG8_MMA(ai, bj, At, Bt) do { __builtin_amdgcn_s_setprio(1); _Pragma("unroll") for (int m = 0; m < 4; ++m) _Pragma("unroll") for (int n = 0; n < 2; ++n) _Pragma("unroll") for (int k = 0; k < 2; ++k) \
;         acc[ai][bj][m][n] = __builtin_amdgcn_mfma_f32_16x16x32_bf16(Bt[n][k], At[m][k], acc[ai][bj][m][n], 0, 0, 0); __builtin_amdgcn_s_setprio(0); } while (0)
; #define PG8_WAIT_V(n) asm volatile("s_waitcnt vmcnt(" #n ")" ::: "memory")
; #define PG8_WAIT_L(n) asm volatile("s_waitcnt lgkmcnt(" #n ")" ::: "memory")
; #define PG8_BAR __builtin_amdgcn_s_barrier()
; #define PG8_SCHED __builtin_amdgcn_sched_barrier(0)
; template <class Epi, class Sched, bool ALIGN_EPI = false, bool SP2 = false>
; __device__ __forceinline__ void gemm_phase(PG8_LAS unsigned char* lds, const Gemm g, const Sched& S, const Epi& E) {
;     ...
;             PG8_LDA(At, 1, 1); PG8_STAGE(PG8_SB(1, 0), b3, voffB); PG8_STAGE(PG8_SB(1, 1), b3 + hstep, voffB); PG8_STAGE(PG8_SA(1, 0), a3, voffA);
;             PG8_WAIT_V(8); PG8_WAIT_L(0); PG8_BAR; PG8_MMA(1, 0, At, B0); PG8_MMA(1, 1, At, B1); PG8_BAR; PG8_SCHED;
	s_add_i32 s28, s61, s30
	v_lshl_add_u64 v[214:215], v[214:215], 0, s[8:9]
	s_mov_b32 m0, s28
	ds_read_b128 v[182:185], v151 offset:49152
	global_load_lds_dwordx4 v[214:215], off
	s_add_i32 m0, s28, 0x2000
	s_add_u32 s26, s26, 0x40080
	v_lshl_add_u64 v[214:215], v[216:217], 0, s[8:9]
	s_addc_u32 s27, s27, 0
	s_add_i32 s28, s62, s30
	global_load_lds_dwordx4 v[214:215], off
	v_lshl_add_u64 v[214:215], s[26:27], 0, v[128:129]
	s_mov_b32 m0, s28
	ds_read_b128 v[186:189], v151 offset:50176
	global_load_lds_dwordx4 v[214:215], off
	v_lshl_add_u64 v[214:215], s[26:27], 0, v[130:131]
	s_add_i32 m0, s28, 0x2000
	ds_read_b128 v[190:193], v151 offset:51200
	global_load_lds_dwordx4 v[214:215], off
	v_lshl_add_u64 v[214:215], v[218:219], 0, s[8:9]
	s_mov_b32 m0, s38
	ds_read_b128 v[194:197], v151 offset:52224
	global_load_lds_dwordx4 v[214:215], off
	v_lshl_add_u64 v[214:215], v[220:221], 0, s[8:9]
	s_mov_b32 m0, s39
	ds_read_b128 v[198:201], v151 offset:53248
	global_load_lds_dwordx4 v[214:215], off
	ds_read_b128 v[202:205], v151 offset:54272
	ds_read_b128 v[206:209], v151 offset:55296
	ds_read_b128 v[210:213], v151 offset:56320
	s_waitcnt vmcnt(8)
	s_waitcnt lgkmcnt(0)
	s_barrier
	s_setprio 1
	s_waitcnt lgkmcnt(0)
	v_mfma_f32_16x16x32_bf16 v[60:63], v[140:143], v[182:185], v[60:63]
	v_mfma_f32_16x16x32_bf16 v[56:59], v[158:161], v[182:185], v[56:59]
	v_mfma_f32_16x16x32_bf16 v[44:47], v[140:143], v[190:193], v[44:47]
	v_mfma_f32_16x16x32_bf16 v[40:43], v[158:161], v[190:193], v[40:43]
	v_mfma_f32_16x16x32_bf16 v[28:31], v[140:143], v[198:201], v[28:31]
	v_mfma_f32_16x16x32_bf16 v[24:27], v[158:161], v[198:201], v[24:27]
	v_mfma_f32_16x16x32_bf16 v[12:15], v[140:143], v[206:209], v[12:15]
	v_mfma_f32_16x16x32_bf16 v[8:11], v[158:161], v[206:209], v[8:11]
	v_mfma_f32_16x16x32_bf16 v[60:63], v[154:157], v[186:189], v[60:63]
	v_mfma_f32_16x16x32_bf16 v[56:59], v[162:165], v[186:189], v[56:59]
	v_mfma_f32_16x16x32_bf16 v[44:47], v[154:157], v[194:197], v[44:47]
	v_mfma_f32_16x16x32_bf16 v[40:43], v[162:165], v[194:197], v[40:43]
	v_mfma_f32_16x16x32_bf16 v[28:31], v[154:157], v[202:205], v[28:31]
	v_mfma_f32_16x16x32_bf16 v[24:27], v[162:165], v[202:205], v[24:27]
	v_mfma_f32_16x16x32_bf16 v[12:15], v[154:157], v[210:213], v[12:15]
	v_mfma_f32_16x16x32_bf16 v[8:11], v[162:165], v[210:213], v[8:11]
	s_setprio 0
	s_setprio 1
	v_mfma_f32_16x16x32_bf16 v[52:55], v[166:169], v[182:185], v[52:55]
	v_mfma_f32_16x16x32_bf16 v[48:51], v[174:177], v[182:185], v[48:51]
	v_mfma_f32_16x16x32_bf16 v[36:39], v[166:169], v[190:193], v[36:39]
	v_mfma_f32_16x16x32_bf16 v[32:35], v[174:177], v[190:193], v[32:35]
	v_mfma_f32_16x16x32_bf16 v[20:23], v[166:169], v[198:201], v[20:23]
	v_mfma_f32_16x16x32_bf16 v[16:19], v[174:177], v[198:201], v[16:19]
	v_mfma_f32_16x16x32_bf16 v[4:7], v[166:169], v[206:209], v[4:7]
	v_mfma_f32_16x16x32_bf16 v[0:3], v[174:177], v[206:209], v[0:3]
	v_mfma_f32_16x16x32_bf16 v[52:55], v[170:173], v[186:189], v[52:55]
	v_mfma_f32_16x16x32_bf16 v[48:51], v[178:181], v[186:189], v[48:51]
	v_mfma_f32_16x16x32_bf16 v[36:39], v[170:173], v[194:197], v[36:39]
	v_mfma_f32_16x16x32_bf16 v[32:35], v[178:181], v[194:197], v[32:35]
	v_mfma_f32_16x16x32_bf16 v[20:23], v[170:173], v[202:205], v[20:23]
	v_mfma_f32_16x16x32_bf16 v[16:19], v[178:181], v[202:205], v[16:19]
	v_mfma_f32_16x16x32_bf16 v[4:7], v[170:173], v[210:213], v[4:7]
	v_mfma_f32_16x16x32_bf16 v[0:3], v[178:181], v[210:213], v[0:3]
	s_setprio 0
	s_barrier
	s_add_i32 s60, s60, 2
	s_add_u32 s24, s24, 0x100
	s_addc_u32 s25, s25, 0
	s_add_u32 s58, s58, 0x100
	s_addc_u32 s59, s59, 0
	s_cmp_gt_u32 s60, 13
	s_cbranch_scc0 .LBB0_1400
	s_nop 0
	s_nop 0
	s_nop 0
	s_nop 0
	s_nop 0
	s_nop 0
	s_nop 0
	s_nop 0
	s_nop 0
	s_and_b64 vcc, exec, s[10:11]
	s_cbranch_vccz .LBB0_1403
	s_barrier

; #define PG8_STAGE(bufoff, gbase, voff) do { _Pragma("unroll") for (int _i = 0; _i < 2; ++_i) \
;         __builtin_amdgcn_global_load_lds((const unsigned*)((const char*)(gbase) + (voff)[_i]), (PG8_LAS unsigned*)(lds + (bufoff) + ldsw + _i * 8192), 16, 0, 0); } while (0)
; #define PG8_LDA(dst, b, h) do { _Pragma("unroll") for (int m = 0; m < 4; ++m) _Pragma("unroll") for (int k = 0; k < 2; ++k) dst[m][k] = *(const PG8_LAS bf16x8*)(lds + PG8_SA(b, h) + aoff + m * 2048 + k * 1024); } while (0)
; #define PG8_LDB(dst, b, h) do { _Pragma("unroll") for (int n = 0; n < 2; ++n) _Pragma("unroll") for (int k = 0; k < 2; ++k) dst[n][k] = *(const PG8_LAS bf16x8*)(lds + PG8_SB(b, h) + boff + n * 2048 + k * 1024); } while (0)
; #define PG8_MMA(ai, bj, At, Bt) do { __builtin_amdgcn_s_setprio(1); _Pragma("unroll") for (int m = 0; m < 4; ++m) _Pragma("unroll") for (int n = 0; n < 2; ++n) _Pragma("unroll") for (int k = 0; k < 2; ++k) \
;         acc[ai][bj][m][n] = __builtin_amdgcn_mfma_f32_16x16x32_bf16(Bt[n][k], At[m][k], acc[ai][bj][m][n], 0, 0, 0); __builtin_amdgcn_s_setprio(0); } while (0)
; #define PG8_WAIT_V(n) asm volatile("s_waitcnt vmcnt(" #n ")" ::: "memory")
; #define PG8_WAIT_L(n) asm volatile("s_waitcnt lgkmcnt(" #n ")" ::: "memory")
; #define PG8_BAR __builtin_amdgcn_s_barrier()
; #define PG8_SCHED __builtin_amdgcn_sched_barrier(0)
; template <class Epi, class Sched, bool ALIGN_EPI = false, bool SP2 = false>
; __device__ __forceinline__ void gemm_phase(PG8_LAS unsigned char* lds, const Gemm g, const Sched& S, const Epi& E) {
;     ...
;             PG8_LDB(B0, 0, 0); PG8_LDB(B1, 0, 1); PG8_SCHED; PG8_LDA(At, 0, 0); PG8_STAGE(PG8_SA(1, 1), a1 + hstep, voffA);
;             PG8_WAIT_V(8); PG8_WAIT_L(0); PG8_BAR; PG8_MMA(0, 0, At, B0); PG8_MMA(0, 1, At, B1); PG8_BAR; PG8_SCHED;
;             PG8_LDA(At, 0, 1); PG8_STAGE(PG8_SB(0, 0), b2, voffB); PG8_STAGE(PG8_SB(0, 1), b2 + hstep, voffB); PG8_STAGE(PG8_SA(0, 0), a2, voffA);
;             PG8_WAIT_V(8); PG8_WAIT_L(0); PG8_BAR; PG8_MMA(1, 0, At, B0); PG8_MMA(1, 1, At, B1); PG8_BAR; PG8_SCHED;
.LBB0_1487:
	s_add_u32 s6, s4, 0xfffc0080
	s_addc_u32 s7, s5, -1
	s_cmp_eq_u32 s51, 12
	s_cselect_b32 s9, s10, s7
	s_cselect_b32 s8, s11, s6
	s_cselect_b32 s7, s21, s50
	s_cselect_b32 s6, s23, s45
	v_lshl_add_u64 v[152:153], s[4:5], 0, v[136:137]
	s_add_i32 m0, s31, 0xc000
	ds_read_b128 v[144:147], v155
	global_load_lds_dwordx4 v[152:153], off
	v_lshl_add_u64 v[152:153], s[4:5], 0, v[138:139]
	s_add_i32 m0, s31, 0xe000
	ds_read_b128 v[160:163], v155 offset:1024
	global_load_lds_dwordx4 v[152:153], off
	ds_read_b128 v[164:167], v155 offset:2048
	ds_read_b128 v[168:171], v155 offset:3072
	ds_read_b128 v[172:175], v156
	ds_read_b128 v[176:179], v156 offset:1024
	ds_read_b128 v[180:183], v156 offset:2048
	ds_read_b128 v[184:187], v156 offset:3072
	ds_read_b128 v[188:191], v157
	ds_read_b128 v[192:195], v157 offset:1024
	ds_read_b128 v[196:199], v157 offset:2048
	ds_read_b128 v[200:203], v157 offset:3072
	ds_read_b128 v[204:207], v157 offset:4096
	ds_read_b128 v[208:211], v157 offset:5120
	ds_read_b128 v[212:215], v157 offset:6144
	ds_read_b128 v[216:219], v157 offset:7168
	s_waitcnt vmcnt(8)
	s_waitcnt lgkmcnt(0)
	s_barrier
	s_setprio 1
	s_waitcnt lgkmcnt(0)
	v_mfma_f32_16x16x32_bf16 v[124:127], v[144:147], v[188:191], v[124:127]
	v_mfma_f32_16x16x32_bf16 v[116:119], v[164:167], v[188:191], v[116:119]
	v_mfma_f32_16x16x32_bf16 v[108:111], v[144:147], v[196:199], v[108:111]
	v_mfma_f32_16x16x32_bf16 v[100:103], v[164:167], v[196:199], v[100:103]
	v_mfma_f32_16x16x32_bf16 v[92:95], v[144:147], v[204:207], v[92:95]
	v_mfma_f32_16x16x32_bf16 v[84:87], v[164:167], v[204:207], v[84:87]
	v_mfma_f32_16x16x32_bf16 v[76:79], v[144:147], v[212:215], v[76:79]
	v_mfma_f32_16x16x32_bf16 v[68:71], v[164:167], v[212:215], v[68:71]
	v_mfma_f32_16x16x32_bf16 v[124:127], v[160:163], v[192:195], v[124:127]
	v_mfma_f32_16x16x32_bf16 v[116:119], v[168:171], v[192:195], v[116:119]
	v_mfma_f32_16x16x32_bf16 v[108:111], v[160:163], v[200:203], v[108:111]
	v_mfma_f32_16x16x32_bf16 v[100:103], v[168:171], v[200:203], v[100:103]
	v_mfma_f32_16x16x32_bf16 v[92:95], v[160:163], v[208:211], v[92:95]
	v_mfma_f32_16x16x32_bf16 v[84:87], v[168:171], v[208:211], v[84:87]
	v_mfma_f32_16x16x32_bf16 v[76:79], v[160:163], v[216:219], v[76:79]
	v_mfma_f32_16x16x32_bf16 v[68:71], v[168:171], v[216:219], v[68:71]
	s_setprio 0
	s_setprio 1
	v_mfma_f32_16x16x32_bf16 v[120:123], v[172:175], v[188:191], v[120:123]
	v_mfma_f32_16x16x32_bf16 v[112:115], v[180:183], v[188:191], v[112:115]
	v_mfma_f32_16x16x32_bf16 v[104:107], v[172:175], v[196:199], v[104:107]
	v_mfma_f32_16x16x32_bf16 v[96:99], v[180:183], v[196:199], v[96:99]
	v_mfma_f32_16x16x32_bf16 v[88:91], v[172:175], v[204:207], v[88:91]
	v_mfma_f32_16x16x32_bf16 v[80:83], v[180:183], v[204:207], v[80:83]
	v_mfma_f32_16x16x32_bf16 v[72:75], v[172:175], v[212:215], v[72:75]
	v_mfma_f32_16x16x32_bf16 v[64:67], v[180:183], v[212:215], v[64:67]
	v_mfma_f32_16x16x32_bf16 v[120:123], v[176:179], v[192:195], v[120:123]
	v_mfma_f32_16x16x32_bf16 v[112:115], v[184:187], v[192:195], v[112:115]
	v_mfma_f32_16x16x32_bf16 v[104:107], v[176:179], v[200:203], v[104:107]
	v_mfma_f32_16x16x32_bf16 v[96:99], v[184:187], v[200:203], v[96:99]
	v_mfma_f32_16x16x32_bf16 v[88:91], v[176:179], v[208:211], v[88:91]
	v_mfma_f32_16x16x32_bf16 v[80:83], v[184:187], v[208:211], v[80:83]
	v_mfma_f32_16x16x32_bf16 v[72:75], v[176:179], v[216:219], v[72:75]
	v_mfma_f32_16x16x32_bf16 v[64:67], v[184:187], v[216:219], v[64:67]
	s_setprio 0
	s_barrier
	s_add_i32 s52, s41, s28
	v_lshl_add_u64 v[152:153], s[6:7], 0, v[132:133]
	s_mov_b32 m0, s52
	v_lshl_add_u64 v[220:221], s[6:7], 0, v[128:129]
	global_load_lds_dwordx4 v[152:153], off
	s_add_i32 m0, s52, 0x2000
	s_add_u32 s52, s6, 0x40000
	s_addc_u32 s53, s7, 0
	s_add_i32 s54, s42, s28
	global_load_lds_dwordx4 v[220:221], off
	v_lshl_add_u64 v[222:223], s[52:53], 0, v[132:133]
	s_mov_b32 m0, s54
	v_lshl_add_u64 v[224:225], s[8:9], 0, v[130:131]
	global_load_lds_dwordx4 v[222:223], off
	v_lshl_add_u64 v[222:223], s[52:53], 0, v[128:129]
	s_add_i32 m0, s54, 0x2000
	ds_read_b128 v[188:191], v157 offset:16384
	global_load_lds_dwordx4 v[222:223], off
	v_lshl_add_u64 v[222:223], s[8:9], 0, v[134:135]
	s_mov_b32 m0, s31
	ds_read_b128 v[192:195], v157 offset:17408
	global_load_lds_dwordx4 v[222:223], off
	s_mov_b32 m0, s34
	ds_read_b128 v[196:199], v157 offset:18432
	global_load_lds_dwordx4 v[224:225], off
	ds_read_b128 v[200:203], v157 offset:19456
	ds_read_b128 v[204:207], v157 offset:20480
	ds_read_b128 v[208:211], v157 offset:21504
	ds_read_b128 v[212:215], v157 offset:22528
	ds_read_b128 v[216:219], v157 offset:23552
	s_waitcnt vmcnt(8)
	s_waitcnt lgkmcnt(0)
	s_barrier
; #define PG8_STAGE(bufoff, gbase, voff) do { _Pragma("unroll") for (int _i = 0; _i < 2; ++_i) \
;         __builtin_amdgcn_global_load_lds((const unsigned*)((const char*)(gbase) + (voff)[_i]), (PG8_LAS unsigned*)(lds + (bufoff) + ldsw + _i * 8192), 16, 0, 0); } while (0)
; #define PG8_LDA(dst, b, h) do { _Pragma("unroll") for (int m = 0; m < 4; ++m) _Pragma("unroll") for (int k = 0; k < 2; ++k) dst[m][k] = *(const PG8_LAS bf16x8*)(lds + PG8_SA(b, h) + aoff + m * 2048 + k * 1024); } while (0)
; #define PG8_LDB(dst, b, h) do { _Pragma("unroll") for (int n = 0; n < 2; ++n) _Pragma("unroll") for (int k = 0; k < 2; ++k) dst[n][k] = *(const PG8_LAS bf16x8*)(lds + PG8_SB(b, h) + boff + n * 2048 + k * 1024); } while (0)
; #define PG8_MMA(ai, bj, At, Bt) do { __builtin_amdgcn_s_setprio(1); _Pragma("unroll") for (int m = 0; m < 4; ++m) _Pragma("unroll") for (int n = 0; n < 2; ++n) _Pragma("unroll") for (int k = 0; k < 2; ++k) \
;         acc[ai][bj][m][n] = __builtin_amdgcn_mfma_f32_16x16x32_bf16(Bt[n][k], At[m][k], acc[ai][bj][m][n], 0, 0, 0); __builtin_amdgcn_s_setprio(0); } while (0)
; #define PG8_WAIT_V(n) asm volatile("s_waitcnt vmcnt(" #n ")" ::: "memory")
; #define PG8_WAIT_L(n) asm volatile("s_waitcnt lgkmcnt(" #n ")" ::: "memory")
; #define PG8_BAR __builtin_amdgcn_s_barrier()
; #define PG8_SCHED __builtin_amdgcn_sched_barrier(0)
; template <class Epi, class Sched, bool ALIGN_EPI = false, bool SP2 = false>
; __device__ __forceinline__ void gemm_phase(PG8_LAS unsigned char* lds, const Gemm g, const Sched& S, const Epi& E) {
;     ...
;             PG8_WAIT_V(8); PG8_WAIT_L(0); PG8_BAR; PG8_MMA(1, 0, At, B0); PG8_MMA(1, 1, At, B1); PG8_BAR; PG8_SCHED;
;             PG8_LDB(B0, 1, 0); PG8_LDB(B1, 1, 1); PG8_SCHED; PG8_LDA(At, 1, 0); PG8_STAGE(PG8_SA(0, 1), a2 + hstep, voffA);
;             PG8_WAIT_V(8); PG8_WAIT_L(0); PG8_BAR; PG8_MMA(0, 0, At, B0); PG8_MMA(0, 1, At, B1); PG8_BAR; PG8_SCHED;
	s_setprio 1
	s_waitcnt lgkmcnt(0)
	v_mfma_f32_16x16x32_bf16 v[60:63], v[144:147], v[188:191], v[60:63]
	v_mfma_f32_16x16x32_bf16 v[52:55], v[164:167], v[188:191], v[52:55]
	v_mfma_f32_16x16x32_bf16 v[44:47], v[144:147], v[196:199], v[44:47]
	v_mfma_f32_16x16x32_bf16 v[36:39], v[164:167], v[196:199], v[36:39]
	v_mfma_f32_16x16x32_bf16 v[28:31], v[144:147], v[204:207], v[28:31]
	v_mfma_f32_16x16x32_bf16 v[20:23], v[164:167], v[204:207], v[20:23]
	v_mfma_f32_16x16x32_bf16 v[12:15], v[144:147], v[212:215], v[12:15]
	v_mfma_f32_16x16x32_bf16 v[4:7], v[164:167], v[212:215], v[4:7]
	v_mfma_f32_16x16x32_bf16 v[60:63], v[160:163], v[192:195], v[60:63]
	v_mfma_f32_16x16x32_bf16 v[52:55], v[168:171], v[192:195], v[52:55]
	v_mfma_f32_16x16x32_bf16 v[44:47], v[160:163], v[200:203], v[44:47]
	v_mfma_f32_16x16x32_bf16 v[36:39], v[168:171], v[200:203], v[36:39]
	v_mfma_f32_16x16x32_bf16 v[28:31], v[160:163], v[208:211], v[28:31]
	v_mfma_f32_16x16x32_bf16 v[20:23], v[168:171], v[208:211], v[20:23]
	v_mfma_f32_16x16x32_bf16 v[12:15], v[160:163], v[216:219], v[12:15]
	v_mfma_f32_16x16x32_bf16 v[4:7], v[168:171], v[216:219], v[4:7]
	s_setprio 0
	s_setprio 1
	v_mfma_f32_16x16x32_bf16 v[56:59], v[172:175], v[188:191], v[56:59]
	v_mfma_f32_16x16x32_bf16 v[48:51], v[180:183], v[188:191], v[48:51]
	v_mfma_f32_16x16x32_bf16 v[40:43], v[172:175], v[196:199], v[40:43]
	v_mfma_f32_16x16x32_bf16 v[32:35], v[180:183], v[196:199], v[32:35]
	v_mfma_f32_16x16x32_bf16 v[24:27], v[172:175], v[204:207], v[24:27]
	v_mfma_f32_16x16x32_bf16 v[16:19], v[180:183], v[204:207], v[16:19]
	v_mfma_f32_16x16x32_bf16 v[8:11], v[172:175], v[212:215], v[8:11]
	v_mfma_f32_16x16x32_bf16 v[0:3], v[180:183], v[212:215], v[0:3]
	v_mfma_f32_16x16x32_bf16 v[56:59], v[176:179], v[192:195], v[56:59]
	v_mfma_f32_16x16x32_bf16 v[48:51], v[184:187], v[192:195], v[48:51]
	v_mfma_f32_16x16x32_bf16 v[40:43], v[176:179], v[200:203], v[40:43]
	v_mfma_f32_16x16x32_bf16 v[32:35], v[184:187], v[200:203], v[32:35]
	v_mfma_f32_16x16x32_bf16 v[24:27], v[176:179], v[208:211], v[24:27]
	v_mfma_f32_16x16x32_bf16 v[16:19], v[184:187], v[208:211], v[16:19]
	v_mfma_f32_16x16x32_bf16 v[8:11], v[176:179], v[216:219], v[8:11]
	v_mfma_f32_16x16x32_bf16 v[0:3], v[184:187], v[216:219], v[0:3]
	s_setprio 0
	s_barrier
	s_add_i32 s52, 0, 0x18000
	s_add_i32 s53, 0, 0x1c000
	s_add_u32 s8, s8, 0x40000
	s_addc_u32 s9, s9, 0
	s_mov_b32 m0, s35
	v_lshl_add_u64 v[226:227], s[8:9], 0, v[134:135]
	global_load_lds_dwordx4 v[226:227], off
	v_lshl_add_u64 v[226:227], s[8:9], 0, v[130:131]
	s_mov_b32 m0, s36
	v_add_u32_e32 v159, s52, v151
	global_load_lds_dwordx4 v[226:227], off
	ds_read_b128 v[144:147], v159
	ds_read_b128 v[160:163], v159 offset:1024
	ds_read_b128 v[164:167], v159 offset:2048
	ds_read_b128 v[168:171], v159 offset:3072
	v_add_u32_e32 v159, s53, v151
	ds_read_b128 v[172:175], v159
	ds_read_b128 v[176:179], v159 offset:1024
	ds_read_b128 v[180:183], v159 offset:2048
	ds_read_b128 v[184:187], v159 offset:3072
	ds_read_b128 v[188:191], v157 offset:32768
	ds_read_b128 v[192:195], v157 offset:33792
	ds_read_b128 v[196:199], v157 offset:34816
	ds_read_b128 v[200:203], v157 offset:35840
	ds_read_b128 v[204:207], v157 offset:36864
	ds_read_b128 v[208:211], v157 offset:37888
	ds_read_b128 v[212:215], v157 offset:38912
	ds_read_b128 v[216:219], v157 offset:39936
	s_waitcnt vmcnt(8)
	s_waitcnt lgkmcnt(0)
	s_barrier
	s_setprio 1
	s_waitcnt lgkmcnt(0)
	v_mfma_f32_16x16x32_bf16 v[124:127], v[144:147], v[188:191], v[124:127]
	v_mfma_f32_16x16x32_bf16 v[116:119], v[164:167], v[188:191], v[116:119]
	v_mfma_f32_16x16x32_bf16 v[108:111], v[144:147], v[196:199], v[108:111]
	v_mfma_f32_16x16x32_bf16 v[100:103], v[164:167], v[196:199], v[100:103]
	v_mfma_f32_16x16x32_bf16 v[92:95], v[144:147], v[204:207], v[92:95]
	v_mfma_f32_16x16x32_bf16 v[84:87], v[164:167], v[204:207], v[84:87]
	v_mfma_f32_16x16x32_bf16 v[76:79], v[144:147], v[212:215], v[76:79]
	v_mfma_f32_16x16x32_bf16 v[68:71], v[164:167], v[212:215], v[68:71]
	v_mfma_f32_16x16x32_bf16 v[124:127], v[160:163], v[192:195], v[124:127]
	v_mfma_f32_16x16x32_bf16 v[116:119], v[168:171], v[192:195], v[116:119]
	v_mfma_f32_16x16x32_bf16 v[108:111], v[160:163], v[200:203], v[108:111]
	v_mfma_f32_16x16x32_bf16 v[100:103], v[168:171], v[200:203], v[100:103]
	v_mfma_f32_16x16x32_bf16 v[92:95], v[160:163], v[208:211], v[92:95]
	v_mfma_f32_16x16x32_bf16 v[84:87], v[168:171], v[208:211], v[84:87]
	v_mfma_f32_16x16x32_bf16 v[76:79], v[160:163], v[216:219], v[76:79]
	v_mfma_f32_16x16x32_bf16 v[68:71], v[168:171], v[216:219], v[68:71]
	s_setprio 0
	s_setprio 1
	v_mfma_f32_16x16x32_bf16 v[120:123], v[172:175], v[188:191], v[120:123]
	v_mfma_f32_16x16x32_bf16 v[112:115], v[180:183], v[188:191], v[112:115]
	v_mfma_f32_16x16x32_bf16 v[104:107], v[172:175], v[196:199], v[104:107]
	v_mfma_f32_16x16x32_bf16 v[96:99], v[180:183], v[196:199], v[96:99]
	v_mfma_f32_16x16x32_bf16 v[88:91], v[172:175], v[204:207], v[88:91]
	v_mfma_f32_16x16x32_bf16 v[80:83], v[180:183], v[204:207], v[80:83]
	v_mfma_f32_16x16x32_bf16 v[72:75], v[172:175], v[212:215], v[72:75]
	v_mfma_f32_16x16x32_bf16 v[64:67], v[180:183], v[212:215], v[64:67]
	v_mfma_f32_16x16x32_bf16 v[120:123], v[176:179], v[192:195], v[120:123]
	v_mfma_f32_16x16x32_bf16 v[112:115], v[184:187], v[192:195], v[112:115]
	v_mfma_f32_16x16x32_bf16 v[104:107], v[176:179], v[200:203], v[104:107]
	v_mfma_f32_16x16x32_bf16 v[96:99], v[184:187], v[200:203], v[96:99]
	v_mfma_f32_16x16x32_bf16 v[88:91], v[176:179], v[208:211], v[88:91]
	v_mfma_f32_16x16x32_bf16 v[80:83], v[184:187], v[208:211], v[80:83]
	v_mfma_f32_16x16x32_bf16 v[72:75], v[176:179], v[216:219], v[72:75]
	v_mfma_f32_16x16x32_bf16 v[64:67], v[184:187], v[216:219], v[64:67]
	s_setprio 0
	s_barrier
; #define PG8_STAGE(bufoff, gbase, voff) do { _Pragma("unroll") for (int _i = 0; _i < 2; ++_i) \
;         __builtin_amdgcn_global_load_lds((const unsigned*)((const char*)(gbase) + (voff)[_i]), (PG8_LAS unsigned*)(lds + (bufoff) + ldsw + _i * 8192), 16, 0, 0); } while (0)
; #define PG8_LDA(dst, b, h) do { _Pragma("unroll") for (int m = 0; m < 4; ++m) _Pragma("unroll") for (int k = 0; k < 2; ++k) dst[m][k] = *(const PG8_LAS bf16x8*)(lds + PG8_SA(b, h) + aoff + m * 2048 + k * 1024); } while (0)
; #define PG8_MMA(ai, bj, At, Bt) do { __builtin_amdgcn_s_setprio(1); _Pragma("unroll") for (int m = 0; m < 4; ++m) _Pragma("unroll") for (int n = 0; n < 2; ++n) _Pragma("unroll") for (int k = 0; k < 2; ++k) \
;         acc[ai][bj][m][n] = __builtin_amdgcn_mfma_f32_16x16x32_bf16(Bt[n][k], At[m][k], acc[ai][bj][m][n], 0, 0, 0); __builtin_amdgcn_s_setprio(0); } while (0)
; #define PG8_WAIT_V(n) asm volatile("s_waitcnt vmcnt(" #n ")" ::: "memory")
; #define PG8_WAIT_L(n) asm volatile("s_waitcnt lgkmcnt(" #n ")" ::: "memory")
; #define PG8_BAR __builtin_amdgcn_s_barrier()
; #define PG8_SCHED __builtin_amdgcn_sched_barrier(0)
; template <class Epi, class Sched, bool ALIGN_EPI = false, bool SP2 = false>
; __device__ __forceinline__ void gemm_phase(PG8_LAS unsigned char* lds, const Gemm g, const Sched& S, const Epi& E) {
;     ...
;             PG8_LDA(At, 1, 1); PG8_STAGE(PG8_SB(1, 0), b3, voffB); PG8_STAGE(PG8_SB(1, 1), b3 + hstep, voffB); PG8_STAGE(PG8_SA(1, 0), a3, voffA);
;             PG8_WAIT_V(8); PG8_WAIT_L(0); PG8_BAR; PG8_MMA(1, 0, At, B0); PG8_MMA(1, 1, At, B1); PG8_BAR; PG8_SCHED;
	s_add_i32 s8, s52, s28
	v_lshl_add_u64 v[152:153], v[152:153], 0, s[16:17]
	s_mov_b32 m0, s8
	ds_read_b128 v[188:191], v157 offset:49152
	global_load_lds_dwordx4 v[152:153], off
	s_add_i32 m0, s8, 0x2000
	s_add_u32 s6, s6, 0x40080
	v_lshl_add_u64 v[152:153], v[220:221], 0, s[16:17]
	s_addc_u32 s7, s7, 0
	s_add_i32 s8, s53, s28
	global_load_lds_dwordx4 v[152:153], off
	v_lshl_add_u64 v[152:153], s[6:7], 0, v[132:133]
	s_mov_b32 m0, s8
	ds_read_b128 v[192:195], v157 offset:50176
	global_load_lds_dwordx4 v[152:153], off
	v_lshl_add_u64 v[152:153], s[6:7], 0, v[128:129]
	s_add_i32 m0, s8, 0x2000
	ds_read_b128 v[196:199], v157 offset:51200
	global_load_lds_dwordx4 v[152:153], off
	v_lshl_add_u64 v[152:153], v[222:223], 0, s[16:17]
	s_mov_b32 m0, s38
	ds_read_b128 v[200:203], v157 offset:52224
	global_load_lds_dwordx4 v[152:153], off
	v_lshl_add_u64 v[152:153], v[224:225], 0, s[16:17]
	s_mov_b32 m0, s39
	ds_read_b128 v[204:207], v157 offset:53248
	global_load_lds_dwordx4 v[152:153], off
	ds_read_b128 v[208:211], v157 offset:54272
	ds_read_b128 v[212:215], v157 offset:55296
	ds_read_b128 v[216:219], v157 offset:56320
	s_waitcnt vmcnt(8)
	s_waitcnt lgkmcnt(0)
	s_barrier
	s_setprio 1
	s_waitcnt lgkmcnt(0)
	v_mfma_f32_16x16x32_bf16 v[60:63], v[144:147], v[188:191], v[60:63]
	v_mfma_f32_16x16x32_bf16 v[52:55], v[164:167], v[188:191], v[52:55]
	v_mfma_f32_16x16x32_bf16 v[44:47], v[144:147], v[196:199], v[44:47]
	v_mfma_f32_16x16x32_bf16 v[36:39], v[164:167], v[196:199], v[36:39]
	v_mfma_f32_16x16x32_bf16 v[28:31], v[144:147], v[204:207], v[28:31]
	v_mfma_f32_16x16x32_bf16 v[20:23], v[164:167], v[204:207], v[20:23]
	v_mfma_f32_16x16x32_bf16 v[12:15], v[144:147], v[212:215], v[12:15]
	v_mfma_f32_16x16x32_bf16 v[4:7], v[164:167], v[212:215], v[4:7]
	v_mfma_f32_16x16x32_bf16 v[60:63], v[160:163], v[192:195], v[60:63]
	v_mfma_f32_16x16x32_bf16 v[52:55], v[168:171], v[192:195], v[52:55]
	v_mfma_f32_16x16x32_bf16 v[44:47], v[160:163], v[200:203], v[44:47]
	v_mfma_f32_16x16x32_bf16 v[36:39], v[168:171], v[200:203], v[36:39]
	v_mfma_f32_16x16x32_bf16 v[28:31], v[160:163], v[208:211], v[28:31]
	v_mfma_f32_16x16x32_bf16 v[20:23], v[168:171], v[208:211], v[20:23]
	v_mfma_f32_16x16x32_bf16 v[12:15], v[160:163], v[216:219], v[12:15]
	v_mfma_f32_16x16x32_bf16 v[4:7], v[168:171], v[216:219], v[4:7]
	s_setprio 0
	s_setprio 1
	v_mfma_f32_16x16x32_bf16 v[56:59], v[172:175], v[188:191], v[56:59]
	v_mfma_f32_16x16x32_bf16 v[48:51], v[180:183], v[188:191], v[48:51]
	v_mfma_f32_16x16x32_bf16 v[40:43], v[172:175], v[196:199], v[40:43]
	v_mfma_f32_16x16x32_bf16 v[32:35], v[180:183], v[196:199], v[32:35]
	v_mfma_f32_16x16x32_bf16 v[24:27], v[172:175], v[204:207], v[24:27]
	v_mfma_f32_16x16x32_bf16 v[16:19], v[180:183], v[204:207], v[16:19]
	v_mfma_f32_16x16x32_bf16 v[8:11], v[172:175], v[212:215], v[8:11]
	v_mfma_f32_16x16x32_bf16 v[0:3], v[180:183], v[212:215], v[0:3]
	v_mfma_f32_16x16x32_bf16 v[56:59], v[176:179], v[192:195], v[56:59]
	v_mfma_f32_16x16x32_bf16 v[48:51], v[184:187], v[192:195], v[48:51]
	v_mfma_f32_16x16x32_bf16 v[40:43], v[176:179], v[200:203], v[40:43]
	v_mfma_f32_16x16x32_bf16 v[32:35], v[184:187], v[200:203], v[32:35]
	v_mfma_f32_16x16x32_bf16 v[24:27], v[176:179], v[208:211], v[24:27]
	v_mfma_f32_16x16x32_bf16 v[16:19], v[184:187], v[208:211], v[16:19]
	v_mfma_f32_16x16x32_bf16 v[8:11], v[176:179], v[216:219], v[8:11]
	v_mfma_f32_16x16x32_bf16 v[0:3], v[184:187], v[216:219], v[0:3]
	s_setprio 0
	s_barrier
	s_add_i32 s51, s51, 2
	s_add_u32 s4, s4, 0x100
	s_addc_u32 s5, s5, 0
	s_add_u32 s45, s45, 0x100
	s_addc_u32 s50, s50, 0
	s_cmp_gt_u32 s51, 13
	s_cbranch_scc0 .LBB0_1487
	s_nop 0
	s_nop 0
	s_nop 0
	s_nop 0
	s_nop 0
	s_nop 0
	s_nop 0
	s_nop 0
	s_nop 0
	s_and_b64 vcc, exec, s[18:19]
	s_cbranch_vccz .LBB0_1490
	s_barrier

; #define PG8_STAGE(bufoff, gbase, voff) do { _Pragma("unroll") for (int _i = 0; _i < 2; ++_i) \
;         __builtin_amdgcn_global_load_lds((const unsigned*)((const char*)(gbase) + (voff)[_i]), (PG8_LAS unsigned*)(lds + (bufoff) + ldsw + _i * 8192), 16, 0, 0); } while (0)
; #define PG8_LDA(dst, b, h) do { _Pragma("unroll") for (int m = 0; m < 4; ++m) _Pragma("unroll") for (int k = 0; k < 2; ++k) dst[m][k] = *(const PG8_LAS bf16x8*)(lds + PG8_SA(b, h) + aoff + m * 2048 + k * 1024); } while (0)
; #define PG8_LDB(dst, b, h) do { _Pragma("unroll") for (int n = 0; n < 2; ++n) _Pragma("unroll") for (int k = 0; k < 2; ++k) dst[n][k] = *(const PG8_LAS bf16x8*)(lds + PG8_SB(b, h) + boff + n * 2048 + k * 1024); } while (0)
; #define PG8_MMA(ai, bj, At, Bt) do { __builtin_amdgcn_s_setprio(1); _Pragma("unroll") for (int m = 0; m < 4; ++m) _Pragma("unroll") for (int n = 0; n < 2; ++n) _Pragma("unroll") for (int k = 0; k < 2; ++k) \
;         acc[ai][bj][m][n] = __builtin_amdgcn_mfma_f32_16x16x32_bf16(Bt[n][k], At[m][k], acc[ai][bj][m][n], 0, 0, 0); __builtin_amdgcn_s_setprio(0); } while (0)
; #define PG8_WAIT_V(n) asm volatile("s_waitcnt vmcnt(" #n ")" ::: "memory")
; #define PG8_WAIT_L(n) asm volatile("s_waitcnt lgkmcnt(" #n ")" ::: "memory")
; #define PG8_BAR __builtin_amdgcn_s_barrier()
; #define PG8_SCHED __builtin_amdgcn_sched_barrier(0)
; template <class Epi, class Sched, bool ALIGN_EPI = false, bool SP2 = false>
; __device__ __forceinline__ void gemm_phase(PG8_LAS unsigned char* lds, const Gemm g, const Sched& S, const Epi& E) {
;     ...
;             PG8_LDB(B0, 0, 0); PG8_LDB(B1, 0, 1); PG8_SCHED; PG8_LDA(At, 0, 0); PG8_STAGE(PG8_SA(1, 1), a1 + hstep, voffA);
;             PG8_WAIT_V(8); PG8_WAIT_L(0); PG8_BAR; PG8_MMA(0, 0, At, B0); PG8_MMA(0, 1, At, B1); PG8_BAR; PG8_SCHED;
;             PG8_LDA(At, 0, 1); PG8_STAGE(PG8_SB(0, 0), b2, voffB); PG8_STAGE(PG8_SB(0, 1), b2 + hstep, voffB); PG8_STAGE(PG8_SA(0, 0), a2, voffA);
;             PG8_WAIT_V(8); PG8_WAIT_L(0); PG8_BAR; PG8_MMA(1, 0, At, B0); PG8_MMA(1, 1, At, B1); PG8_BAR; PG8_SCHED;
.LBB0_1572:
	s_add_u32 s22, s20, 0xfff50080
	s_addc_u32 s23, s21, -1
	s_cmp_eq_u32 s47, 40
	s_cselect_b32 s25, s1, s23
	s_cselect_b32 s24, s0, s22
	s_cselect_b32 s23, s19, s46
	s_cselect_b32 s22, s18, s45
	v_lshl_add_u64 v[214:215], s[20:21], 0, v[132:133]
	s_add_i32 m0, s27, 0xc000
	ds_read_b128 v[140:143], v189
	global_load_lds_dwordx4 v[214:215], off
	v_lshl_add_u64 v[214:215], s[20:21], 0, v[134:135]
	s_add_i32 m0, s27, 0xe000
	ds_read_b128 v[144:147], v189 offset:1024
	global_load_lds_dwordx4 v[214:215], off
	ds_read_b128 v[152:155], v189 offset:2048
	ds_read_b128 v[156:159], v189 offset:3072
	ds_read_b128 v[160:163], v190
	ds_read_b128 v[164:167], v190 offset:1024
	ds_read_b128 v[168:171], v190 offset:2048
	ds_read_b128 v[172:175], v190 offset:3072
	ds_read_b128 v[176:179], v191
	ds_read_b128 v[180:183], v191 offset:1024
	ds_read_b128 v[184:187], v191 offset:2048
	ds_read_b128 v[194:197], v191 offset:3072
	ds_read_b128 v[198:201], v191 offset:4096
	ds_read_b128 v[202:205], v191 offset:5120
	ds_read_b128 v[206:209], v191 offset:6144
	ds_read_b128 v[210:213], v191 offset:7168
	s_waitcnt vmcnt(8)
	s_waitcnt lgkmcnt(0)
	s_barrier
	s_setprio 1
	s_waitcnt lgkmcnt(0)
	v_mfma_f32_16x16x32_bf16 v[124:127], v[140:143], v[176:179], v[124:127]
	v_mfma_f32_16x16x32_bf16 v[120:123], v[152:155], v[176:179], v[120:123]
	v_mfma_f32_16x16x32_bf16 v[108:111], v[140:143], v[184:187], v[108:111]
	v_mfma_f32_16x16x32_bf16 v[104:107], v[152:155], v[184:187], v[104:107]
	v_mfma_f32_16x16x32_bf16 v[92:95], v[140:143], v[198:201], v[92:95]
	v_mfma_f32_16x16x32_bf16 v[88:91], v[152:155], v[198:201], v[88:91]
	v_mfma_f32_16x16x32_bf16 v[76:79], v[140:143], v[206:209], v[76:79]
	v_mfma_f32_16x16x32_bf16 v[72:75], v[152:155], v[206:209], v[72:75]
	v_mfma_f32_16x16x32_bf16 v[124:127], v[144:147], v[180:183], v[124:127]
	v_mfma_f32_16x16x32_bf16 v[120:123], v[156:159], v[180:183], v[120:123]
	v_mfma_f32_16x16x32_bf16 v[108:111], v[144:147], v[194:197], v[108:111]
	v_mfma_f32_16x16x32_bf16 v[104:107], v[156:159], v[194:197], v[104:107]
	v_mfma_f32_16x16x32_bf16 v[92:95], v[144:147], v[202:205], v[92:95]
	v_mfma_f32_16x16x32_bf16 v[88:91], v[156:159], v[202:205], v[88:91]
	v_mfma_f32_16x16x32_bf16 v[76:79], v[144:147], v[210:213], v[76:79]
	v_mfma_f32_16x16x32_bf16 v[72:75], v[156:159], v[210:213], v[72:75]
	s_setprio 0
	s_setprio 1
	v_mfma_f32_16x16x32_bf16 v[116:119], v[160:163], v[176:179], v[116:119]
	v_mfma_f32_16x16x32_bf16 v[112:115], v[168:171], v[176:179], v[112:115]
	v_mfma_f32_16x16x32_bf16 v[100:103], v[160:163], v[184:187], v[100:103]
	v_mfma_f32_16x16x32_bf16 v[96:99], v[168:171], v[184:187], v[96:99]
	v_mfma_f32_16x16x32_bf16 v[84:87], v[160:163], v[198:201], v[84:87]
	v_mfma_f32_16x16x32_bf16 v[80:83], v[168:171], v[198:201], v[80:83]
	v_mfma_f32_16x16x32_bf16 v[68:71], v[160:163], v[206:209], v[68:71]
	v_mfma_f32_16x16x32_bf16 v[64:67], v[168:171], v[206:209], v[64:67]
	v_mfma_f32_16x16x32_bf16 v[116:119], v[164:167], v[180:183], v[116:119]
	v_mfma_f32_16x16x32_bf16 v[112:115], v[172:175], v[180:183], v[112:115]
	v_mfma_f32_16x16x32_bf16 v[100:103], v[164:167], v[194:197], v[100:103]
	v_mfma_f32_16x16x32_bf16 v[96:99], v[172:175], v[194:197], v[96:99]
	v_mfma_f32_16x16x32_bf16 v[84:87], v[164:167], v[202:205], v[84:87]
	v_mfma_f32_16x16x32_bf16 v[80:83], v[172:175], v[202:205], v[80:83]
	v_mfma_f32_16x16x32_bf16 v[68:71], v[164:167], v[210:213], v[68:71]
	v_mfma_f32_16x16x32_bf16 v[64:67], v[172:175], v[210:213], v[64:67]
	s_setprio 0
	s_barrier
	s_add_i32 s50, s38, s26
	v_lshl_add_u64 v[214:215], s[22:23], 0, v[128:129]
	s_mov_b32 m0, s50
	v_lshl_add_u64 v[216:217], s[22:23], 0, v[130:131]
	global_load_lds_dwordx4 v[214:215], off
	s_add_i32 m0, s50, 0x2000
	s_add_u32 s50, s22, 0xb0000
	s_addc_u32 s51, s23, 0
	s_add_i32 s52, s39, s26
	global_load_lds_dwordx4 v[216:217], off
	v_lshl_add_u64 v[218:219], s[50:51], 0, v[128:129]
	s_mov_b32 m0, s52
	v_lshl_add_u64 v[220:221], s[24:25], 0, v[130:131]
	global_load_lds_dwordx4 v[218:219], off
	v_lshl_add_u64 v[218:219], s[50:51], 0, v[130:131]
	s_add_i32 m0, s52, 0x2000
	ds_read_b128 v[176:179], v191 offset:16384
	global_load_lds_dwordx4 v[218:219], off
	v_lshl_add_u64 v[218:219], s[24:25], 0, v[128:129]
	s_mov_b32 m0, s27
	ds_read_b128 v[180:183], v191 offset:17408
	global_load_lds_dwordx4 v[218:219], off
	s_mov_b32 m0, s28
	ds_read_b128 v[184:187], v191 offset:18432
	global_load_lds_dwordx4 v[220:221], off
	ds_read_b128 v[194:197], v191 offset:19456
	ds_read_b128 v[198:201], v191 offset:20480
	ds_read_b128 v[202:205], v191 offset:21504
	ds_read_b128 v[206:209], v191 offset:22528
	ds_read_b128 v[210:213], v191 offset:23552
	s_waitcnt vmcnt(8)
	s_waitcnt lgkmcnt(0)
	s_barrier
; #define PG8_STAGE(bufoff, gbase, voff) do { _Pragma("unroll") for (int _i = 0; _i < 2; ++_i) \
;         __builtin_amdgcn_global_load_lds((const unsigned*)((const char*)(gbase) + (voff)[_i]), (PG8_LAS unsigned*)(lds + (bufoff) + ldsw + _i * 8192), 16, 0, 0); } while (0)
; #define PG8_LDA(dst, b, h) do { _Pragma("unroll") for (int m = 0; m < 4; ++m) _Pragma("unroll") for (int k = 0; k < 2; ++k) dst[m][k] = *(const PG8_LAS bf16x8*)(lds + PG8_SA(b, h) + aoff + m * 2048 + k * 1024); } while (0)
; #define PG8_LDB(dst, b, h) do { _Pragma("unroll") for (int n = 0; n < 2; ++n) _Pragma("unroll") for (int k = 0; k < 2; ++k) dst[n][k] = *(const PG8_LAS bf16x8*)(lds + PG8_SB(b, h) + boff + n * 2048 + k * 1024); } while (0)
; #define PG8_MMA(ai, bj, At, Bt) do { __builtin_amdgcn_s_setprio(1); _Pragma("unroll") for (int m = 0; m < 4; ++m) _Pragma("unroll") for (int n = 0; n < 2; ++n) _Pragma("unroll") for (int k = 0; k < 2; ++k) \
;         acc[ai][bj][m][n] = __builtin_amdgcn_mfma_f32_16x16x32_bf16(Bt[n][k], At[m][k], acc[ai][bj][m][n], 0, 0, 0); __builtin_amdgcn_s_setprio(0); } while (0)
; #define PG8_WAIT_V(n) asm volatile("s_waitcnt vmcnt(" #n ")" ::: "memory")
; #define PG8_WAIT_L(n) asm volatile("s_waitcnt lgkmcnt(" #n ")" ::: "memory")
; #define PG8_BAR __builtin_amdgcn_s_barrier()
; #define PG8_SCHED __builtin_amdgcn_sched_barrier(0)
; template <class Epi, class Sched, bool ALIGN_EPI = false, bool SP2 = false>
; __device__ __forceinline__ void gemm_phase(PG8_LAS unsigned char* lds, const Gemm g, const Sched& S, const Epi& E) {
;     ...
;             PG8_WAIT_V(8); PG8_WAIT_L(0); PG8_BAR; PG8_MMA(1, 0, At, B0); PG8_MMA(1, 1, At, B1); PG8_BAR; PG8_SCHED;
;             PG8_LDB(B0, 1, 0); PG8_LDB(B1, 1, 1); PG8_SCHED; PG8_LDA(At, 1, 0); PG8_STAGE(PG8_SA(0, 1), a2 + hstep, voffA);
;             PG8_WAIT_V(8); PG8_WAIT_L(0); PG8_BAR; PG8_MMA(0, 0, At, B0); PG8_MMA(0, 1, At, B1); PG8_BAR; PG8_SCHED;
	s_setprio 1
	s_waitcnt lgkmcnt(0)
	v_mfma_f32_16x16x32_bf16 v[60:63], v[140:143], v[176:179], v[60:63]
	v_mfma_f32_16x16x32_bf16 v[56:59], v[152:155], v[176:179], v[56:59]
	v_mfma_f32_16x16x32_bf16 v[44:47], v[140:143], v[184:187], v[44:47]
	v_mfma_f32_16x16x32_bf16 v[40:43], v[152:155], v[184:187], v[40:43]
	v_mfma_f32_16x16x32_bf16 v[28:31], v[140:143], v[198:201], v[28:31]
	v_mfma_f32_16x16x32_bf16 v[24:27], v[152:155], v[198:201], v[24:27]
	v_mfma_f32_16x16x32_bf16 v[12:15], v[140:143], v[206:209], v[12:15]
	v_mfma_f32_16x16x32_bf16 v[8:11], v[152:155], v[206:209], v[8:11]
	v_mfma_f32_16x16x32_bf16 v[60:63], v[144:147], v[180:183], v[60:63]
	v_mfma_f32_16x16x32_bf16 v[56:59], v[156:159], v[180:183], v[56:59]
	v_mfma_f32_16x16x32_bf16 v[44:47], v[144:147], v[194:197], v[44:47]
	v_mfma_f32_16x16x32_bf16 v[40:43], v[156:159], v[194:197], v[40:43]
	v_mfma_f32_16x16x32_bf16 v[28:31], v[144:147], v[202:205], v[28:31]
	v_mfma_f32_16x16x32_bf16 v[24:27], v[156:159], v[202:205], v[24:27]
	v_mfma_f32_16x16x32_bf16 v[12:15], v[144:147], v[210:213], v[12:15]
	v_mfma_f32_16x16x32_bf16 v[8:11], v[156:159], v[210:213], v[8:11]
	s_setprio 0
	s_setprio 1
	v_mfma_f32_16x16x32_bf16 v[52:55], v[160:163], v[176:179], v[52:55]
	v_mfma_f32_16x16x32_bf16 v[48:51], v[168:171], v[176:179], v[48:51]
	v_mfma_f32_16x16x32_bf16 v[36:39], v[160:163], v[184:187], v[36:39]
	v_mfma_f32_16x16x32_bf16 v[32:35], v[168:171], v[184:187], v[32:35]
	v_mfma_f32_16x16x32_bf16 v[20:23], v[160:163], v[198:201], v[20:23]
	v_mfma_f32_16x16x32_bf16 v[16:19], v[168:171], v[198:201], v[16:19]
	v_mfma_f32_16x16x32_bf16 v[4:7], v[160:163], v[206:209], v[4:7]
	v_mfma_f32_16x16x32_bf16 v[0:3], v[168:171], v[206:209], v[0:3]
	v_mfma_f32_16x16x32_bf16 v[52:55], v[164:167], v[180:183], v[52:55]
	v_mfma_f32_16x16x32_bf16 v[48:51], v[172:175], v[180:183], v[48:51]
	v_mfma_f32_16x16x32_bf16 v[36:39], v[164:167], v[194:197], v[36:39]
	v_mfma_f32_16x16x32_bf16 v[32:35], v[172:175], v[194:197], v[32:35]
	v_mfma_f32_16x16x32_bf16 v[20:23], v[164:167], v[202:205], v[20:23]
	v_mfma_f32_16x16x32_bf16 v[16:19], v[172:175], v[202:205], v[16:19]
	v_mfma_f32_16x16x32_bf16 v[4:7], v[164:167], v[210:213], v[4:7]
	v_mfma_f32_16x16x32_bf16 v[0:3], v[172:175], v[210:213], v[0:3]
	s_setprio 0
	s_barrier
	s_add_i32 s50, 0, 0x18000
	s_add_i32 s51, 0, 0x1c000
	s_add_u32 s24, s24, 0xb0000
	s_addc_u32 s25, s25, 0
	s_mov_b32 m0, s29
	v_lshl_add_u64 v[222:223], s[24:25], 0, v[128:129]
	global_load_lds_dwordx4 v[222:223], off
	v_lshl_add_u64 v[222:223], s[24:25], 0, v[130:131]
	s_mov_b32 m0, s30
	v_add_u32_e32 v156, s50, v151
	global_load_lds_dwordx4 v[222:223], off
	v_add_u32_e32 v172, s51, v151
	ds_read_b128 v[140:143], v156
	ds_read_b128 v[144:147], v156 offset:1024
	ds_read_b128 v[152:155], v156 offset:2048
	ds_read_b128 v[156:159], v156 offset:3072
	ds_read_b128 v[160:163], v172
	ds_read_b128 v[164:167], v172 offset:1024
	ds_read_b128 v[168:171], v172 offset:2048
	ds_read_b128 v[172:175], v172 offset:3072
	ds_read_b128 v[176:179], v191 offset:32768
	ds_read_b128 v[180:183], v191 offset:33792
	ds_read_b128 v[184:187], v191 offset:34816
	ds_read_b128 v[194:197], v191 offset:35840
	ds_read_b128 v[198:201], v191 offset:36864
	ds_read_b128 v[202:205], v191 offset:37888
	ds_read_b128 v[206:209], v191 offset:38912
	ds_read_b128 v[210:213], v191 offset:39936
	s_waitcnt vmcnt(8)
	s_waitcnt lgkmcnt(0)
	s_barrier
	s_setprio 1
	s_waitcnt lgkmcnt(0)
	v_mfma_f32_16x16x32_bf16 v[124:127], v[140:143], v[176:179], v[124:127]
	v_mfma_f32_16x16x32_bf16 v[120:123], v[152:155], v[176:179], v[120:123]
	v_mfma_f32_16x16x32_bf16 v[108:111], v[140:143], v[184:187], v[108:111]
	v_mfma_f32_16x16x32_bf16 v[104:107], v[152:155], v[184:187], v[104:107]
	v_mfma_f32_16x16x32_bf16 v[92:95], v[140:143], v[198:201], v[92:95]
	v_mfma_f32_16x16x32_bf16 v[88:91], v[152:155], v[198:201], v[88:91]
	v_mfma_f32_16x16x32_bf16 v[76:79], v[140:143], v[206:209], v[76:79]
	v_mfma_f32_16x16x32_bf16 v[72:75], v[152:155], v[206:209], v[72:75]
	v_mfma_f32_16x16x32_bf16 v[124:127], v[144:147], v[180:183], v[124:127]
	v_mfma_f32_16x16x32_bf16 v[120:123], v[156:159], v[180:183], v[120:123]
	v_mfma_f32_16x16x32_bf16 v[108:111], v[144:147], v[194:197], v[108:111]
	v_mfma_f32_16x16x32_bf16 v[104:107], v[156:159], v[194:197], v[104:107]
	v_mfma_f32_16x16x32_bf16 v[92:95], v[144:147], v[202:205], v[92:95]
	v_mfma_f32_16x16x32_bf16 v[88:91], v[156:159], v[202:205], v[88:91]
	v_mfma_f32_16x16x32_bf16 v[76:79], v[144:147], v[210:213], v[76:79]
	v_mfma_f32_16x16x32_bf16 v[72:75], v[156:159], v[210:213], v[72:75]
	s_setprio 0
	s_setprio 1
	v_mfma_f32_16x16x32_bf16 v[116:119], v[160:163], v[176:179], v[116:119]
	v_mfma_f32_16x16x32_bf16 v[112:115], v[168:171], v[176:179], v[112:115]
	v_mfma_f32_16x16x32_bf16 v[100:103], v[160:163], v[184:187], v[100:103]
	v_mfma_f32_16x16x32_bf16 v[96:99], v[168:171], v[184:187], v[96:99]
	v_mfma_f32_16x16x32_bf16 v[84:87], v[160:163], v[198:201], v[84:87]
	v_mfma_f32_16x16x32_bf16 v[80:83], v[168:171], v[198:201], v[80:83]
	v_mfma_f32_16x16x32_bf16 v[68:71], v[160:163], v[206:209], v[68:71]
	v_mfma_f32_16x16x32_bf16 v[64:67], v[168:171], v[206:209], v[64:67]
	v_mfma_f32_16x16x32_bf16 v[116:119], v[164:167], v[180:183], v[116:119]
	v_mfma_f32_16x16x32_bf16 v[112:115], v[172:175], v[180:183], v[112:115]
	v_mfma_f32_16x16x32_bf16 v[100:103], v[164:167], v[194:197], v[100:103]
	v_mfma_f32_16x16x32_bf16 v[96:99], v[172:175], v[194:197], v[96:99]
	v_mfma_f32_16x16x32_bf16 v[84:87], v[164:167], v[202:205], v[84:87]
	v_mfma_f32_16x16x32_bf16 v[80:83], v[172:175], v[202:205], v[80:83]
	v_mfma_f32_16x16x32_bf16 v[68:71], v[164:167], v[210:213], v[68:71]
	v_mfma_f32_16x16x32_bf16 v[64:67], v[172:175], v[210:213], v[64:67]
	s_setprio 0
	s_barrier
; #define PG8_STAGE(bufoff, gbase, voff) do { _Pragma("unroll") for (int _i = 0; _i < 2; ++_i) \
;         __builtin_amdgcn_global_load_lds((const unsigned*)((const char*)(gbase) + (voff)[_i]), (PG8_LAS unsigned*)(lds + (bufoff) + ldsw + _i * 8192), 16, 0, 0); } while (0)
; #define PG8_LDA(dst, b, h) do { _Pragma("unroll") for (int m = 0; m < 4; ++m) _Pragma("unroll") for (int k = 0; k < 2; ++k) dst[m][k] = *(const PG8_LAS bf16x8*)(lds + PG8_SA(b, h) + aoff + m * 2048 + k * 1024); } while (0)
; #define PG8_MMA(ai, bj, At, Bt) do { __builtin_amdgcn_s_setprio(1); _Pragma("unroll") for (int m = 0; m < 4; ++m) _Pragma("unroll") for (int n = 0; n < 2; ++n) _Pragma("unroll") for (int k = 0; k < 2; ++k) \
;         acc[ai][bj][m][n] = __builtin_amdgcn_mfma_f32_16x16x32_bf16(Bt[n][k], At[m][k], acc[ai][bj][m][n], 0, 0, 0); __builtin_amdgcn_s_setprio(0); } while (0)
; #define PG8_WAIT_V(n) asm volatile("s_waitcnt vmcnt(" #n ")" ::: "memory")
; #define PG8_WAIT_L(n) asm volatile("s_waitcnt lgkmcnt(" #n ")" ::: "memory")
; #define PG8_BAR __builtin_amdgcn_s_barrier()
; #define PG8_SCHED __builtin_amdgcn_sched_barrier(0)
; template <class Epi, class Sched, bool ALIGN_EPI = false, bool SP2 = false>
; __device__ __forceinline__ void gemm_phase(PG8_LAS unsigned char* lds, const Gemm g, const Sched& S, const Epi& E) {
;     ...
;             PG8_LDA(At, 1, 1); PG8_STAGE(PG8_SB(1, 0), b3, voffB); PG8_STAGE(PG8_SB(1, 1), b3 + hstep, voffB); PG8_STAGE(PG8_SA(1, 0), a3, voffA);
;             PG8_WAIT_V(8); PG8_WAIT_L(0); PG8_BAR; PG8_MMA(1, 0, At, B0); PG8_MMA(1, 1, At, B1); PG8_BAR; PG8_SCHED;
	s_add_i32 s24, s50, s26
	v_lshl_add_u64 v[214:215], v[214:215], 0, s[14:15]
	s_mov_b32 m0, s24
	ds_read_b128 v[176:179], v191 offset:49152
	global_load_lds_dwordx4 v[214:215], off
	s_add_i32 m0, s24, 0x2000
	s_add_u32 s22, s22, 0xb0080
	v_lshl_add_u64 v[214:215], v[216:217], 0, s[14:15]
	s_addc_u32 s23, s23, 0
	s_add_i32 s24, s51, s26
	global_load_lds_dwordx4 v[214:215], off
	v_lshl_add_u64 v[214:215], s[22:23], 0, v[128:129]
	s_mov_b32 m0, s24
	ds_read_b128 v[180:183], v191 offset:50176
	global_load_lds_dwordx4 v[214:215], off
	v_lshl_add_u64 v[214:215], s[22:23], 0, v[130:131]
	s_add_i32 m0, s24, 0x2000
	ds_read_b128 v[184:187], v191 offset:51200
	global_load_lds_dwordx4 v[214:215], off
	v_lshl_add_u64 v[214:215], v[218:219], 0, s[14:15]
	s_mov_b32 m0, s34
	ds_read_b128 v[194:197], v191 offset:52224
	global_load_lds_dwordx4 v[214:215], off
	v_lshl_add_u64 v[214:215], v[220:221], 0, s[14:15]
	s_mov_b32 m0, s35
	ds_read_b128 v[198:201], v191 offset:53248
	global_load_lds_dwordx4 v[214:215], off
	ds_read_b128 v[202:205], v191 offset:54272
	ds_read_b128 v[206:209], v191 offset:55296
	ds_read_b128 v[210:213], v191 offset:56320
	s_waitcnt vmcnt(8)
	s_waitcnt lgkmcnt(0)
	s_barrier
	s_setprio 1
	s_waitcnt lgkmcnt(0)
	v_mfma_f32_16x16x32_bf16 v[60:63], v[140:143], v[176:179], v[60:63]
	v_mfma_f32_16x16x32_bf16 v[56:59], v[152:155], v[176:179], v[56:59]
	v_mfma_f32_16x16x32_bf16 v[44:47], v[140:143], v[184:187], v[44:47]
	v_mfma_f32_16x16x32_bf16 v[40:43], v[152:155], v[184:187], v[40:43]
	v_mfma_f32_16x16x32_bf16 v[28:31], v[140:143], v[198:201], v[28:31]
	v_mfma_f32_16x16x32_bf16 v[24:27], v[152:155], v[198:201], v[24:27]
	v_mfma_f32_16x16x32_bf16 v[12:15], v[140:143], v[206:209], v[12:15]
	v_mfma_f32_16x16x32_bf16 v[8:11], v[152:155], v[206:209], v[8:11]
	v_mfma_f32_16x16x32_bf16 v[60:63], v[144:147], v[180:183], v[60:63]
	v_mfma_f32_16x16x32_bf16 v[56:59], v[156:159], v[180:183], v[56:59]
	v_mfma_f32_16x16x32_bf16 v[44:47], v[144:147], v[194:197], v[44:47]
	v_mfma_f32_16x16x32_bf16 v[40:43], v[156:159], v[194:197], v[40:43]
	v_mfma_f32_16x16x32_bf16 v[28:31], v[144:147], v[202:205], v[28:31]
	v_mfma_f32_16x16x32_bf16 v[24:27], v[156:159], v[202:205], v[24:27]
	v_mfma_f32_16x16x32_bf16 v[12:15], v[144:147], v[210:213], v[12:15]
	v_mfma_f32_16x16x32_bf16 v[8:11], v[156:159], v[210:213], v[8:11]
	s_setprio 0
	s_setprio 1
	v_mfma_f32_16x16x32_bf16 v[52:55], v[160:163], v[176:179], v[52:55]
	v_mfma_f32_16x16x32_bf16 v[48:51], v[168:171], v[176:179], v[48:51]
	v_mfma_f32_16x16x32_bf16 v[36:39], v[160:163], v[184:187], v[36:39]
	v_mfma_f32_16x16x32_bf16 v[32:35], v[168:171], v[184:187], v[32:35]
	v_mfma_f32_16x16x32_bf16 v[20:23], v[160:163], v[198:201], v[20:23]
	v_mfma_f32_16x16x32_bf16 v[16:19], v[168:171], v[198:201], v[16:19]
	v_mfma_f32_16x16x32_bf16 v[4:7], v[160:163], v[206:209], v[4:7]
	v_mfma_f32_16x16x32_bf16 v[0:3], v[168:171], v[206:209], v[0:3]
	v_mfma_f32_16x16x32_bf16 v[52:55], v[164:167], v[180:183], v[52:55]
	v_mfma_f32_16x16x32_bf16 v[48:51], v[172:175], v[180:183], v[48:51]
	v_mfma_f32_16x16x32_bf16 v[36:39], v[164:167], v[194:197], v[36:39]
	v_mfma_f32_16x16x32_bf16 v[32:35], v[172:175], v[194:197], v[32:35]
	v_mfma_f32_16x16x32_bf16 v[20:23], v[164:167], v[202:205], v[20:23]
	v_mfma_f32_16x16x32_bf16 v[16:19], v[172:175], v[202:205], v[16:19]
	v_mfma_f32_16x16x32_bf16 v[4:7], v[164:167], v[210:213], v[4:7]
	v_mfma_f32_16x16x32_bf16 v[0:3], v[172:175], v[210:213], v[0:3]
	s_setprio 0
	s_barrier
	s_add_i32 s47, s47, 2
	s_add_u32 s20, s20, 0x100
	s_addc_u32 s21, s21, 0
	s_add_u32 s45, s45, 0x100
	s_addc_u32 s46, s46, 0
	s_cmp_gt_u32 s47, 41
	s_cbranch_scc0 .LBB0_1572
	s_nop 0
	s_nop 0
	s_nop 0
	s_nop 0
	s_nop 0
	s_nop 0
	s_nop 0
	s_nop 0
	s_nop 0
	s_and_b64 vcc, exec, s[16:17]
	s_cbranch_vccz .LBB0_1575
	s_barrier

; #define PG8_STAGE(bufoff, gbase, voff) do { _Pragma("unroll") for (int _i = 0; _i < 2; ++_i) \
;         __builtin_amdgcn_global_load_lds((const unsigned*)((const char*)(gbase) + (voff)[_i]), (PG8_LAS unsigned*)(lds + (bufoff) + ldsw + _i * 8192), 16, 0, 0); } while (0)
; #define PG8_LDA(dst, b, h) do { _Pragma("unroll") for (int m = 0; m < 4; ++m) _Pragma("unroll") for (int k = 0; k < 2; ++k) dst[m][k] = *(const PG8_LAS bf16x8*)(lds + PG8_SA(b, h) + aoff + m * 2048 + k * 1024); } while (0)
; #define PG8_LDB(dst, b, h) do { _Pragma("unroll") for (int n = 0; n < 2; ++n) _Pragma("unroll") for (int k = 0; k < 2; ++k) dst[n][k] = *(const PG8_LAS bf16x8*)(lds + PG8_SB(b, h) + boff + n * 2048 + k * 1024); } while (0)
; #define PG8_MMA(ai, bj, At, Bt) do { __builtin_amdgcn_s_setprio(1); _Pragma("unroll") for (int m = 0; m < 4; ++m) _Pragma("unroll") for (int n = 0; n < 2; ++n) _Pragma("unroll") for (int k = 0; k < 2; ++k) \
;         acc[ai][bj][m][n] = __builtin_amdgcn_mfma_f32_16x16x32_bf16(Bt[n][k], At[m][k], acc[ai][bj][m][n], 0, 0, 0); __builtin_amdgcn_s_setprio(0); } while (0)
; #define PG8_WAIT_V(n) asm volatile("s_waitcnt vmcnt(" #n ")" ::: "memory")
; #define PG8_WAIT_L(n) asm volatile("s_waitcnt lgkmcnt(" #n ")" ::: "memory")
; #define PG8_BAR __builtin_amdgcn_s_barrier()
; #define PG8_SCHED __builtin_amdgcn_sched_barrier(0)
; template <class Epi, class Sched, bool ALIGN_EPI = false, bool SP2 = false>
; __device__ __forceinline__ void gemm_phase(PG8_LAS unsigned char* lds, const Gemm g, const Sched& S, const Epi& E) {
;     ...
;             PG8_LDB(B0, 0, 0); PG8_LDB(B1, 0, 1); PG8_SCHED; PG8_LDA(At, 0, 0); PG8_STAGE(PG8_SA(1, 1), a1 + hstep, voffA);
;             PG8_WAIT_V(8); PG8_WAIT_L(0); PG8_BAR; PG8_MMA(0, 0, At, B0); PG8_MMA(0, 1, At, B1); PG8_BAR; PG8_SCHED;
;             PG8_LDA(At, 0, 1); PG8_STAGE(PG8_SB(0, 0), b2, voffB); PG8_STAGE(PG8_SB(0, 1), b2 + hstep, voffB); PG8_STAGE(PG8_SA(0, 0), a2, voffA);
;             PG8_WAIT_V(8); PG8_WAIT_L(0); PG8_BAR; PG8_MMA(1, 0, At, B0); PG8_MMA(1, 1, At, B1); PG8_BAR; PG8_SCHED;
.LBB0_1666:
	s_add_u32 s6, s4, 0xfffc0080
	s_addc_u32 s7, s5, -1
	s_cmp_eq_u32 s55, 12
	s_cselect_b32 s9, s10, s7
	s_cselect_b32 s8, s11, s6
	s_cselect_b32 s7, s25, s54
	s_cselect_b32 s6, s27, s53
	v_lshl_add_u64 v[152:153], s[4:5], 0, v[136:137]
	s_add_i32 m0, s39, 0xc000
	ds_read_b128 v[144:147], v155
	global_load_lds_dwordx4 v[152:153], off
	v_lshl_add_u64 v[152:153], s[4:5], 0, v[138:139]
	s_add_i32 m0, s39, 0xe000
	ds_read_b128 v[160:163], v155 offset:1024
	global_load_lds_dwordx4 v[152:153], off
	ds_read_b128 v[164:167], v155 offset:2048
	ds_read_b128 v[168:171], v155 offset:3072
	ds_read_b128 v[172:175], v156
	ds_read_b128 v[176:179], v156 offset:1024
	ds_read_b128 v[180:183], v156 offset:2048
	ds_read_b128 v[184:187], v156 offset:3072
	ds_read_b128 v[188:191], v157
	ds_read_b128 v[192:195], v157 offset:1024
	ds_read_b128 v[196:199], v157 offset:2048
	ds_read_b128 v[200:203], v157 offset:3072
	ds_read_b128 v[204:207], v157 offset:4096
	ds_read_b128 v[208:211], v157 offset:5120
	ds_read_b128 v[212:215], v157 offset:6144
	ds_read_b128 v[216:219], v157 offset:7168
	s_waitcnt vmcnt(8)
	s_waitcnt lgkmcnt(0)
	s_barrier
	s_setprio 1
	s_waitcnt lgkmcnt(0)
	v_mfma_f32_16x16x32_bf16 v[124:127], v[144:147], v[188:191], v[124:127]
	v_mfma_f32_16x16x32_bf16 v[116:119], v[164:167], v[188:191], v[116:119]
	v_mfma_f32_16x16x32_bf16 v[108:111], v[144:147], v[196:199], v[108:111]
	v_mfma_f32_16x16x32_bf16 v[100:103], v[164:167], v[196:199], v[100:103]
	v_mfma_f32_16x16x32_bf16 v[92:95], v[144:147], v[204:207], v[92:95]
	v_mfma_f32_16x16x32_bf16 v[84:87], v[164:167], v[204:207], v[84:87]
	v_mfma_f32_16x16x32_bf16 v[76:79], v[144:147], v[212:215], v[76:79]
	v_mfma_f32_16x16x32_bf16 v[68:71], v[164:167], v[212:215], v[68:71]
	v_mfma_f32_16x16x32_bf16 v[124:127], v[160:163], v[192:195], v[124:127]
	v_mfma_f32_16x16x32_bf16 v[116:119], v[168:171], v[192:195], v[116:119]
	v_mfma_f32_16x16x32_bf16 v[108:111], v[160:163], v[200:203], v[108:111]
	v_mfma_f32_16x16x32_bf16 v[100:103], v[168:171], v[200:203], v[100:103]
	v_mfma_f32_16x16x32_bf16 v[92:95], v[160:163], v[208:211], v[92:95]
	v_mfma_f32_16x16x32_bf16 v[84:87], v[168:171], v[208:211], v[84:87]
	v_mfma_f32_16x16x32_bf16 v[76:79], v[160:163], v[216:219], v[76:79]
	v_mfma_f32_16x16x32_bf16 v[68:71], v[168:171], v[216:219], v[68:71]
	s_setprio 0
	s_setprio 1
	v_mfma_f32_16x16x32_bf16 v[120:123], v[172:175], v[188:191], v[120:123]
	v_mfma_f32_16x16x32_bf16 v[112:115], v[180:183], v[188:191], v[112:115]
	v_mfma_f32_16x16x32_bf16 v[104:107], v[172:175], v[196:199], v[104:107]
	v_mfma_f32_16x16x32_bf16 v[96:99], v[180:183], v[196:199], v[96:99]
	v_mfma_f32_16x16x32_bf16 v[88:91], v[172:175], v[204:207], v[88:91]
	v_mfma_f32_16x16x32_bf16 v[80:83], v[180:183], v[204:207], v[80:83]
	v_mfma_f32_16x16x32_bf16 v[72:75], v[172:175], v[212:215], v[72:75]
	v_mfma_f32_16x16x32_bf16 v[64:67], v[180:183], v[212:215], v[64:67]
	v_mfma_f32_16x16x32_bf16 v[120:123], v[176:179], v[192:195], v[120:123]
	v_mfma_f32_16x16x32_bf16 v[112:115], v[184:187], v[192:195], v[112:115]
	v_mfma_f32_16x16x32_bf16 v[104:107], v[176:179], v[200:203], v[104:107]
	v_mfma_f32_16x16x32_bf16 v[96:99], v[184:187], v[200:203], v[96:99]
	v_mfma_f32_16x16x32_bf16 v[88:91], v[176:179], v[208:211], v[88:91]
	v_mfma_f32_16x16x32_bf16 v[80:83], v[184:187], v[208:211], v[80:83]
	v_mfma_f32_16x16x32_bf16 v[72:75], v[176:179], v[216:219], v[72:75]
	v_mfma_f32_16x16x32_bf16 v[64:67], v[184:187], v[216:219], v[64:67]
	s_setprio 0
	s_barrier
	s_add_i32 s56, s47, s36
	v_lshl_add_u64 v[152:153], s[6:7], 0, v[132:133]
	s_mov_b32 m0, s56
	v_lshl_add_u64 v[220:221], s[6:7], 0, v[128:129]
	global_load_lds_dwordx4 v[152:153], off
	s_add_i32 m0, s56, 0x2000
	s_add_u32 s56, s6, 0x40000
	s_addc_u32 s57, s7, 0
	s_add_i32 s58, s50, s36
	global_load_lds_dwordx4 v[220:221], off
	v_lshl_add_u64 v[222:223], s[56:57], 0, v[132:133]
	s_mov_b32 m0, s58
	v_lshl_add_u64 v[224:225], s[8:9], 0, v[130:131]
	global_load_lds_dwordx4 v[222:223], off
	v_lshl_add_u64 v[222:223], s[56:57], 0, v[128:129]
	s_add_i32 m0, s58, 0x2000
	ds_read_b128 v[188:191], v157 offset:16384
	global_load_lds_dwordx4 v[222:223], off
	v_lshl_add_u64 v[222:223], s[8:9], 0, v[134:135]
	s_mov_b32 m0, s39
	ds_read_b128 v[192:195], v157 offset:17408
	global_load_lds_dwordx4 v[222:223], off
	s_mov_b32 m0, s40
	ds_read_b128 v[196:199], v157 offset:18432
	global_load_lds_dwordx4 v[224:225], off
	ds_read_b128 v[200:203], v157 offset:19456
	ds_read_b128 v[204:207], v157 offset:20480
	ds_read_b128 v[208:211], v157 offset:21504
	ds_read_b128 v[212:215], v157 offset:22528
	ds_read_b128 v[216:219], v157 offset:23552
	s_waitcnt vmcnt(8)
	s_waitcnt lgkmcnt(0)
	s_barrier
; #define PG8_STAGE(bufoff, gbase, voff) do { _Pragma("unroll") for (int _i = 0; _i < 2; ++_i) \
;         __builtin_amdgcn_global_load_lds((const unsigned*)((const char*)(gbase) + (voff)[_i]), (PG8_LAS unsigned*)(lds + (bufoff) + ldsw + _i * 8192), 16, 0, 0); } while (0)
; #define PG8_LDA(dst, b, h) do { _Pragma("unroll") for (int m = 0; m < 4; ++m) _Pragma("unroll") for (int k = 0; k < 2; ++k) dst[m][k] = *(const PG8_LAS bf16x8*)(lds + PG8_SA(b, h) + aoff + m * 2048 + k * 1024); } while (0)
; #define PG8_LDB(dst, b, h) do { _Pragma("unroll") for (int n = 0; n < 2; ++n) _Pragma("unroll") for (int k = 0; k < 2; ++k) dst[n][k] = *(const PG8_LAS bf16x8*)(lds + PG8_SB(b, h) + boff + n * 2048 + k * 1024); } while (0)
; #define PG8_MMA(ai, bj, At, Bt) do { __builtin_amdgcn_s_setprio(1); _Pragma("unroll") for (int m = 0; m < 4; ++m) _Pragma("unroll") for (int n = 0; n < 2; ++n) _Pragma("unroll") for (int k = 0; k < 2; ++k) \
;         acc[ai][bj][m][n] = __builtin_amdgcn_mfma_f32_16x16x32_bf16(Bt[n][k], At[m][k], acc[ai][bj][m][n], 0, 0, 0); __builtin_amdgcn_s_setprio(0); } while (0)
; #define PG8_WAIT_V(n) asm volatile("s_waitcnt vmcnt(" #n ")" ::: "memory")
; #define PG8_WAIT_L(n) asm volatile("s_waitcnt lgkmcnt(" #n ")" ::: "memory")
; #define PG8_BAR __builtin_amdgcn_s_barrier()
; #define PG8_SCHED __builtin_amdgcn_sched_barrier(0)
; template <class Epi, class Sched, bool ALIGN_EPI = false, bool SP2 = false>
; __device__ __forceinline__ void gemm_phase(PG8_LAS unsigned char* lds, const Gemm g, const Sched& S, const Epi& E) {
;     ...
;             PG8_WAIT_V(8); PG8_WAIT_L(0); PG8_BAR; PG8_MMA(1, 0, At, B0); PG8_MMA(1, 1, At, B1); PG8_BAR; PG8_SCHED;
;             PG8_LDB(B0, 1, 0); PG8_LDB(B1, 1, 1); PG8_SCHED; PG8_LDA(At, 1, 0); PG8_STAGE(PG8_SA(0, 1), a2 + hstep, voffA);
;             PG8_WAIT_V(8); PG8_WAIT_L(0); PG8_BAR; PG8_MMA(0, 0, At, B0); PG8_MMA(0, 1, At, B1); PG8_BAR; PG8_SCHED;
	s_setprio 1
	s_waitcnt lgkmcnt(0)
	v_mfma_f32_16x16x32_bf16 v[60:63], v[144:147], v[188:191], v[60:63]
	v_mfma_f32_16x16x32_bf16 v[52:55], v[164:167], v[188:191], v[52:55]
	v_mfma_f32_16x16x32_bf16 v[44:47], v[144:147], v[196:199], v[44:47]
	v_mfma_f32_16x16x32_bf16 v[36:39], v[164:167], v[196:199], v[36:39]
	v_mfma_f32_16x16x32_bf16 v[28:31], v[144:147], v[204:207], v[28:31]
	v_mfma_f32_16x16x32_bf16 v[20:23], v[164:167], v[204:207], v[20:23]
	v_mfma_f32_16x16x32_bf16 v[12:15], v[144:147], v[212:215], v[12:15]
	v_mfma_f32_16x16x32_bf16 v[4:7], v[164:167], v[212:215], v[4:7]
	v_mfma_f32_16x16x32_bf16 v[60:63], v[160:163], v[192:195], v[60:63]
	v_mfma_f32_16x16x32_bf16 v[52:55], v[168:171], v[192:195], v[52:55]
	v_mfma_f32_16x16x32_bf16 v[44:47], v[160:163], v[200:203], v[44:47]
	v_mfma_f32_16x16x32_bf16 v[36:39], v[168:171], v[200:203], v[36:39]
	v_mfma_f32_16x16x32_bf16 v[28:31], v[160:163], v[208:211], v[28:31]
	v_mfma_f32_16x16x32_bf16 v[20:23], v[168:171], v[208:211], v[20:23]
	v_mfma_f32_16x16x32_bf16 v[12:15], v[160:163], v[216:219], v[12:15]
	v_mfma_f32_16x16x32_bf16 v[4:7], v[168:171], v[216:219], v[4:7]
	s_setprio 0
	s_setprio 1
	v_mfma_f32_16x16x32_bf16 v[56:59], v[172:175], v[188:191], v[56:59]
	v_mfma_f32_16x16x32_bf16 v[48:51], v[180:183], v[188:191], v[48:51]
	v_mfma_f32_16x16x32_bf16 v[40:43], v[172:175], v[196:199], v[40:43]
	v_mfma_f32_16x16x32_bf16 v[32:35], v[180:183], v[196:199], v[32:35]
	v_mfma_f32_16x16x32_bf16 v[24:27], v[172:175], v[204:207], v[24:27]
	v_mfma_f32_16x16x32_bf16 v[16:19], v[180:183], v[204:207], v[16:19]
	v_mfma_f32_16x16x32_bf16 v[8:11], v[172:175], v[212:215], v[8:11]
	v_mfma_f32_16x16x32_bf16 v[0:3], v[180:183], v[212:215], v[0:3]
	v_mfma_f32_16x16x32_bf16 v[56:59], v[176:179], v[192:195], v[56:59]
	v_mfma_f32_16x16x32_bf16 v[48:51], v[184:187], v[192:195], v[48:51]
	v_mfma_f32_16x16x32_bf16 v[40:43], v[176:179], v[200:203], v[40:43]
	v_mfma_f32_16x16x32_bf16 v[32:35], v[184:187], v[200:203], v[32:35]
	v_mfma_f32_16x16x32_bf16 v[24:27], v[176:179], v[208:211], v[24:27]
	v_mfma_f32_16x16x32_bf16 v[16:19], v[184:187], v[208:211], v[16:19]
	v_mfma_f32_16x16x32_bf16 v[8:11], v[176:179], v[216:219], v[8:11]
	v_mfma_f32_16x16x32_bf16 v[0:3], v[184:187], v[216:219], v[0:3]
	s_setprio 0
	s_barrier
	s_add_i32 s56, 0, 0x18000
	s_add_i32 s57, 0, 0x1c000
	s_add_u32 s8, s8, 0x40000
	s_addc_u32 s9, s9, 0
	s_mov_b32 m0, s41
	v_lshl_add_u64 v[226:227], s[8:9], 0, v[134:135]
	global_load_lds_dwordx4 v[226:227], off
	v_lshl_add_u64 v[226:227], s[8:9], 0, v[130:131]
	s_mov_b32 m0, s42
	v_add_u32_e32 v159, s56, v151
	global_load_lds_dwordx4 v[226:227], off
	ds_read_b128 v[144:147], v159
	ds_read_b128 v[160:163], v159 offset:1024
	ds_read_b128 v[164:167], v159 offset:2048
	ds_read_b128 v[168:171], v159 offset:3072
	v_add_u32_e32 v159, s57, v151
	ds_read_b128 v[172:175], v159
	ds_read_b128 v[176:179], v159 offset:1024
	ds_read_b128 v[180:183], v159 offset:2048
	ds_read_b128 v[184:187], v159 offset:3072
	ds_read_b128 v[188:191], v157 offset:32768
	ds_read_b128 v[192:195], v157 offset:33792
	ds_read_b128 v[196:199], v157 offset:34816
	ds_read_b128 v[200:203], v157 offset:35840
	ds_read_b128 v[204:207], v157 offset:36864
	ds_read_b128 v[208:211], v157 offset:37888
	ds_read_b128 v[212:215], v157 offset:38912
	ds_read_b128 v[216:219], v157 offset:39936
	s_waitcnt vmcnt(8)
	s_waitcnt lgkmcnt(0)
	s_barrier
	s_setprio 1
	s_waitcnt lgkmcnt(0)
	v_mfma_f32_16x16x32_bf16 v[124:127], v[144:147], v[188:191], v[124:127]
	v_mfma_f32_16x16x32_bf16 v[116:119], v[164:167], v[188:191], v[116:119]
	v_mfma_f32_16x16x32_bf16 v[108:111], v[144:147], v[196:199], v[108:111]
	v_mfma_f32_16x16x32_bf16 v[100:103], v[164:167], v[196:199], v[100:103]
	v_mfma_f32_16x16x32_bf16 v[92:95], v[144:147], v[204:207], v[92:95]
	v_mfma_f32_16x16x32_bf16 v[84:87], v[164:167], v[204:207], v[84:87]
	v_mfma_f32_16x16x32_bf16 v[76:79], v[144:147], v[212:215], v[76:79]
	v_mfma_f32_16x16x32_bf16 v[68:71], v[164:167], v[212:215], v[68:71]
	v_mfma_f32_16x16x32_bf16 v[124:127], v[160:163], v[192:195], v[124:127]
	v_mfma_f32_16x16x32_bf16 v[116:119], v[168:171], v[192:195], v[116:119]
	v_mfma_f32_16x16x32_bf16 v[108:111], v[160:163], v[200:203], v[108:111]
	v_mfma_f32_16x16x32_bf16 v[100:103], v[168:171], v[200:203], v[100:103]
	v_mfma_f32_16x16x32_bf16 v[92:95], v[160:163], v[208:211], v[92:95]
	v_mfma_f32_16x16x32_bf16 v[84:87], v[168:171], v[208:211], v[84:87]
	v_mfma_f32_16x16x32_bf16 v[76:79], v[160:163], v[216:219], v[76:79]
	v_mfma_f32_16x16x32_bf16 v[68:71], v[168:171], v[216:219], v[68:71]
	s_setprio 0
	s_setprio 1
	v_mfma_f32_16x16x32_bf16 v[120:123], v[172:175], v[188:191], v[120:123]
	v_mfma_f32_16x16x32_bf16 v[112:115], v[180:183], v[188:191], v[112:115]
	v_mfma_f32_16x16x32_bf16 v[104:107], v[172:175], v[196:199], v[104:107]
	v_mfma_f32_16x16x32_bf16 v[96:99], v[180:183], v[196:199], v[96:99]
	v_mfma_f32_16x16x32_bf16 v[88:91], v[172:175], v[204:207], v[88:91]
	v_mfma_f32_16x16x32_bf16 v[80:83], v[180:183], v[204:207], v[80:83]
	v_mfma_f32_16x16x32_bf16 v[72:75], v[172:175], v[212:215], v[72:75]
	v_mfma_f32_16x16x32_bf16 v[64:67], v[180:183], v[212:215], v[64:67]
	v_mfma_f32_16x16x32_bf16 v[120:123], v[176:179], v[192:195], v[120:123]
	v_mfma_f32_16x16x32_bf16 v[112:115], v[184:187], v[192:195], v[112:115]
	v_mfma_f32_16x16x32_bf16 v[104:107], v[176:179], v[200:203], v[104:107]
	v_mfma_f32_16x16x32_bf16 v[96:99], v[184:187], v[200:203], v[96:99]
	v_mfma_f32_16x16x32_bf16 v[88:91], v[176:179], v[208:211], v[88:91]
	v_mfma_f32_16x16x32_bf16 v[80:83], v[184:187], v[208:211], v[80:83]
	v_mfma_f32_16x16x32_bf16 v[72:75], v[176:179], v[216:219], v[72:75]
	v_mfma_f32_16x16x32_bf16 v[64:67], v[184:187], v[216:219], v[64:67]
	s_setprio 0
	s_barrier
; #define PG8_STAGE(bufoff, gbase, voff) do { _Pragma("unroll") for (int _i = 0; _i < 2; ++_i) \
;         __builtin_amdgcn_global_load_lds((const unsigned*)((const char*)(gbase) + (voff)[_i]), (PG8_LAS unsigned*)(lds + (bufoff) + ldsw + _i * 8192), 16, 0, 0); } while (0)
; #define PG8_LDA(dst, b, h) do { _Pragma("unroll") for (int m = 0; m < 4; ++m) _Pragma("unroll") for (int k = 0; k < 2; ++k) dst[m][k] = *(const PG8_LAS bf16x8*)(lds + PG8_SA(b, h) + aoff + m * 2048 + k * 1024); } while (0)
; #define PG8_MMA(ai, bj, At, Bt) do { __builtin_amdgcn_s_setprio(1); _Pragma("unroll") for (int m = 0; m < 4; ++m) _Pragma("unroll") for (int n = 0; n < 2; ++n) _Pragma("unroll") for (int k = 0; k < 2; ++k) \
;         acc[ai][bj][m][n] = __builtin_amdgcn_mfma_f32_16x16x32_bf16(Bt[n][k], At[m][k], acc[ai][bj][m][n], 0, 0, 0); __builtin_amdgcn_s_setprio(0); } while (0)
; #define PG8_WAIT_V(n) asm volatile("s_waitcnt vmcnt(" #n ")" ::: "memory")
; #define PG8_WAIT_L(n) asm volatile("s_waitcnt lgkmcnt(" #n ")" ::: "memory")
; #define PG8_BAR __builtin_amdgcn_s_barrier()
; #define PG8_SCHED __builtin_amdgcn_sched_barrier(0)
; template <class Epi, class Sched, bool ALIGN_EPI = false, bool SP2 = false>
; __device__ __forceinline__ void gemm_phase(PG8_LAS unsigned char* lds, const Gemm g, const Sched& S, const Epi& E) {
;     ...
;             PG8_LDA(At, 1, 1); PG8_STAGE(PG8_SB(1, 0), b3, voffB); PG8_STAGE(PG8_SB(1, 1), b3 + hstep, voffB); PG8_STAGE(PG8_SA(1, 0), a3, voffA);
;             PG8_WAIT_V(8); PG8_WAIT_L(0); PG8_BAR; PG8_MMA(1, 0, At, B0); PG8_MMA(1, 1, At, B1); PG8_BAR; PG8_SCHED;
	s_add_i32 s8, s56, s36
	v_lshl_add_u64 v[152:153], v[152:153], 0, s[20:21]
	s_mov_b32 m0, s8
	ds_read_b128 v[188:191], v157 offset:49152
	global_load_lds_dwordx4 v[152:153], off
	s_add_i32 m0, s8, 0x2000
	s_add_u32 s6, s6, 0x40080
	v_lshl_add_u64 v[152:153], v[220:221], 0, s[20:21]
	s_addc_u32 s7, s7, 0
	s_add_i32 s8, s57, s36
	global_load_lds_dwordx4 v[152:153], off
	v_lshl_add_u64 v[152:153], s[6:7], 0, v[132:133]
	s_mov_b32 m0, s8
	ds_read_b128 v[192:195], v157 offset:50176
	global_load_lds_dwordx4 v[152:153], off
	v_lshl_add_u64 v[152:153], s[6:7], 0, v[128:129]
	s_add_i32 m0, s8, 0x2000
	ds_read_b128 v[196:199], v157 offset:51200
	global_load_lds_dwordx4 v[152:153], off
	v_lshl_add_u64 v[152:153], v[222:223], 0, s[20:21]
	s_mov_b32 m0, s44
	ds_read_b128 v[200:203], v157 offset:52224
	global_load_lds_dwordx4 v[152:153], off
	v_lshl_add_u64 v[152:153], v[224:225], 0, s[20:21]
	s_mov_b32 m0, s45
	ds_read_b128 v[204:207], v157 offset:53248
	global_load_lds_dwordx4 v[152:153], off
	ds_read_b128 v[208:211], v157 offset:54272
	ds_read_b128 v[212:215], v157 offset:55296
	ds_read_b128 v[216:219], v157 offset:56320
	s_waitcnt vmcnt(8)
	s_waitcnt lgkmcnt(0)
	s_barrier
	s_setprio 1
	s_waitcnt lgkmcnt(0)
	v_mfma_f32_16x16x32_bf16 v[60:63], v[144:147], v[188:191], v[60:63]
	v_mfma_f32_16x16x32_bf16 v[52:55], v[164:167], v[188:191], v[52:55]
	v_mfma_f32_16x16x32_bf16 v[44:47], v[144:147], v[196:199], v[44:47]
	v_mfma_f32_16x16x32_bf16 v[36:39], v[164:167], v[196:199], v[36:39]
	v_mfma_f32_16x16x32_bf16 v[28:31], v[144:147], v[204:207], v[28:31]
	v_mfma_f32_16x16x32_bf16 v[20:23], v[164:167], v[204:207], v[20:23]
	v_mfma_f32_16x16x32_bf16 v[12:15], v[144:147], v[212:215], v[12:15]
	v_mfma_f32_16x16x32_bf16 v[4:7], v[164:167], v[212:215], v[4:7]
	v_mfma_f32_16x16x32_bf16 v[60:63], v[160:163], v[192:195], v[60:63]
	v_mfma_f32_16x16x32_bf16 v[52:55], v[168:171], v[192:195], v[52:55]
	v_mfma_f32_16x16x32_bf16 v[44:47], v[160:163], v[200:203], v[44:47]
	v_mfma_f32_16x16x32_bf16 v[36:39], v[168:171], v[200:203], v[36:39]
	v_mfma_f32_16x16x32_bf16 v[28:31], v[160:163], v[208:211], v[28:31]
	v_mfma_f32_16x16x32_bf16 v[20:23], v[168:171], v[208:211], v[20:23]
	v_mfma_f32_16x16x32_bf16 v[12:15], v[160:163], v[216:219], v[12:15]
	v_mfma_f32_16x16x32_bf16 v[4:7], v[168:171], v[216:219], v[4:7]
	s_setprio 0
	s_setprio 1
	v_mfma_f32_16x16x32_bf16 v[56:59], v[172:175], v[188:191], v[56:59]
	v_mfma_f32_16x16x32_bf16 v[48:51], v[180:183], v[188:191], v[48:51]
	v_mfma_f32_16x16x32_bf16 v[40:43], v[172:175], v[196:199], v[40:43]
	v_mfma_f32_16x16x32_bf16 v[32:35], v[180:183], v[196:199], v[32:35]
	v_mfma_f32_16x16x32_bf16 v[24:27], v[172:175], v[204:207], v[24:27]
	v_mfma_f32_16x16x32_bf16 v[16:19], v[180:183], v[204:207], v[16:19]
	v_mfma_f32_16x16x32_bf16 v[8:11], v[172:175], v[212:215], v[8:11]
	v_mfma_f32_16x16x32_bf16 v[0:3], v[180:183], v[212:215], v[0:3]
	v_mfma_f32_16x16x32_bf16 v[56:59], v[176:179], v[192:195], v[56:59]
	v_mfma_f32_16x16x32_bf16 v[48:51], v[184:187], v[192:195], v[48:51]
	v_mfma_f32_16x16x32_bf16 v[40:43], v[176:179], v[200:203], v[40:43]
	v_mfma_f32_16x16x32_bf16 v[32:35], v[184:187], v[200:203], v[32:35]
	v_mfma_f32_16x16x32_bf16 v[24:27], v[176:179], v[208:211], v[24:27]
	v_mfma_f32_16x16x32_bf16 v[16:19], v[184:187], v[208:211], v[16:19]
	v_mfma_f32_16x16x32_bf16 v[8:11], v[176:179], v[216:219], v[8:11]
	v_mfma_f32_16x16x32_bf16 v[0:3], v[184:187], v[216:219], v[0:3]
	s_setprio 0
	s_barrier
	s_add_i32 s55, s55, 2
	s_add_u32 s4, s4, 0x100
	s_addc_u32 s5, s5, 0
	s_add_u32 s53, s53, 0x100
	s_addc_u32 s54, s54, 0
	s_cmp_gt_u32 s55, 13
	s_cbranch_scc0 .LBB0_1666
	s_nop 0
	s_nop 0
	s_nop 0
	s_nop 0
	s_nop 0
	s_nop 0
	s_nop 0
	s_nop 0
	s_nop 0
	s_and_b64 vcc, exec, s[22:23]
	s_cbranch_vccz .LBB0_1669
	s_barrier

; #define PG8_STAGE(bufoff, gbase, voff) do { _Pragma("unroll") for (int _i = 0; _i < 2; ++_i) \
;         __builtin_amdgcn_global_load_lds((const unsigned*)((const char*)(gbase) + (voff)[_i]), (PG8_LAS unsigned*)(lds + (bufoff) + ldsw + _i * 8192), 16, 0, 0); } while (0)
; #define PG8_LDA(dst, b, h) do { _Pragma("unroll") for (int m = 0; m < 4; ++m) _Pragma("unroll") for (int k = 0; k < 2; ++k) dst[m][k] = *(const PG8_LAS bf16x8*)(lds + PG8_SA(b, h) + aoff + m * 2048 + k * 1024); } while (0)
; #define PG8_LDB(dst, b, h) do { _Pragma("unroll") for (int n = 0; n < 2; ++n) _Pragma("unroll") for (int k = 0; k < 2; ++k) dst[n][k] = *(const PG8_LAS bf16x8*)(lds + PG8_SB(b, h) + boff + n * 2048 + k * 1024); } while (0)
; #define PG8_MMA(ai, bj, At, Bt) do { __builtin_amdgcn_s_setprio(1); _Pragma("unroll") for (int m = 0; m < 4; ++m) _Pragma("unroll") for (int n = 0; n < 2; ++n) _Pragma("unroll") for (int k = 0; k < 2; ++k) \
;         acc[ai][bj][m][n] = __builtin_amdgcn_mfma_f32_16x16x32_bf16(Bt[n][k], At[m][k], acc[ai][bj][m][n], 0, 0, 0); __builtin_amdgcn_s_setprio(0); } while (0)
; #define PG8_WAIT_V(n) asm volatile("s_waitcnt vmcnt(" #n ")" ::: "memory")
; #define PG8_WAIT_L(n) asm volatile("s_waitcnt lgkmcnt(" #n ")" ::: "memory")
; #define PG8_BAR __builtin_amdgcn_s_barrier()
; #define PG8_SCHED __builtin_amdgcn_sched_barrier(0)
; template <class Epi, class Sched, bool ALIGN_EPI = false, bool SP2 = false>
; __device__ __forceinline__ void gemm_phase(PG8_LAS unsigned char* lds, const Gemm g, const Sched& S, const Epi& E) {
;     ...
;             PG8_LDB(B0, 0, 0); PG8_LDB(B1, 0, 1); PG8_SCHED; PG8_LDA(At, 0, 0); PG8_STAGE(PG8_SA(1, 1), a1 + hstep, voffA);
;             PG8_WAIT_V(8); PG8_WAIT_L(0); PG8_BAR; PG8_MMA(0, 0, At, B0); PG8_MMA(0, 1, At, B1); PG8_BAR; PG8_SCHED;
;             PG8_LDA(At, 0, 1); PG8_STAGE(PG8_SB(0, 0), b2, voffB); PG8_STAGE(PG8_SB(0, 1), b2 + hstep, voffB); PG8_STAGE(PG8_SA(0, 0), a2, voffA);
;             PG8_WAIT_V(8); PG8_WAIT_L(0); PG8_BAR; PG8_MMA(1, 0, At, B0); PG8_MMA(1, 1, At, B1); PG8_BAR; PG8_SCHED;
.LBB0_1751:
	s_add_u32 s22, s20, 0xfff50080
	s_addc_u32 s23, s21, -1
	s_cmp_eq_u32 s47, 40
	s_cselect_b32 s25, s1, s23
	s_cselect_b32 s24, s0, s22
	s_cselect_b32 s23, s19, s46
	s_cselect_b32 s22, s18, s45
	v_lshl_add_u64 v[190:191], s[20:21], 0, v[132:133]
	s_add_i32 m0, s27, 0xc000
	ds_read_b128 v[140:143], v194
	global_load_lds_dwordx4 v[190:191], off
	v_lshl_add_u64 v[190:191], s[20:21], 0, v[134:135]
	s_add_i32 m0, s27, 0xe000
	ds_read_b128 v[144:147], v194 offset:1024
	global_load_lds_dwordx4 v[190:191], off
	ds_read_b128 v[150:153], v194 offset:2048
	ds_read_b128 v[154:157], v194 offset:3072
	ds_read_b128 v[158:161], v195
	ds_read_b128 v[162:165], v195 offset:1024
	ds_read_b128 v[166:169], v195 offset:2048
	ds_read_b128 v[170:173], v195 offset:3072
	ds_read_b128 v[174:177], v196
	ds_read_b128 v[178:181], v196 offset:1024
	ds_read_b128 v[182:185], v196 offset:2048
	ds_read_b128 v[186:189], v196 offset:3072
	ds_read_b128 v[200:203], v196 offset:4096
	ds_read_b128 v[204:207], v196 offset:5120
	ds_read_b128 v[208:211], v196 offset:6144
	ds_read_b128 v[212:215], v196 offset:7168
	s_waitcnt vmcnt(8)
	s_waitcnt lgkmcnt(0)
	s_barrier
	s_setprio 1
	s_waitcnt lgkmcnt(0)
	v_mfma_f32_16x16x32_bf16 v[124:127], v[140:143], v[174:177], v[124:127]
	v_mfma_f32_16x16x32_bf16 v[120:123], v[150:153], v[174:177], v[120:123]
	v_mfma_f32_16x16x32_bf16 v[108:111], v[140:143], v[182:185], v[108:111]
	v_mfma_f32_16x16x32_bf16 v[104:107], v[150:153], v[182:185], v[104:107]
	v_mfma_f32_16x16x32_bf16 v[92:95], v[140:143], v[200:203], v[92:95]
	v_mfma_f32_16x16x32_bf16 v[88:91], v[150:153], v[200:203], v[88:91]
	v_mfma_f32_16x16x32_bf16 v[76:79], v[140:143], v[208:211], v[76:79]
	v_mfma_f32_16x16x32_bf16 v[72:75], v[150:153], v[208:211], v[72:75]
	v_mfma_f32_16x16x32_bf16 v[124:127], v[144:147], v[178:181], v[124:127]
	v_mfma_f32_16x16x32_bf16 v[120:123], v[154:157], v[178:181], v[120:123]
	v_mfma_f32_16x16x32_bf16 v[108:111], v[144:147], v[186:189], v[108:111]
	v_mfma_f32_16x16x32_bf16 v[104:107], v[154:157], v[186:189], v[104:107]
	v_mfma_f32_16x16x32_bf16 v[92:95], v[144:147], v[204:207], v[92:95]
	v_mfma_f32_16x16x32_bf16 v[88:91], v[154:157], v[204:207], v[88:91]
	v_mfma_f32_16x16x32_bf16 v[76:79], v[144:147], v[212:215], v[76:79]
	v_mfma_f32_16x16x32_bf16 v[72:75], v[154:157], v[212:215], v[72:75]
	s_setprio 0
	s_setprio 1
	v_mfma_f32_16x16x32_bf16 v[116:119], v[158:161], v[174:177], v[116:119]
	v_mfma_f32_16x16x32_bf16 v[112:115], v[166:169], v[174:177], v[112:115]
	v_mfma_f32_16x16x32_bf16 v[100:103], v[158:161], v[182:185], v[100:103]
	v_mfma_f32_16x16x32_bf16 v[96:99], v[166:169], v[182:185], v[96:99]
	v_mfma_f32_16x16x32_bf16 v[84:87], v[158:161], v[200:203], v[84:87]
	v_mfma_f32_16x16x32_bf16 v[80:83], v[166:169], v[200:203], v[80:83]
	v_mfma_f32_16x16x32_bf16 v[68:71], v[158:161], v[208:211], v[68:71]
	v_mfma_f32_16x16x32_bf16 v[64:67], v[166:169], v[208:211], v[64:67]
	v_mfma_f32_16x16x32_bf16 v[116:119], v[162:165], v[178:181], v[116:119]
	v_mfma_f32_16x16x32_bf16 v[112:115], v[170:173], v[178:181], v[112:115]
	v_mfma_f32_16x16x32_bf16 v[100:103], v[162:165], v[186:189], v[100:103]
	v_mfma_f32_16x16x32_bf16 v[96:99], v[170:173], v[186:189], v[96:99]
	v_mfma_f32_16x16x32_bf16 v[84:87], v[162:165], v[204:207], v[84:87]
	v_mfma_f32_16x16x32_bf16 v[80:83], v[170:173], v[204:207], v[80:83]
	v_mfma_f32_16x16x32_bf16 v[68:71], v[162:165], v[212:215], v[68:71]
	v_mfma_f32_16x16x32_bf16 v[64:67], v[170:173], v[212:215], v[64:67]
	s_setprio 0
	s_barrier
	s_add_i32 s50, s38, s26
	v_lshl_add_u64 v[190:191], s[22:23], 0, v[128:129]
	s_mov_b32 m0, s50
	v_lshl_add_u64 v[216:217], s[22:23], 0, v[130:131]
	global_load_lds_dwordx4 v[190:191], off
	s_add_i32 m0, s50, 0x2000
	s_add_u32 s50, s22, 0xb0000
	s_addc_u32 s51, s23, 0
	s_add_i32 s52, s39, s26
	global_load_lds_dwordx4 v[216:217], off
	v_lshl_add_u64 v[218:219], s[50:51], 0, v[128:129]
	s_mov_b32 m0, s52
	v_lshl_add_u64 v[220:221], s[24:25], 0, v[130:131]
	global_load_lds_dwordx4 v[218:219], off
	v_lshl_add_u64 v[218:219], s[50:51], 0, v[130:131]
	s_add_i32 m0, s52, 0x2000
	ds_read_b128 v[174:177], v196 offset:16384
	global_load_lds_dwordx4 v[218:219], off
	v_lshl_add_u64 v[218:219], s[24:25], 0, v[128:129]
	s_mov_b32 m0, s27
	ds_read_b128 v[178:181], v196 offset:17408
	global_load_lds_dwordx4 v[218:219], off
	s_mov_b32 m0, s28
	ds_read_b128 v[182:185], v196 offset:18432
	global_load_lds_dwordx4 v[220:221], off
	ds_read_b128 v[186:189], v196 offset:19456
	ds_read_b128 v[200:203], v196 offset:20480
	ds_read_b128 v[204:207], v196 offset:21504
	ds_read_b128 v[208:211], v196 offset:22528
	ds_read_b128 v[212:215], v196 offset:23552
	s_waitcnt vmcnt(8)
	s_waitcnt lgkmcnt(0)
	s_barrier
; #define PG8_STAGE(bufoff, gbase, voff) do { _Pragma("unroll") for (int _i = 0; _i < 2; ++_i) \
;         __builtin_amdgcn_global_load_lds((const unsigned*)((const char*)(gbase) + (voff)[_i]), (PG8_LAS unsigned*)(lds + (bufoff) + ldsw + _i * 8192), 16, 0, 0); } while (0)
; #define PG8_LDA(dst, b, h) do { _Pragma("unroll") for (int m = 0; m < 4; ++m) _Pragma("unroll") for (int k = 0; k < 2; ++k) dst[m][k] = *(const PG8_LAS bf16x8*)(lds + PG8_SA(b, h) + aoff + m * 2048 + k * 1024); } while (0)
; #define PG8_LDB(dst, b, h) do { _Pragma("unroll") for (int n = 0; n < 2; ++n) _Pragma("unroll") for (int k = 0; k < 2; ++k) dst[n][k] = *(const PG8_LAS bf16x8*)(lds + PG8_SB(b, h) + boff + n * 2048 + k * 1024); } while (0)
; #define PG8_MMA(ai, bj, At, Bt) do { __builtin_amdgcn_s_setprio(1); _Pragma("unroll") for (int m = 0; m < 4; ++m) _Pragma("unroll") for (int n = 0; n < 2; ++n) _Pragma("unroll") for (int k = 0; k < 2; ++k) \
;         acc[ai][bj][m][n] = __builtin_amdgcn_mfma_f32_16x16x32_bf16(Bt[n][k], At[m][k], acc[ai][bj][m][n], 0, 0, 0); __builtin_amdgcn_s_setprio(0); } while (0)
; #define PG8_WAIT_V(n) asm volatile("s_waitcnt vmcnt(" #n ")" ::: "memory")
; #define PG8_WAIT_L(n) asm volatile("s_waitcnt lgkmcnt(" #n ")" ::: "memory")
; #define PG8_BAR __builtin_amdgcn_s_barrier()
; #define PG8_SCHED __builtin_amdgcn_sched_barrier(0)
; template <class Epi, class Sched, bool ALIGN_EPI = false, bool SP2 = false>
; __device__ __forceinline__ void gemm_phase(PG8_LAS unsigned char* lds, const Gemm g, const Sched& S, const Epi& E) {
;     ...
;             PG8_WAIT_V(8); PG8_WAIT_L(0); PG8_BAR; PG8_MMA(1, 0, At, B0); PG8_MMA(1, 1, At, B1); PG8_BAR; PG8_SCHED;
;             PG8_LDB(B0, 1, 0); PG8_LDB(B1, 1, 1); PG8_SCHED; PG8_LDA(At, 1, 0); PG8_STAGE(PG8_SA(0, 1), a2 + hstep, voffA);
;             PG8_WAIT_V(8); PG8_WAIT_L(0); PG8_BAR; PG8_MMA(0, 0, At, B0); PG8_MMA(0, 1, At, B1); PG8_BAR; PG8_SCHED;
	s_setprio 1
	s_waitcnt lgkmcnt(0)
	v_mfma_f32_16x16x32_bf16 v[60:63], v[140:143], v[174:177], v[60:63]
	v_mfma_f32_16x16x32_bf16 v[56:59], v[150:153], v[174:177], v[56:59]
	v_mfma_f32_16x16x32_bf16 v[44:47], v[140:143], v[182:185], v[44:47]
	v_mfma_f32_16x16x32_bf16 v[40:43], v[150:153], v[182:185], v[40:43]
	v_mfma_f32_16x16x32_bf16 v[28:31], v[140:143], v[200:203], v[28:31]
	v_mfma_f32_16x16x32_bf16 v[24:27], v[150:153], v[200:203], v[24:27]
	v_mfma_f32_16x16x32_bf16 v[12:15], v[140:143], v[208:211], v[12:15]
	v_mfma_f32_16x16x32_bf16 v[8:11], v[150:153], v[208:211], v[8:11]
	v_mfma_f32_16x16x32_bf16 v[60:63], v[144:147], v[178:181], v[60:63]
	v_mfma_f32_16x16x32_bf16 v[56:59], v[154:157], v[178:181], v[56:59]
	v_mfma_f32_16x16x32_bf16 v[44:47], v[144:147], v[186:189], v[44:47]
	v_mfma_f32_16x16x32_bf16 v[40:43], v[154:157], v[186:189], v[40:43]
	v_mfma_f32_16x16x32_bf16 v[28:31], v[144:147], v[204:207], v[28:31]
	v_mfma_f32_16x16x32_bf16 v[24:27], v[154:157], v[204:207], v[24:27]
	v_mfma_f32_16x16x32_bf16 v[12:15], v[144:147], v[212:215], v[12:15]
	v_mfma_f32_16x16x32_bf16 v[8:11], v[154:157], v[212:215], v[8:11]
	s_setprio 0
	s_setprio 1
	v_mfma_f32_16x16x32_bf16 v[52:55], v[158:161], v[174:177], v[52:55]
	v_mfma_f32_16x16x32_bf16 v[48:51], v[166:169], v[174:177], v[48:51]
	v_mfma_f32_16x16x32_bf16 v[36:39], v[158:161], v[182:185], v[36:39]
	v_mfma_f32_16x16x32_bf16 v[32:35], v[166:169], v[182:185], v[32:35]
	v_mfma_f32_16x16x32_bf16 v[20:23], v[158:161], v[200:203], v[20:23]
	v_mfma_f32_16x16x32_bf16 v[16:19], v[166:169], v[200:203], v[16:19]
	v_mfma_f32_16x16x32_bf16 v[4:7], v[158:161], v[208:211], v[4:7]
	v_mfma_f32_16x16x32_bf16 v[0:3], v[166:169], v[208:211], v[0:3]
	v_mfma_f32_16x16x32_bf16 v[52:55], v[162:165], v[178:181], v[52:55]
	v_mfma_f32_16x16x32_bf16 v[48:51], v[170:173], v[178:181], v[48:51]
	v_mfma_f32_16x16x32_bf16 v[36:39], v[162:165], v[186:189], v[36:39]
	v_mfma_f32_16x16x32_bf16 v[32:35], v[170:173], v[186:189], v[32:35]
	v_mfma_f32_16x16x32_bf16 v[20:23], v[162:165], v[204:207], v[20:23]
	v_mfma_f32_16x16x32_bf16 v[16:19], v[170:173], v[204:207], v[16:19]
	v_mfma_f32_16x16x32_bf16 v[4:7], v[162:165], v[212:215], v[4:7]
	v_mfma_f32_16x16x32_bf16 v[0:3], v[170:173], v[212:215], v[0:3]
	s_setprio 0
	s_barrier
	s_add_i32 s50, 0, 0x18000
	s_add_i32 s51, 0, 0x1c000
	s_add_u32 s24, s24, 0xb0000
	s_addc_u32 s25, s25, 0
	s_mov_b32 m0, s29
	v_lshl_add_u64 v[222:223], s[24:25], 0, v[128:129]
	global_load_lds_dwordx4 v[222:223], off
	v_lshl_add_u64 v[222:223], s[24:25], 0, v[130:131]
	s_mov_b32 m0, s30
	v_add_u32_e32 v154, s50, v192
	global_load_lds_dwordx4 v[222:223], off
	v_add_u32_e32 v170, s51, v192
	ds_read_b128 v[140:143], v154
	ds_read_b128 v[144:147], v154 offset:1024
	ds_read_b128 v[150:153], v154 offset:2048
	ds_read_b128 v[154:157], v154 offset:3072
	ds_read_b128 v[158:161], v170
	ds_read_b128 v[162:165], v170 offset:1024
	ds_read_b128 v[166:169], v170 offset:2048
	ds_read_b128 v[170:173], v170 offset:3072
	ds_read_b128 v[174:177], v196 offset:32768
	ds_read_b128 v[178:181], v196 offset:33792
	ds_read_b128 v[182:185], v196 offset:34816
	ds_read_b128 v[186:189], v196 offset:35840
	ds_read_b128 v[200:203], v196 offset:36864
	ds_read_b128 v[204:207], v196 offset:37888
	ds_read_b128 v[208:211], v196 offset:38912
	ds_read_b128 v[212:215], v196 offset:39936
	s_waitcnt vmcnt(8)
	s_waitcnt lgkmcnt(0)
	s_barrier
	s_setprio 1
	s_waitcnt lgkmcnt(0)
	v_mfma_f32_16x16x32_bf16 v[124:127], v[140:143], v[174:177], v[124:127]
	v_mfma_f32_16x16x32_bf16 v[120:123], v[150:153], v[174:177], v[120:123]
	v_mfma_f32_16x16x32_bf16 v[108:111], v[140:143], v[182:185], v[108:111]
	v_mfma_f32_16x16x32_bf16 v[104:107], v[150:153], v[182:185], v[104:107]
	v_mfma_f32_16x16x32_bf16 v[92:95], v[140:143], v[200:203], v[92:95]
	v_mfma_f32_16x16x32_bf16 v[88:91], v[150:153], v[200:203], v[88:91]
	v_mfma_f32_16x16x32_bf16 v[76:79], v[140:143], v[208:211], v[76:79]
	v_mfma_f32_16x16x32_bf16 v[72:75], v[150:153], v[208:211], v[72:75]
	v_mfma_f32_16x16x32_bf16 v[124:127], v[144:147], v[178:181], v[124:127]
	v_mfma_f32_16x16x32_bf16 v[120:123], v[154:157], v[178:181], v[120:123]
	v_mfma_f32_16x16x32_bf16 v[108:111], v[144:147], v[186:189], v[108:111]
	v_mfma_f32_16x16x32_bf16 v[104:107], v[154:157], v[186:189], v[104:107]
	v_mfma_f32_16x16x32_bf16 v[92:95], v[144:147], v[204:207], v[92:95]
	v_mfma_f32_16x16x32_bf16 v[88:91], v[154:157], v[204:207], v[88:91]
	v_mfma_f32_16x16x32_bf16 v[76:79], v[144:147], v[212:215], v[76:79]
	v_mfma_f32_16x16x32_bf16 v[72:75], v[154:157], v[212:215], v[72:75]
	s_setprio 0
	s_setprio 1
	v_mfma_f32_16x16x32_bf16 v[116:119], v[158:161], v[174:177], v[116:119]
	v_mfma_f32_16x16x32_bf16 v[112:115], v[166:169], v[174:177], v[112:115]
	v_mfma_f32_16x16x32_bf16 v[100:103], v[158:161], v[182:185], v[100:103]
	v_mfma_f32_16x16x32_bf16 v[96:99], v[166:169], v[182:185], v[96:99]
	v_mfma_f32_16x16x32_bf16 v[84:87], v[158:161], v[200:203], v[84:87]
	v_mfma_f32_16x16x32_bf16 v[80:83], v[166:169], v[200:203], v[80:83]
	v_mfma_f32_16x16x32_bf16 v[68:71], v[158:161], v[208:211], v[68:71]
	v_mfma_f32_16x16x32_bf16 v[64:67], v[166:169], v[208:211], v[64:67]
	v_mfma_f32_16x16x32_bf16 v[116:119], v[162:165], v[178:181], v[116:119]
	v_mfma_f32_16x16x32_bf16 v[112:115], v[170:173], v[178:181], v[112:115]
	v_mfma_f32_16x16x32_bf16 v[100:103], v[162:165], v[186:189], v[100:103]
	v_mfma_f32_16x16x32_bf16 v[96:99], v[170:173], v[186:189], v[96:99]
	v_mfma_f32_16x16x32_bf16 v[84:87], v[162:165], v[204:207], v[84:87]
	v_mfma_f32_16x16x32_bf16 v[80:83], v[170:173], v[204:207], v[80:83]
	v_mfma_f32_16x16x32_bf16 v[68:71], v[162:165], v[212:215], v[68:71]
	v_mfma_f32_16x16x32_bf16 v[64:67], v[170:173], v[212:215], v[64:67]
	s_setprio 0
	s_barrier
; #define PG8_STAGE(bufoff, gbase, voff) do { _Pragma("unroll") for (int _i = 0; _i < 2; ++_i) \
;         __builtin_amdgcn_global_load_lds((const unsigned*)((const char*)(gbase) + (voff)[_i]), (PG8_LAS unsigned*)(lds + (bufoff) + ldsw + _i * 8192), 16, 0, 0); } while (0)
; #define PG8_LDA(dst, b, h) do { _Pragma("unroll") for (int m = 0; m < 4; ++m) _Pragma("unroll") for (int k = 0; k < 2; ++k) dst[m][k] = *(const PG8_LAS bf16x8*)(lds + PG8_SA(b, h) + aoff + m * 2048 + k * 1024); } while (0)
; #define PG8_MMA(ai, bj, At, Bt) do { __builtin_amdgcn_s_setprio(1); _Pragma("unroll") for (int m = 0; m < 4; ++m) _Pragma("unroll") for (int n = 0; n < 2; ++n) _Pragma("unroll") for (int k = 0; k < 2; ++k) \
;         acc[ai][bj][m][n] = __builtin_amdgcn_mfma_f32_16x16x32_bf16(Bt[n][k], At[m][k], acc[ai][bj][m][n], 0, 0, 0); __builtin_amdgcn_s_setprio(0); } while (0)
; #define PG8_WAIT_V(n) asm volatile("s_waitcnt vmcnt(" #n ")" ::: "memory")
; #define PG8_WAIT_L(n) asm volatile("s_waitcnt lgkmcnt(" #n ")" ::: "memory")
; #define PG8_BAR __builtin_amdgcn_s_barrier()
; #define PG8_SCHED __builtin_amdgcn_sched_barrier(0)
; template <class Epi, class Sched, bool ALIGN_EPI = false, bool SP2 = false>
; __device__ __forceinline__ void gemm_phase(PG8_LAS unsigned char* lds, const Gemm g, const Sched& S, const Epi& E) {
;     ...
;             PG8_LDA(At, 1, 1); PG8_STAGE(PG8_SB(1, 0), b3, voffB); PG8_STAGE(PG8_SB(1, 1), b3 + hstep, voffB); PG8_STAGE(PG8_SA(1, 0), a3, voffA);
;             PG8_WAIT_V(8); PG8_WAIT_L(0); PG8_BAR; PG8_MMA(1, 0, At, B0); PG8_MMA(1, 1, At, B1); PG8_BAR; PG8_SCHED;
	s_add_i32 s24, s50, s26
	v_lshl_add_u64 v[190:191], v[190:191], 0, s[14:15]
	s_mov_b32 m0, s24
	ds_read_b128 v[174:177], v196 offset:49152
	global_load_lds_dwordx4 v[190:191], off
	s_add_i32 m0, s24, 0x2000
	s_add_u32 s22, s22, 0xb0080
	v_lshl_add_u64 v[190:191], v[216:217], 0, s[14:15]
	s_addc_u32 s23, s23, 0
	s_add_i32 s24, s51, s26
	global_load_lds_dwordx4 v[190:191], off
	v_lshl_add_u64 v[190:191], s[22:23], 0, v[128:129]
	s_mov_b32 m0, s24
	ds_read_b128 v[178:181], v196 offset:50176
	global_load_lds_dwordx4 v[190:191], off
	v_lshl_add_u64 v[190:191], s[22:23], 0, v[130:131]
	s_add_i32 m0, s24, 0x2000
	ds_read_b128 v[182:185], v196 offset:51200
	global_load_lds_dwordx4 v[190:191], off
	v_lshl_add_u64 v[190:191], v[218:219], 0, s[14:15]
	s_mov_b32 m0, s34
	ds_read_b128 v[186:189], v196 offset:52224
	global_load_lds_dwordx4 v[190:191], off
	v_lshl_add_u64 v[190:191], v[220:221], 0, s[14:15]
	s_mov_b32 m0, s35
	ds_read_b128 v[200:203], v196 offset:53248
	global_load_lds_dwordx4 v[190:191], off
	ds_read_b128 v[204:207], v196 offset:54272
	ds_read_b128 v[208:211], v196 offset:55296
	ds_read_b128 v[212:215], v196 offset:56320
	s_waitcnt vmcnt(8)
	s_waitcnt lgkmcnt(0)
	s_barrier
	s_setprio 1
	s_waitcnt lgkmcnt(0)
	v_mfma_f32_16x16x32_bf16 v[60:63], v[140:143], v[174:177], v[60:63]
	v_mfma_f32_16x16x32_bf16 v[56:59], v[150:153], v[174:177], v[56:59]
	v_mfma_f32_16x16x32_bf16 v[44:47], v[140:143], v[182:185], v[44:47]
	v_mfma_f32_16x16x32_bf16 v[40:43], v[150:153], v[182:185], v[40:43]
	v_mfma_f32_16x16x32_bf16 v[28:31], v[140:143], v[200:203], v[28:31]
	v_mfma_f32_16x16x32_bf16 v[24:27], v[150:153], v[200:203], v[24:27]
	v_mfma_f32_16x16x32_bf16 v[12:15], v[140:143], v[208:211], v[12:15]
	v_mfma_f32_16x16x32_bf16 v[8:11], v[150:153], v[208:211], v[8:11]
	v_mfma_f32_16x16x32_bf16 v[60:63], v[144:147], v[178:181], v[60:63]
	v_mfma_f32_16x16x32_bf16 v[56:59], v[154:157], v[178:181], v[56:59]
	v_mfma_f32_16x16x32_bf16 v[44:47], v[144:147], v[186:189], v[44:47]
	v_mfma_f32_16x16x32_bf16 v[40:43], v[154:157], v[186:189], v[40:43]
	v_mfma_f32_16x16x32_bf16 v[28:31], v[144:147], v[204:207], v[28:31]
	v_mfma_f32_16x16x32_bf16 v[24:27], v[154:157], v[204:207], v[24:27]
	v_mfma_f32_16x16x32_bf16 v[12:15], v[144:147], v[212:215], v[12:15]
	v_mfma_f32_16x16x32_bf16 v[8:11], v[154:157], v[212:215], v[8:11]
	s_setprio 0
	s_setprio 1
	v_mfma_f32_16x16x32_bf16 v[52:55], v[158:161], v[174:177], v[52:55]
	v_mfma_f32_16x16x32_bf16 v[48:51], v[166:169], v[174:177], v[48:51]
	v_mfma_f32_16x16x32_bf16 v[36:39], v[158:161], v[182:185], v[36:39]
	v_mfma_f32_16x16x32_bf16 v[32:35], v[166:169], v[182:185], v[32:35]
	v_mfma_f32_16x16x32_bf16 v[20:23], v[158:161], v[200:203], v[20:23]
	v_mfma_f32_16x16x32_bf16 v[16:19], v[166:169], v[200:203], v[16:19]
	v_mfma_f32_16x16x32_bf16 v[4:7], v[158:161], v[208:211], v[4:7]
	v_mfma_f32_16x16x32_bf16 v[0:3], v[166:169], v[208:211], v[0:3]
	v_mfma_f32_16x16x32_bf16 v[52:55], v[162:165], v[178:181], v[52:55]
	v_mfma_f32_16x16x32_bf16 v[48:51], v[170:173], v[178:181], v[48:51]
	v_mfma_f32_16x16x32_bf16 v[36:39], v[162:165], v[186:189], v[36:39]
	v_mfma_f32_16x16x32_bf16 v[32:35], v[170:173], v[186:189], v[32:35]
	v_mfma_f32_16x16x32_bf16 v[20:23], v[162:165], v[204:207], v[20:23]
	v_mfma_f32_16x16x32_bf16 v[16:19], v[170:173], v[204:207], v[16:19]
	v_mfma_f32_16x16x32_bf16 v[4:7], v[162:165], v[212:215], v[4:7]
	v_mfma_f32_16x16x32_bf16 v[0:3], v[170:173], v[212:215], v[0:3]
	s_setprio 0
	s_barrier
	s_add_i32 s47, s47, 2
	s_add_u32 s20, s20, 0x100
	s_addc_u32 s21, s21, 0
	s_add_u32 s45, s45, 0x100
	s_addc_u32 s46, s46, 0
	s_cmp_gt_u32 s47, 41
	s_cbranch_scc0 .LBB0_1751
	s_nop 0
	s_nop 0
	s_nop 0
	s_nop 0
	s_nop 0
	s_nop 0
	s_nop 0
	s_nop 0
	s_nop 0
	s_and_b64 vcc, exec, s[16:17]
	s_cbranch_vccz .LBB0_1754
	s_barrier
